# v20: + batched merge-1 chain epilogue gate loads, pipelined mlstm_out/qkprep/prenorm row loops, attention epilogue gate prefetch, early publish of context rows from the mLSTM chains (ctx mlstm_out/mer
# speedup vs baseline: 1.0690x; 1.0156x over previous
.LBB0_167:
	s_or_b64 exec, exec, s[10:11]
	s_cmp_eq_u32 s30, 0
	s_cselect_b64 s[14:15], -1, 0
	v_writelane_b32 v255, s14, 12
	s_mov_b32 s10, s30
	s_mov_b32 s11, s31
	v_writelane_b32 v255, s15, 13
	v_writelane_b32 v255, s10, 14
	s_cmp_lg_u32 s10, 0
	v_ashrrev_i32_e32 v1, 6, v4
	v_writelane_b32 v255, s11, 15
	s_cselect_b64 s[10:11], -1, 0
	v_readlane_b32 s6, v253, 0
	v_writelane_b32 v255, s10, 16
	s_waitcnt lgkmcnt(0)
	v_add_u32_e32 v24, s6, v1
	s_movk_i32 s6, 0x4400
	v_writelane_b32 v255, s11, 17
	v_cmp_gt_i32_e32 vcc, s6, v24
	s_barrier
	s_and_saveexec_b64 s[78:79], vcc
	s_cbranch_execz .LBB0_178
	v_readlane_b32 s26, v255, 12
	v_readlane_b32 s27, v255, 13
	s_load_dwordx2 s[80:81], s[12:13], 0xb0
	s_and_b64 s[10:11], s[26:27], exec
	s_cselect_b32 s6, 0, 0xa8
	s_add_u32 s10, s12, s6
	s_addc_u32 s11, s13, 0
	s_load_dwordx2 s[82:83], s[10:11], 0x0
	s_nop 0
	s_load_dwordx2 s[10:11], s[12:13], 0x10
	s_load_dwordx2 s[14:15], s[12:13], 0x20
	s_waitcnt lgkmcnt(0)
	s_add_u32 s6, s80, 0x8710000
	s_addc_u32 s18, s81, 0
	s_and_b64 s[26:27], s[26:27], exec
	v_xor_b32_e32 v1, 32, v223
	v_readlane_b32 s26, v255, 14
	v_cmp_lt_i32_e32 vcc, v1, v225
	s_cselect_b32 s84, s10, s6
	s_mul_i32 s10, s26, 0xf000
	v_cndmask_b32_e32 v1, v223, v1, vcc
	v_cmp_lt_i32_e32 vcc, v243, v225
	s_cselect_b32 s85, s11, s18
	s_mul_hi_u32 s6, s26, 0xf000
	s_add_u32 s10, s80, s10
	v_cndmask_b32_e32 v6, v223, v243, vcc
	v_cmp_lt_i32_e32 vcc, v222, v225
	s_addc_u32 s6, s81, s6
	v_lshlrev_b32_e32 v46, 2, v6
	v_cndmask_b32_e32 v6, v223, v222, vcc
	v_cmp_lt_i32_e32 vcc, v229, v225
	v_readlane_b32 s27, v255, 15
	s_add_u32 s86, s10, 0x10000
	v_lshlrev_b32_e32 v47, 2, v6
	v_cndmask_b32_e32 v6, v223, v229, vcc
	v_cmp_lt_i32_e32 vcc, v230, v225
	s_addc_u32 s87, s6, 0
	s_lshl_b64 s[10:11], s[26:27], 12
	v_lshlrev_b32_e32 v48, 2, v6
	v_cndmask_b32_e32 v6, v223, v230, vcc
	v_cmp_lt_i32_e32 vcc, v231, v225
	v_and_b32_e32 v5, 63, v4
	s_add_u32 s10, s14, s10
	v_lshlrev_b32_e32 v49, 2, v6
	v_cndmask_b32_e32 v6, v223, v231, vcc
	v_ashrrev_i32_e32 v25, 31, v24
	s_addc_u32 s11, s15, s11
	v_lshlrev_b32_e32 v2, 2, v5
	v_mov_b32_e32 v3, v0
	v_lshlrev_b32_e32 v50, 2, v6
	v_lshlrev_b32_e32 v6, 4, v5
	v_and_b32_e32 v4, 4, v4
	v_mov_b32_e32 v7, v0
	v_lshlrev_b64 v[10:11], 6, v[24:25]
	v_add_u32_e32 v51, 0, v6
	v_cmp_ne_u32_e64 s[40:41], 0, v4
	v_lshl_add_u64 v[28:29], s[10:11], 0, v[6:7]
	v_or_b32_e32 v4, 0x100, v2
	v_or_b32_e32 v6, 0x200, v2
	v_or_b32_e32 v8, 0x300, v2
	v_lshl_add_u64 v[10:11], v[10:11], 0, v[2:3]
	s_mov_b64 s[10:11], 0x8600000
	v_lshlrev_b64 v[32:33], 11, v[24:25]
	v_lshlrev_b32_e32 v1, 2, v1
	v_cmp_gt_u32_e32 vcc, 16, v5
	v_lshl_add_u32 v26, s26, 4, v5
	v_mov_b32_e32 v27, v0
	v_cmp_eq_u32_e64 s[42:43], 15, v5
	v_cmp_eq_u32_e64 s[44:45], 14, v5
	v_cmp_eq_u32_e64 s[46:47], 13, v5
	v_cmp_eq_u32_e64 s[48:49], 12, v5
	v_cmp_eq_u32_e64 s[50:51], 11, v5
	v_cmp_eq_u32_e64 s[52:53], 10, v5
	v_cmp_eq_u32_e64 s[54:55], 9, v5
	v_cmp_eq_u32_e64 s[56:57], 8, v5
	v_cmp_eq_u32_e64 s[58:59], 7, v5
	v_cmp_eq_u32_e64 s[60:61], 6, v5
	v_cmp_eq_u32_e64 s[62:63], 5, v5
	v_cmp_eq_u32_e64 s[64:65], 4, v5
	v_cmp_eq_u32_e64 s[66:67], 3, v5
	v_cmp_eq_u32_e64 s[68:69], 2, v5
	v_cmp_eq_u32_e64 s[70:71], 1, v5
	v_cmp_eq_u32_e64 s[72:73], 0, v5
	v_lshl_add_u64 v[30:31], v[10:11], 0, s[10:11]
	v_lshl_or_b32 v32, v5, 3, v32
	s_mov_b64 s[88:89], 0
	v_lshlrev_b32_e32 v34, 2, v2
	v_lshlrev_b32_e32 v36, 2, v4
	v_lshlrev_b32_e32 v38, 2, v6
	v_lshlrev_b32_e32 v40, 2, v8
	s_mov_b32 s100, 0x78787879
	s_movk_i32 s101, 0xef00
	v_mov_b32_e32 v116, v24
	v_min_i32_e32 v116, 0x43ff, v116
	v_mul_hi_i32 v117, v116, s100
	v_lshrrev_b32_e32 v118, 31, v117
	v_ashrrev_i32_e32 v117, 11, v117
	v_add_u32_e32 v117, v117, v118
	v_mad_i32_i24 v118, v117, s101, v116
	v_lshlrev_b32_e32 v119, 12, v118
	v_lshl_add_u32 v120, v117, 24, v119
	v_lshl_add_u32 v121, v117, 20, v119
	v_add_u32_e32 v120, 0xfff00000, v120
	v_lshrrev_b32_e32 v119, 8, v118
	v_cmp_lt_i32_e64 s[74:75], 0, v119
	v_mov_b32_e32 v122, s84
	v_mov_b32_e32 v123, s85
	v_mov_b32_e32 v118, s82
	v_mov_b32_e32 v119, s83
	v_cndmask_b32_e64 v120, v121, v120, s[74:75]
	v_mov_b32_e32 v121, 0
	v_cndmask_b32_e64 v122, v122, v118, s[74:75]
	v_cndmask_b32_e64 v123, v123, v119, s[74:75]
	v_mov_b32_e32 v118, v34
	v_mov_b32_e32 v119, 0
	v_lshl_add_u64 v[122:123], v[122:123], 0, v[120:121]
	v_lshl_add_u64 v[122:123], v[122:123], 0, v[118:119]
	global_load_dwordx4 v[100:103], v[122:123], off
	global_load_dwordx4 v[104:107], v[122:123], off offset:1024
	global_load_dwordx4 v[108:111], v[122:123], off offset:2048
	global_load_dwordx4 v[112:115], v[122:123], off offset:3072
	s_waitcnt vmcnt(0)
	s_branch .LBB0_171

.LBB0_173:
	s_andn2_saveexec_b64 s[10:11], s[10:11]
	v_ashrrev_i32_e32 v9, 31, v8
	v_lshlrev_b64 v[2:3], 20, v[4:5]
	v_lshl_add_u64 v[2:3], s[84:85], 0, v[2:3]
	v_lshlrev_b64 v[4:5], 12, v[8:9]
	v_lshl_add_u64 v[6:7], v[2:3], 0, v[4:5]
	v_mov_b64_e32 v[2:3], 0x3000
	s_or_b64 exec, exec, s[10:11]
	v_mov_b32_e32 v35, v0
	v_lshl_add_u64 v[4:5], v[6:7], 0, v[34:35]
	s_waitcnt vmcnt(1)
	v_mov_b32_e32 v6, v100
	v_mov_b32_e32 v7, v101
	v_mov_b32_e32 v8, v102
	v_mov_b32_e32 v9, v103
	v_mov_b32_e32 v12, v104
	v_mov_b32_e32 v13, v105
	v_mov_b32_e32 v14, v106
	v_mov_b32_e32 v15, v107
	v_lshl_add_u64 v[2:3], v[2:3], 2, s[86:87]
	s_mov_b64 s[10:11], 0x1000
	v_lshl_add_u64 v[44:45], v[2:3], 0, v[34:35]
	s_mov_b32 s6, 0x6400000
	v_mov_b32_e32 v37, v0
	v_mov_b32_e32 v39, v0
	v_mov_b32_e32 v41, v0
	v_mov_b32_e32 v16, v7
	v_mov_b32_e32 v17, v13
	v_mov_b32_e32 v10, v6
	v_mov_b32_e32 v11, v12
	v_pk_mul_f32 v[16:17], v[16:17], v[16:17]
	s_nop 0
	v_pk_fma_f32 v[10:11], v[10:11], v[10:11], v[16:17]
	v_mov_b32_e32 v16, v8
	v_mov_b32_e32 v17, v14
	v_pk_fma_f32 v[10:11], v[16:17], v[16:17], v[10:11]
	v_mov_b32_e32 v16, v9
	v_mov_b32_e32 v17, v15
	v_pk_fma_f32 v[10:11], v[16:17], v[16:17], v[10:11]
	v_mov_b32_e32 v20, v108
	v_mov_b32_e32 v21, v109
	v_mov_b32_e32 v22, v110
	v_mov_b32_e32 v23, v111
	v_mov_b32_e32 v16, v112
	v_mov_b32_e32 v17, v113
	v_mov_b32_e32 v18, v114
	v_mov_b32_e32 v19, v115
	v_add_f32_e32 v10, v10, v11
	global_load_dwordx4 v[56:59], v[28:29], off
	v_mov_b32_e32 v42, v21
	v_mov_b32_e32 v43, v17
	v_mov_b32_e32 v4, v20
	v_mov_b32_e32 v5, v16
	v_pk_mul_f32 v[42:43], v[42:43], v[42:43]
	s_nop 0
	v_pk_fma_f32 v[4:5], v[4:5], v[4:5], v[42:43]
	v_mov_b32_e32 v42, v22
	v_mov_b32_e32 v43, v18
	v_pk_fma_f32 v[4:5], v[42:43], v[42:43], v[4:5]
	v_mov_b32_e32 v42, v23
	v_mov_b32_e32 v43, v19
	v_pk_fma_f32 v[4:5], v[42:43], v[42:43], v[4:5]
	v_lshl_add_u64 v[42:43], v[2:3], 0, s[10:11]
	v_add_f32_e32 v4, v10, v4
	v_add_f32_e32 v4, v4, v5
	ds_bpermute_b32 v5, v1, v4
	v_lshl_add_u64 v[10:11], v[42:43], 0, v[34:35]
	global_load_dwordx4 v[60:63], v[10:11], off
	s_waitcnt lgkmcnt(0)
	v_add_f32_e32 v4, v4, v5
	ds_bpermute_b32 v5, v46, v4
	s_waitcnt lgkmcnt(0)
	v_add_f32_e32 v4, v4, v5
	ds_bpermute_b32 v5, v47, v4
	s_waitcnt lgkmcnt(0)
	v_add_f32_e32 v4, v4, v5
	ds_bpermute_b32 v5, v48, v4
	s_waitcnt lgkmcnt(0)
	v_add_f32_e32 v4, v4, v5
	ds_bpermute_b32 v5, v49, v4
	s_waitcnt lgkmcnt(0)
	v_add_f32_e32 v4, v4, v5
	ds_bpermute_b32 v5, v50, v4
	s_waitcnt lgkmcnt(0)
	v_add_f32_e32 v4, v4, v5
	v_fmamk_f32 v4, v4, 0x3a800000, v234
	v_cmp_gt_f32_e64 s[74:75], s90, v4
	v_mul_f32_e32 v5, 0x4b800000, v4
	s_waitcnt vmcnt(0)
	v_add_f32_e32 v10, 1.0, v60
	v_cndmask_b32_e64 v4, v4, v5, s[74:75]
	v_rsq_f32_e32 v4, v4
	s_nop 0
	v_mul_f32_e32 v5, 0x45800000, v4
	v_cndmask_b32_e64 v54, v4, v5, s[74:75]
	global_load_dwordx4 v[2:5], v[44:45], off
	v_mul_f32_e32 v6, v6, v54
	v_mul_f32_e32 v6, v56, v6
	s_waitcnt vmcnt(0)
	v_fma_f32 v25, v10, v6, v2
	v_mul_f32_e32 v2, v7, v54
	v_mul_f32_e32 v2, v57, v2
	v_add_f32_e32 v6, 1.0, v61
	v_fma_f32 v35, v6, v2, v3
	v_mul_f32_e32 v2, v8, v54
	v_mul_f32_e32 v2, v58, v2
	v_add_f32_e32 v3, 1.0, v62
	v_fma_f32 v4, v3, v2, v4
	v_mul_f32_e32 v2, v9, v54
	v_mul_f32_e32 v2, v59, v2
	v_add_f32_e32 v3, 1.0, v63
	v_fmac_f32_e32 v5, v3, v2
	v_lshl_add_u64 v[2:3], s[80:81], 0, v[32:33]
	v_add_co_u32_e64 v2, s[74:75], s6, v2
	s_nop 1
	v_cvt_pk_bf16_f32 v6, v25, v35
	s_nop 1
	v_cvt_pk_bf16_f32 v7, v4, v5
	s_nop 1
	v_addc_co_u32_e64 v3, s[74:75], 0, v3, s[74:75]
	global_store_dwordx2 v[2:3], v[6:7], off
	v_lshl_add_u64 v[6:7], v[42:43], 0, v[36:37]
	global_load_dwordx4 v[56:59], v[28:29], off offset:1024
	global_load_dwordx4 v[8:11], v[44:45], off offset:1024
	global_load_dwordx4 v[60:63], v[6:7], off
	v_mul_f32_e32 v6, v12, v54
	s_waitcnt vmcnt(2)
	v_mul_f32_e32 v6, v56, v6
	s_waitcnt vmcnt(0)
	v_add_f32_e32 v7, 1.0, v60
	v_fma_f32 v37, v7, v6, v8
	v_mul_f32_e32 v6, v13, v54
	v_mul_f32_e32 v6, v57, v6
	v_add_f32_e32 v7, 1.0, v61
	v_fma_f32 v52, v7, v6, v9
	v_mul_f32_e32 v6, v14, v54
	v_mul_f32_e32 v6, v58, v6
	v_add_f32_e32 v7, 1.0, v62
	v_fma_f32 v53, v7, v6, v10
	v_mul_f32_e32 v6, v15, v54
	v_mul_f32_e32 v6, v59, v6
	v_add_f32_e32 v7, 1.0, v63
	v_fmac_f32_e32 v11, v7, v6
	s_nop 1
	v_cvt_pk_bf16_f32 v6, v37, v52
	s_nop 1
	v_cvt_pk_bf16_f32 v7, v53, v11
	global_store_dwordx2 v[2:3], v[6:7], off offset:512
	v_lshl_add_u64 v[56:57], v[42:43], 0, v[38:39]
	global_load_dwordx4 v[6:9], v[28:29], off offset:2048
	global_load_dwordx4 v[12:15], v[44:45], off offset:2048
	v_mul_f32_e32 v10, v20, v54
	global_load_dwordx4 v[56:59], v[56:57], off
	v_lshl_add_u64 v[42:43], v[42:43], 0, v[40:41]
	s_waitcnt vmcnt(2)
	v_mul_f32_e32 v6, v6, v10
	s_waitcnt vmcnt(0)
	v_add_f32_e32 v10, 1.0, v56
	v_fma_f32 v10, v6, v10, v12
	v_mul_f32_e32 v6, v21, v54
	v_mul_f32_e32 v6, v7, v6
	v_add_f32_e32 v7, 1.0, v57
	v_fma_f32 v12, v6, v7, v13
	v_mul_f32_e32 v6, v22, v54
	v_mul_f32_e32 v6, v8, v6
	v_add_f32_e32 v7, 1.0, v58
	v_fma_f32 v13, v6, v7, v14
	v_mul_f32_e32 v6, v23, v54
	v_mul_f32_e32 v6, v9, v6
	v_add_f32_e32 v7, 1.0, v59
	v_fmac_f32_e32 v15, v6, v7
	s_nop 1
	v_cvt_pk_bf16_f32 v6, v10, v12
	s_nop 1
	v_cvt_pk_bf16_f32 v7, v13, v15
	global_store_dwordx2 v[2:3], v[6:7], off offset:1024
	global_load_dwordx4 v[20:23], v[28:29], off offset:3072
	s_nop 0
	global_load_dwordx4 v[6:9], v[44:45], off offset:3072
	v_mul_f32_e32 v14, v16, v54
	global_load_dwordx4 v[42:45], v[42:43], off
	s_waitcnt vmcnt(2)
	v_mul_f32_e32 v14, v14, v20
	s_waitcnt vmcnt(0)
	v_add_f32_e32 v16, 1.0, v42
	v_fma_f32 v6, v14, v16, v6
	v_mul_f32_e32 v14, v17, v54
	v_mul_f32_e32 v14, v14, v21
	v_add_f32_e32 v16, 1.0, v43
	v_fma_f32 v7, v14, v16, v7
	v_mul_f32_e32 v14, v18, v54
	v_mul_f32_e32 v14, v14, v22
	v_add_f32_e32 v16, 1.0, v44
	v_fma_f32 v8, v14, v16, v8
	v_mul_f32_e32 v14, v19, v54
	v_mul_f32_e32 v14, v14, v23
	v_add_f32_e32 v16, 1.0, v45
	v_fmac_f32_e32 v9, v14, v16
	s_nop 1
	v_cvt_pk_bf16_f32 v16, v6, v7
	s_nop 1
	v_cvt_pk_bf16_f32 v17, v8, v9
	global_store_dwordx2 v[2:3], v[16:17], off offset:1536
	v_readlane_b32 s74, v254, 47
	s_nop 1
	v_add_u32_e32 v116, s74, v24
	v_min_i32_e32 v116, 0x43ff, v116
	v_mul_hi_i32 v117, v116, s100
	v_lshrrev_b32_e32 v118, 31, v117
	v_ashrrev_i32_e32 v117, 11, v117
	v_add_u32_e32 v117, v117, v118
	v_mad_i32_i24 v118, v117, s101, v116
	v_lshlrev_b32_e32 v119, 12, v118
	v_lshl_add_u32 v120, v117, 24, v119
	v_lshl_add_u32 v121, v117, 20, v119
	v_add_u32_e32 v120, 0xfff00000, v120
	v_lshrrev_b32_e32 v119, 8, v118
	v_cmp_lt_i32_e64 s[74:75], 0, v119
	v_mov_b32_e32 v122, s84
	v_mov_b32_e32 v123, s85
	v_mov_b32_e32 v118, s82
	v_mov_b32_e32 v119, s83
	v_cndmask_b32_e64 v120, v121, v120, s[74:75]
	v_mov_b32_e32 v121, 0
	v_cndmask_b32_e64 v122, v122, v118, s[74:75]
	v_cndmask_b32_e64 v123, v123, v119, s[74:75]
	v_mov_b32_e32 v118, v34
	v_mov_b32_e32 v119, 0
	v_lshl_add_u64 v[122:123], v[122:123], 0, v[120:121]
	v_lshl_add_u64 v[122:123], v[122:123], 0, v[118:119]
	global_load_dwordx4 v[100:103], v[122:123], off
	global_load_dwordx4 v[104:107], v[122:123], off offset:1024
	global_load_dwordx4 v[108:111], v[122:123], off offset:2048
	global_load_dwordx4 v[112:115], v[122:123], off offset:3072
	ds_read_b128 v[16:19], v51
	ds_read_b128 v[42:45], v51 offset:16384
	ds_read_b128 v[54:57], v51 offset:28672
	s_waitcnt lgkmcnt(2)
	v_mul_f32_e32 v2, v35, v17
	v_fmac_f32_e32 v2, v25, v16
	v_fmac_f32_e32 v2, v4, v18
	v_fmac_f32_e32 v2, v5, v19
	ds_read_b128 v[16:19], v51 offset:1024
	v_add_f32_e32 v2, 0, v2
	s_waitcnt lgkmcnt(0)
	v_mul_f32_e32 v3, v52, v17
	v_fmac_f32_e32 v3, v37, v16
	v_fmac_f32_e32 v3, v53, v18
	v_fmac_f32_e32 v3, v11, v19
	ds_read_b128 v[16:19], v51 offset:2048
	v_add_f32_e32 v2, v2, v3
	s_waitcnt lgkmcnt(0)
	v_mul_f32_e32 v3, v12, v17
	v_fmac_f32_e32 v3, v10, v16
	v_fmac_f32_e32 v3, v13, v18
	v_fmac_f32_e32 v3, v15, v19
	ds_read_b128 v[16:19], v51 offset:3072
	v_add_f32_e32 v2, v2, v3
	s_waitcnt lgkmcnt(0)
	v_mul_f32_e32 v3, v7, v17
	v_fmac_f32_e32 v3, v6, v16
	v_fmac_f32_e32 v3, v8, v18
	v_fmac_f32_e32 v3, v9, v19
	ds_read_b128 v[16:19], v51 offset:4096
	v_add_f32_e32 v2, v2, v3
	ds_bpermute_b32 v3, v1, v2
	s_waitcnt lgkmcnt(1)
	v_mul_f32_e32 v14, v35, v17
	v_fmac_f32_e32 v14, v25, v16
	v_fmac_f32_e32 v14, v4, v18
	v_fmac_f32_e32 v14, v5, v19
	ds_read_b128 v[16:19], v51 offset:5120
	v_add_f32_e32 v14, 0, v14
	s_waitcnt lgkmcnt(1)
	v_add_f32_e32 v2, v2, v3
	ds_bpermute_b32 v3, v46, v2
	s_waitcnt lgkmcnt(1)
	v_mul_f32_e32 v17, v52, v17
	v_fmac_f32_e32 v17, v37, v16
	v_fmac_f32_e32 v17, v53, v18
	v_fmac_f32_e32 v17, v11, v19
	v_add_f32_e32 v14, v14, v17
	ds_read_b128 v[16:19], v51 offset:6144
	s_waitcnt lgkmcnt(1)
	v_add_f32_e32 v2, v2, v3
	ds_bpermute_b32 v3, v47, v2
	s_waitcnt lgkmcnt(1)
	v_mul_f32_e32 v17, v12, v17
	v_fmac_f32_e32 v17, v10, v16
	v_fmac_f32_e32 v17, v13, v18
	v_fmac_f32_e32 v17, v15, v19
	v_add_f32_e32 v14, v14, v17
	ds_read_b128 v[16:19], v51 offset:7168
	s_waitcnt lgkmcnt(1)
	v_add_f32_e32 v2, v2, v3
	ds_bpermute_b32 v3, v48, v2
	s_waitcnt lgkmcnt(1)
	v_mul_f32_e32 v17, v7, v17
	v_fmac_f32_e32 v17, v6, v16
	v_fmac_f32_e32 v17, v8, v18
	v_fmac_f32_e32 v17, v9, v19
	ds_read_b128 v[18:21], v51 offset:8192
	v_add_f32_e32 v14, v14, v17
	ds_bpermute_b32 v16, v1, v14
	s_waitcnt lgkmcnt(2)
	v_add_f32_e32 v2, v2, v3
	ds_bpermute_b32 v3, v49, v2
	s_waitcnt lgkmcnt(2)
	v_mul_f32_e32 v17, v35, v19
	v_fmac_f32_e32 v17, v25, v18
	v_fmac_f32_e32 v17, v4, v20
	v_fmac_f32_e32 v17, v5, v21
	ds_read_b128 v[18:21], v51 offset:9216
	v_add_f32_e32 v17, 0, v17
	s_waitcnt lgkmcnt(2)
	v_add_f32_e32 v14, v14, v16
	ds_bpermute_b32 v16, v46, v14
	s_waitcnt lgkmcnt(2)
	v_add_f32_e32 v2, v2, v3
	s_waitcnt lgkmcnt(1)
	v_mul_f32_e32 v19, v52, v19
	v_fmac_f32_e32 v19, v37, v18
	v_fmac_f32_e32 v19, v53, v20
	v_fmac_f32_e32 v19, v11, v21
	v_add_f32_e32 v17, v17, v19
	ds_read_b128 v[18:21], v51 offset:10240
	s_waitcnt lgkmcnt(1)
	v_add_f32_e32 v14, v14, v16
	ds_bpermute_b32 v16, v47, v14
	ds_bpermute_b32 v3, v50, v2
	s_waitcnt lgkmcnt(2)
	v_mul_f32_e32 v19, v12, v19
	v_fmac_f32_e32 v19, v10, v18
	v_fmac_f32_e32 v19, v13, v20
	v_fmac_f32_e32 v19, v15, v21
	v_add_f32_e32 v17, v17, v19
	ds_read_b128 v[18:21], v51 offset:11264
	s_waitcnt lgkmcnt(2)
	v_add_f32_e32 v14, v14, v16
	ds_bpermute_b32 v16, v48, v14
	s_waitcnt lgkmcnt(1)
	v_mul_f32_e32 v19, v7, v19
	v_fmac_f32_e32 v19, v6, v18
	v_fmac_f32_e32 v19, v8, v20
	v_fmac_f32_e32 v19, v9, v21
	ds_read_b128 v[20:23], v51 offset:12288
	v_add_f32_e32 v17, v17, v19
	ds_bpermute_b32 v18, v1, v17
	s_waitcnt lgkmcnt(2)
	v_add_f32_e32 v14, v14, v16
	ds_bpermute_b32 v16, v49, v14
	s_waitcnt lgkmcnt(2)
	v_mul_f32_e32 v19, v35, v21
	v_fmac_f32_e32 v19, v25, v20
	v_fmac_f32_e32 v19, v4, v22
	v_fmac_f32_e32 v19, v5, v23
	ds_read_b128 v[20:23], v51 offset:13312
	v_add_f32_e32 v19, 0, v19
	s_waitcnt lgkmcnt(2)
	v_add_f32_e32 v17, v17, v18
	ds_bpermute_b32 v18, v46, v17
	s_waitcnt lgkmcnt(2)
	v_add_f32_e32 v14, v14, v16
	s_waitcnt lgkmcnt(1)
	v_mul_f32_e32 v21, v52, v21
	v_fmac_f32_e32 v21, v37, v20
	v_fmac_f32_e32 v21, v53, v22
	v_fmac_f32_e32 v21, v11, v23
	v_add_f32_e32 v19, v19, v21
	ds_read_b128 v[20:23], v51 offset:14336
	s_waitcnt lgkmcnt(1)
	v_add_f32_e32 v17, v17, v18
	ds_bpermute_b32 v18, v47, v17
	ds_bpermute_b32 v16, v50, v14
	s_waitcnt lgkmcnt(2)
	v_mul_f32_e32 v21, v12, v21
	v_fmac_f32_e32 v21, v10, v20
	v_fmac_f32_e32 v21, v13, v22
	v_fmac_f32_e32 v21, v15, v23
	v_add_f32_e32 v19, v19, v21
	ds_read_b128 v[20:23], v51 offset:15360
	s_waitcnt lgkmcnt(2)
	v_add_f32_e32 v17, v17, v18
	ds_bpermute_b32 v18, v48, v17
	s_waitcnt lgkmcnt(1)
	v_mul_f32_e32 v21, v7, v21
	v_fmac_f32_e32 v21, v6, v20
	v_fmac_f32_e32 v21, v8, v22
	v_fmac_f32_e32 v21, v9, v23
	v_add_f32_e32 v19, v19, v21
	v_mul_f32_e32 v21, v35, v43
	v_fmac_f32_e32 v21, v25, v42
	v_fmac_f32_e32 v21, v4, v44
	v_fmac_f32_e32 v21, v5, v45
	ds_read_b128 v[42:45], v51 offset:17408
	v_add_f32_e32 v21, 0, v21
	ds_bpermute_b32 v20, v1, v19
	s_waitcnt lgkmcnt(2)
	v_add_f32_e32 v17, v17, v18
	ds_bpermute_b32 v18, v49, v17
	s_waitcnt lgkmcnt(2)
	v_mul_f32_e32 v22, v52, v43
	v_fmac_f32_e32 v22, v37, v42
	v_fmac_f32_e32 v22, v53, v44
	v_fmac_f32_e32 v22, v11, v45
	ds_read_b128 v[42:45], v51 offset:18432
	v_add_f32_e32 v21, v21, v22
	s_waitcnt lgkmcnt(2)
	v_add_f32_e32 v19, v19, v20
	ds_bpermute_b32 v20, v46, v19
	s_waitcnt lgkmcnt(2)
	v_add_f32_e32 v17, v17, v18
	s_waitcnt lgkmcnt(1)
	v_mul_f32_e32 v22, v12, v43
	v_fmac_f32_e32 v22, v10, v42
	v_fmac_f32_e32 v22, v13, v44
	v_fmac_f32_e32 v22, v15, v45
	ds_read_b128 v[42:45], v51 offset:19456
	v_add_f32_e32 v21, v21, v22
	s_waitcnt lgkmcnt(1)
	v_add_f32_e32 v19, v19, v20
	ds_bpermute_b32 v20, v47, v19
	ds_bpermute_b32 v18, v50, v17
	s_waitcnt lgkmcnt(2)
	v_mul_f32_e32 v22, v7, v43
	v_fmac_f32_e32 v22, v6, v42
	v_fmac_f32_e32 v22, v8, v44
	v_fmac_f32_e32 v22, v9, v45
	ds_read_b128 v[42:45], v51 offset:20480
	v_add_f32_e32 v21, v21, v22
	ds_bpermute_b32 v22, v1, v21
	s_waitcnt lgkmcnt(3)
	v_add_f32_e32 v19, v19, v20
	ds_bpermute_b32 v20, v48, v19
	s_waitcnt lgkmcnt(2)
	v_mul_f32_e32 v23, v35, v43
	v_fmac_f32_e32 v23, v25, v42
	v_fmac_f32_e32 v23, v4, v44
	v_fmac_f32_e32 v23, v5, v45
	ds_read_b128 v[42:45], v51 offset:21504
	v_add_f32_e32 v23, 0, v23
	s_waitcnt lgkmcnt(2)
	v_add_f32_e32 v21, v21, v22
	ds_bpermute_b32 v22, v46, v21
	s_waitcnt lgkmcnt(2)
	v_add_f32_e32 v19, v19, v20
	s_waitcnt lgkmcnt(1)
	v_mul_f32_e32 v39, v52, v43
	v_fmac_f32_e32 v39, v37, v42
	v_fmac_f32_e32 v39, v53, v44
	v_fmac_f32_e32 v39, v11, v45
	ds_read_b128 v[42:45], v51 offset:22528
	v_add_f32_e32 v23, v23, v39
	s_waitcnt lgkmcnt(1)
	v_add_f32_e32 v21, v21, v22
	ds_bpermute_b32 v22, v47, v21
	ds_bpermute_b32 v20, v49, v19
	s_waitcnt lgkmcnt(2)
	v_mul_f32_e32 v39, v12, v43
	v_fmac_f32_e32 v39, v10, v42
	v_fmac_f32_e32 v39, v13, v44
	v_fmac_f32_e32 v39, v15, v45
	ds_read_b128 v[42:45], v51 offset:23552
	v_add_f32_e32 v23, v23, v39
	s_waitcnt lgkmcnt(2)
	v_add_f32_e32 v21, v21, v22
	ds_bpermute_b32 v22, v48, v21
	s_waitcnt lgkmcnt(2)
	v_add_f32_e32 v19, v19, v20
	s_waitcnt lgkmcnt(1)
	v_mul_f32_e32 v39, v7, v43
	v_fmac_f32_e32 v39, v6, v42
	v_fmac_f32_e32 v39, v8, v44
	v_fmac_f32_e32 v39, v9, v45
	ds_read_b128 v[42:45], v51 offset:24576
	v_add_f32_e32 v23, v23, v39
	ds_bpermute_b32 v39, v1, v23
	s_waitcnt lgkmcnt(2)
	v_add_f32_e32 v21, v21, v22
	ds_bpermute_b32 v22, v49, v21
	s_waitcnt lgkmcnt(2)
	v_mul_f32_e32 v41, v35, v43
	v_fmac_f32_e32 v41, v25, v42
	v_fmac_f32_e32 v41, v4, v44
	v_fmac_f32_e32 v41, v5, v45
	ds_read_b128 v[42:45], v51 offset:25600
	v_add_f32_e32 v41, 0, v41
	s_waitcnt lgkmcnt(2)
	v_add_f32_e32 v23, v23, v39
	ds_bpermute_b32 v39, v46, v23
	s_waitcnt lgkmcnt(2)
	v_add_f32_e32 v21, v21, v22
	s_waitcnt lgkmcnt(1)
	v_mul_f32_e32 v43, v52, v43
	v_fmac_f32_e32 v43, v37, v42
	v_fmac_f32_e32 v43, v53, v44
	v_fmac_f32_e32 v43, v11, v45
	v_add_f32_e32 v41, v41, v43
	ds_read_b128 v[42:45], v51 offset:26624
	s_waitcnt lgkmcnt(1)
	v_add_f32_e32 v23, v23, v39
	ds_bpermute_b32 v39, v47, v23
	ds_bpermute_b32 v20, v50, v19
	ds_bpermute_b32 v22, v50, v21
	s_waitcnt lgkmcnt(3)
	v_mul_f32_e32 v43, v12, v43
	v_fmac_f32_e32 v43, v10, v42
	v_fmac_f32_e32 v43, v13, v44
	v_fmac_f32_e32 v43, v15, v45
	v_add_f32_e32 v41, v41, v43
	ds_read_b128 v[42:45], v51 offset:27648
	s_waitcnt lgkmcnt(3)
	v_add_f32_e32 v23, v23, v39
	ds_bpermute_b32 v39, v48, v23
	s_waitcnt lgkmcnt(1)
	v_mul_f32_e32 v43, v7, v43
	v_fmac_f32_e32 v43, v6, v42
	v_fmac_f32_e32 v43, v8, v44
	v_fmac_f32_e32 v43, v9, v45
	v_add_f32_e32 v41, v41, v43
	v_mul_f32_e32 v43, v35, v55
	v_fmac_f32_e32 v43, v25, v54
	v_fmac_f32_e32 v43, v4, v56
	v_fmac_f32_e32 v43, v5, v57
	ds_read_b128 v[54:57], v51 offset:29696
	v_add_f32_e32 v43, 0, v43
	ds_bpermute_b32 v42, v1, v41
	s_waitcnt lgkmcnt(2)
	v_add_f32_e32 v23, v23, v39
	ds_bpermute_b32 v39, v49, v23
	s_waitcnt lgkmcnt(2)
	v_mul_f32_e32 v44, v52, v55
	v_fmac_f32_e32 v44, v37, v54
	v_fmac_f32_e32 v44, v53, v56
	v_fmac_f32_e32 v44, v11, v57
	ds_read_b128 v[54:57], v51 offset:30720
	v_add_f32_e32 v43, v43, v44
	s_waitcnt lgkmcnt(2)
	v_add_f32_e32 v41, v41, v42
	ds_bpermute_b32 v42, v46, v41
	s_waitcnt lgkmcnt(2)
	v_add_f32_e32 v23, v23, v39
	s_waitcnt lgkmcnt(1)
	v_mul_f32_e32 v44, v12, v55
	v_fmac_f32_e32 v44, v10, v54
	v_fmac_f32_e32 v44, v13, v56
	v_fmac_f32_e32 v44, v15, v57
	ds_read_b128 v[54:57], v51 offset:31744
	v_add_f32_e32 v43, v43, v44
	s_waitcnt lgkmcnt(1)
	v_add_f32_e32 v41, v41, v42
	ds_bpermute_b32 v42, v47, v41
	ds_bpermute_b32 v39, v50, v23
	s_waitcnt lgkmcnt(2)
	v_mul_f32_e32 v44, v7, v55
	v_fmac_f32_e32 v44, v6, v54
	v_fmac_f32_e32 v44, v8, v56
	v_fmac_f32_e32 v44, v9, v57
	ds_read_b128 v[54:57], v51 offset:32768
	v_add_f32_e32 v43, v43, v44
	ds_bpermute_b32 v44, v1, v43
	s_waitcnt lgkmcnt(3)
	v_add_f32_e32 v41, v41, v42
	ds_bpermute_b32 v42, v48, v41
	s_waitcnt lgkmcnt(2)
	v_mul_f32_e32 v45, v35, v55
	v_fmac_f32_e32 v45, v25, v54
	v_fmac_f32_e32 v45, v4, v56
	v_fmac_f32_e32 v45, v5, v57
	ds_read_b128 v[54:57], v51 offset:33792
	v_add_f32_e32 v45, 0, v45
	s_waitcnt lgkmcnt(2)
	v_add_f32_e32 v43, v43, v44
	ds_bpermute_b32 v44, v46, v43
	s_waitcnt lgkmcnt(2)
	v_add_f32_e32 v41, v41, v42
	s_waitcnt lgkmcnt(1)
	v_mul_f32_e32 v55, v52, v55
	v_fmac_f32_e32 v55, v37, v54
	v_fmac_f32_e32 v55, v53, v56
	v_fmac_f32_e32 v55, v11, v57
	v_add_f32_e32 v45, v45, v55
	ds_read_b128 v[54:57], v51 offset:34816
	s_waitcnt lgkmcnt(1)
	v_add_f32_e32 v43, v43, v44
	ds_bpermute_b32 v44, v47, v43
	ds_bpermute_b32 v42, v49, v41
	s_waitcnt lgkmcnt(2)
	v_mul_f32_e32 v55, v12, v55
	v_fmac_f32_e32 v55, v10, v54
	v_fmac_f32_e32 v55, v13, v56
	v_fmac_f32_e32 v55, v15, v57
	v_add_f32_e32 v45, v45, v55
	ds_read_b128 v[54:57], v51 offset:35840
	s_waitcnt lgkmcnt(2)
	v_add_f32_e32 v43, v43, v44
	ds_bpermute_b32 v44, v48, v43
	s_waitcnt lgkmcnt(2)
	v_add_f32_e32 v41, v41, v42
	ds_bpermute_b32 v42, v50, v41
	s_waitcnt lgkmcnt(2)
	v_mul_f32_e32 v55, v7, v55
	v_fmac_f32_e32 v55, v6, v54
	v_fmac_f32_e32 v55, v8, v56
	v_fmac_f32_e32 v55, v9, v57
	ds_read_b128 v[56:59], v51 offset:36864
	v_add_f32_e32 v45, v45, v55
	ds_bpermute_b32 v54, v1, v45
	s_waitcnt lgkmcnt(3)
	v_add_f32_e32 v43, v43, v44
	ds_bpermute_b32 v44, v49, v43
	s_waitcnt lgkmcnt(2)
	v_mul_f32_e32 v55, v35, v57
	v_fmac_f32_e32 v55, v25, v56
	v_fmac_f32_e32 v55, v4, v58
	v_fmac_f32_e32 v55, v5, v59
	ds_read_b128 v[56:59], v51 offset:37888
	v_add_f32_e32 v55, 0, v55
	s_waitcnt lgkmcnt(2)
	v_add_f32_e32 v45, v45, v54
	ds_bpermute_b32 v54, v46, v45
	s_waitcnt lgkmcnt(2)
	v_add_f32_e32 v43, v43, v44
	s_waitcnt lgkmcnt(1)
	v_mul_f32_e32 v57, v52, v57
	v_fmac_f32_e32 v57, v37, v56
	v_fmac_f32_e32 v57, v53, v58
	v_fmac_f32_e32 v57, v11, v59
	v_add_f32_e32 v55, v55, v57
	ds_read_b128 v[56:59], v51 offset:38912
	s_waitcnt lgkmcnt(1)
	v_add_f32_e32 v45, v45, v54
	ds_bpermute_b32 v54, v47, v45
	ds_bpermute_b32 v44, v50, v43
	s_waitcnt lgkmcnt(2)
	v_mul_f32_e32 v57, v12, v57
	v_fmac_f32_e32 v57, v10, v56
	v_fmac_f32_e32 v57, v13, v58
	v_fmac_f32_e32 v57, v15, v59
	v_add_f32_e32 v55, v55, v57
	ds_read_b128 v[56:59], v51 offset:39936
	s_waitcnt lgkmcnt(2)
	v_add_f32_e32 v45, v45, v54
	ds_bpermute_b32 v54, v48, v45
	s_waitcnt lgkmcnt(1)
	v_mul_f32_e32 v57, v7, v57
	v_fmac_f32_e32 v57, v6, v56
	v_fmac_f32_e32 v57, v8, v58
	v_fmac_f32_e32 v57, v9, v59
	ds_read_b128 v[58:61], v51 offset:40960
	v_add_f32_e32 v55, v55, v57
	ds_bpermute_b32 v56, v1, v55
	s_waitcnt lgkmcnt(2)
	v_add_f32_e32 v45, v45, v54
	ds_bpermute_b32 v54, v49, v45
	s_waitcnt lgkmcnt(2)
	v_mul_f32_e32 v57, v35, v59
	v_fmac_f32_e32 v57, v25, v58
	v_fmac_f32_e32 v57, v4, v60
	v_fmac_f32_e32 v57, v5, v61
	ds_read_b128 v[58:61], v51 offset:41984
	v_add_f32_e32 v57, 0, v57
	s_waitcnt lgkmcnt(2)
	v_add_f32_e32 v55, v55, v56
	ds_bpermute_b32 v56, v46, v55
	s_waitcnt lgkmcnt(2)
	v_add_f32_e32 v45, v45, v54
	s_waitcnt lgkmcnt(1)
	v_mul_f32_e32 v59, v52, v59
	v_fmac_f32_e32 v59, v37, v58
	v_fmac_f32_e32 v59, v53, v60
	v_fmac_f32_e32 v59, v11, v61
	v_add_f32_e32 v57, v57, v59
	ds_read_b128 v[58:61], v51 offset:43008
	s_waitcnt lgkmcnt(1)
	v_add_f32_e32 v55, v55, v56
	ds_bpermute_b32 v56, v47, v55
	ds_bpermute_b32 v54, v50, v45
	s_waitcnt lgkmcnt(2)
	v_mul_f32_e32 v59, v12, v59
	v_fmac_f32_e32 v59, v10, v58
	v_fmac_f32_e32 v59, v13, v60
	v_fmac_f32_e32 v59, v15, v61
	v_add_f32_e32 v57, v57, v59
	ds_read_b128 v[58:61], v51 offset:44032
	s_waitcnt lgkmcnt(2)
	v_add_f32_e32 v55, v55, v56
	ds_bpermute_b32 v56, v48, v55
	s_waitcnt lgkmcnt(1)
	v_mul_f32_e32 v59, v7, v59
	v_fmac_f32_e32 v59, v6, v58
	v_fmac_f32_e32 v59, v8, v60
	v_fmac_f32_e32 v59, v9, v61
	ds_read_b128 v[60:63], v51 offset:45056
	v_add_f32_e32 v57, v57, v59
	ds_bpermute_b32 v58, v1, v57
	s_waitcnt lgkmcnt(2)
	v_add_f32_e32 v55, v55, v56
	ds_bpermute_b32 v56, v49, v55
	s_waitcnt lgkmcnt(2)
	v_mul_f32_e32 v59, v35, v61
	v_fmac_f32_e32 v59, v25, v60
	v_fmac_f32_e32 v59, v4, v62
	v_fmac_f32_e32 v59, v5, v63
	ds_read_b128 v[60:63], v51 offset:46080
	v_add_f32_e32 v59, 0, v59
	s_waitcnt lgkmcnt(2)
	v_add_f32_e32 v57, v57, v58
	ds_bpermute_b32 v58, v46, v57
	s_waitcnt lgkmcnt(2)
	v_add_f32_e32 v55, v55, v56
	s_waitcnt lgkmcnt(1)
	v_mul_f32_e32 v61, v52, v61
	v_fmac_f32_e32 v61, v37, v60
	v_fmac_f32_e32 v61, v53, v62
	v_fmac_f32_e32 v61, v11, v63
	v_add_f32_e32 v59, v59, v61
	ds_read_b128 v[60:63], v51 offset:47104
	s_waitcnt lgkmcnt(1)
	v_add_f32_e32 v57, v57, v58
	ds_bpermute_b32 v58, v47, v57
	ds_bpermute_b32 v56, v50, v55
	s_waitcnt lgkmcnt(2)
	v_mul_f32_e32 v61, v12, v61
	v_fmac_f32_e32 v61, v10, v60
	v_fmac_f32_e32 v61, v13, v62
	v_fmac_f32_e32 v61, v15, v63
	v_add_f32_e32 v59, v59, v61
	ds_read_b128 v[60:63], v51 offset:48128
	s_waitcnt lgkmcnt(2)
	v_add_f32_e32 v57, v57, v58
	ds_bpermute_b32 v58, v48, v57
	s_waitcnt lgkmcnt(1)
	v_mul_f32_e32 v61, v7, v61
	v_fmac_f32_e32 v61, v6, v60
	v_fmac_f32_e32 v61, v8, v62
	v_fmac_f32_e32 v61, v9, v63
	ds_read_b128 v[62:65], v51 offset:49152
	v_add_f32_e32 v59, v59, v61
	ds_bpermute_b32 v60, v1, v59
	s_waitcnt lgkmcnt(2)
	v_add_f32_e32 v57, v57, v58
	ds_bpermute_b32 v58, v49, v57
	s_waitcnt lgkmcnt(2)
	v_mul_f32_e32 v61, v35, v63
	v_fmac_f32_e32 v61, v25, v62
	v_fmac_f32_e32 v61, v4, v64
	v_fmac_f32_e32 v61, v5, v65
	ds_read_b128 v[62:65], v51 offset:50176
	v_add_f32_e32 v61, 0, v61
	s_waitcnt lgkmcnt(2)
	v_add_f32_e32 v59, v59, v60
	ds_bpermute_b32 v60, v46, v59
	s_waitcnt lgkmcnt(2)
	v_add_f32_e32 v57, v57, v58
	s_waitcnt lgkmcnt(1)
	v_mul_f32_e32 v63, v52, v63
	v_fmac_f32_e32 v63, v37, v62
	v_fmac_f32_e32 v63, v53, v64
	v_fmac_f32_e32 v63, v11, v65
	v_add_f32_e32 v61, v61, v63
	ds_read_b128 v[62:65], v51 offset:51200
	s_waitcnt lgkmcnt(1)
	v_add_f32_e32 v59, v59, v60
	ds_bpermute_b32 v60, v47, v59
	ds_bpermute_b32 v58, v50, v57
	s_waitcnt lgkmcnt(2)
	v_mul_f32_e32 v63, v12, v63
	v_fmac_f32_e32 v63, v10, v62
	v_fmac_f32_e32 v63, v13, v64
	v_fmac_f32_e32 v63, v15, v65
	v_add_f32_e32 v61, v61, v63
	ds_read_b128 v[62:65], v51 offset:52224
	s_waitcnt lgkmcnt(2)
	v_add_f32_e32 v59, v59, v60
	ds_bpermute_b32 v60, v48, v59
	s_waitcnt lgkmcnt(1)
	v_mul_f32_e32 v63, v7, v63
	v_fmac_f32_e32 v63, v6, v62
	v_fmac_f32_e32 v63, v8, v64
	v_fmac_f32_e32 v63, v9, v65
	ds_read_b128 v[64:67], v51 offset:53248
	v_add_f32_e32 v61, v61, v63
	ds_bpermute_b32 v62, v1, v61
	s_waitcnt lgkmcnt(2)
	v_add_f32_e32 v59, v59, v60
	ds_bpermute_b32 v60, v49, v59
	s_waitcnt lgkmcnt(2)
	v_mul_f32_e32 v63, v35, v65
	v_fmac_f32_e32 v63, v25, v64
	v_fmac_f32_e32 v63, v4, v66
	v_fmac_f32_e32 v63, v5, v67
	ds_read_b128 v[64:67], v51 offset:54272
	v_add_f32_e32 v63, 0, v63
	s_waitcnt lgkmcnt(2)
	v_add_f32_e32 v61, v61, v62
	ds_bpermute_b32 v62, v46, v61
	s_waitcnt lgkmcnt(2)
	v_add_f32_e32 v59, v59, v60
	s_waitcnt lgkmcnt(1)
	v_mul_f32_e32 v65, v52, v65
	v_fmac_f32_e32 v65, v37, v64
	v_fmac_f32_e32 v65, v53, v66
	v_fmac_f32_e32 v65, v11, v67
	v_add_f32_e32 v63, v63, v65
	ds_read_b128 v[64:67], v51 offset:55296
	s_waitcnt lgkmcnt(1)
	v_add_f32_e32 v61, v61, v62
	ds_bpermute_b32 v62, v47, v61
	ds_bpermute_b32 v60, v50, v59
	s_waitcnt lgkmcnt(2)
	v_mul_f32_e32 v65, v12, v65
	v_fmac_f32_e32 v65, v10, v64
	v_fmac_f32_e32 v65, v13, v66
	v_fmac_f32_e32 v65, v15, v67
	v_add_f32_e32 v63, v63, v65
	ds_read_b128 v[64:67], v51 offset:56320
	s_waitcnt lgkmcnt(2)
	v_add_f32_e32 v61, v61, v62
	ds_bpermute_b32 v62, v48, v61
	s_waitcnt lgkmcnt(1)
	v_mul_f32_e32 v65, v7, v65
	v_fmac_f32_e32 v65, v6, v64
	v_fmac_f32_e32 v65, v8, v66
	v_fmac_f32_e32 v65, v9, v67
	ds_read_b128 v[66:69], v51 offset:57344
	v_add_f32_e32 v63, v63, v65
	ds_bpermute_b32 v64, v1, v63
	s_waitcnt lgkmcnt(2)
	v_add_f32_e32 v61, v61, v62
	ds_bpermute_b32 v62, v49, v61
	s_waitcnt lgkmcnt(2)
	v_mul_f32_e32 v65, v35, v67
	v_fmac_f32_e32 v65, v25, v66
	v_fmac_f32_e32 v65, v4, v68
	v_fmac_f32_e32 v65, v5, v69
	ds_read_b128 v[66:69], v51 offset:58368
	v_add_f32_e32 v65, 0, v65
	s_waitcnt lgkmcnt(2)
	v_add_f32_e32 v63, v63, v64
	ds_bpermute_b32 v64, v46, v63
	s_waitcnt lgkmcnt(2)
	v_add_f32_e32 v61, v61, v62
	s_waitcnt lgkmcnt(1)
	v_mul_f32_e32 v67, v52, v67
	v_fmac_f32_e32 v67, v37, v66
	v_fmac_f32_e32 v67, v53, v68
	v_fmac_f32_e32 v67, v11, v69
	v_add_f32_e32 v65, v65, v67
	ds_read_b128 v[66:69], v51 offset:59392
	s_waitcnt lgkmcnt(1)
	v_add_f32_e32 v63, v63, v64
	ds_bpermute_b32 v64, v47, v63
	ds_bpermute_b32 v62, v50, v61
	s_waitcnt lgkmcnt(2)
	v_mul_f32_e32 v67, v12, v67
	v_fmac_f32_e32 v67, v10, v66
	v_fmac_f32_e32 v67, v13, v68
	v_fmac_f32_e32 v67, v15, v69
	v_add_f32_e32 v65, v65, v67
	ds_read_b128 v[66:69], v51 offset:60416
	s_waitcnt lgkmcnt(2)
	v_add_f32_e32 v63, v63, v64
	ds_bpermute_b32 v64, v48, v63
	s_waitcnt lgkmcnt(1)
	v_mul_f32_e32 v67, v7, v67
	v_fmac_f32_e32 v67, v6, v66
	v_fmac_f32_e32 v67, v8, v68
	v_fmac_f32_e32 v67, v9, v69
	ds_read_b128 v[68:71], v51 offset:61440
	v_add_f32_e32 v65, v65, v67
	ds_bpermute_b32 v66, v1, v65
	s_waitcnt lgkmcnt(2)
	v_add_f32_e32 v63, v63, v64
	ds_bpermute_b32 v64, v49, v63
	s_waitcnt lgkmcnt(2)
	v_mul_f32_e32 v35, v35, v69
	v_fmac_f32_e32 v35, v25, v68
	v_fmac_f32_e32 v35, v4, v70
	v_fmac_f32_e32 v35, v5, v71
	ds_read_b128 v[68:71], v51 offset:62464
	v_add_f32_e32 v4, 0, v35
	s_waitcnt lgkmcnt(2)
	v_add_f32_e32 v65, v65, v66
	ds_bpermute_b32 v66, v46, v65
	s_waitcnt lgkmcnt(2)
	v_add_f32_e32 v63, v63, v64
	s_waitcnt lgkmcnt(1)
	v_mul_f32_e32 v5, v52, v69
	v_fmac_f32_e32 v5, v37, v68
	v_fmac_f32_e32 v5, v53, v70
	v_fmac_f32_e32 v5, v11, v71
	ds_read_b128 v[68:71], v51 offset:63488
	v_add_f32_e32 v4, v4, v5
	s_waitcnt lgkmcnt(1)
	v_add_f32_e32 v65, v65, v66
	ds_bpermute_b32 v66, v47, v65
	ds_bpermute_b32 v64, v50, v63
	s_waitcnt lgkmcnt(2)
	v_mul_f32_e32 v5, v12, v69
	v_fmac_f32_e32 v5, v10, v68
	v_fmac_f32_e32 v5, v13, v70
	ds_read_b128 v[10:13], v51 offset:64512
	v_fmac_f32_e32 v5, v15, v71
	v_add_f32_e32 v4, v4, v5
	s_waitcnt lgkmcnt(2)
	v_add_f32_e32 v65, v65, v66
	ds_bpermute_b32 v66, v48, v65
	s_waitcnt lgkmcnt(1)
	v_mul_f32_e32 v5, v7, v11
	v_fmac_f32_e32 v5, v6, v10
	v_fmac_f32_e32 v5, v8, v12
	v_fmac_f32_e32 v5, v9, v13
	v_add_f32_e32 v4, v4, v5
	ds_bpermute_b32 v5, v1, v4
	s_waitcnt lgkmcnt(1)
	v_add_f32_e32 v65, v65, v66
	ds_bpermute_b32 v66, v49, v65
	s_waitcnt lgkmcnt(1)
	v_add_f32_e32 v4, v4, v5
	ds_bpermute_b32 v5, v46, v4
	s_waitcnt lgkmcnt(1)
	v_add_f32_e32 v65, v65, v66
	ds_bpermute_b32 v66, v50, v65
	s_waitcnt lgkmcnt(1)
	v_add_f32_e32 v4, v4, v5
	ds_bpermute_b32 v5, v47, v4
	s_waitcnt lgkmcnt(0)
	v_add_f32_e32 v4, v4, v5
	ds_bpermute_b32 v5, v48, v4
	s_waitcnt lgkmcnt(0)
	v_add_f32_e32 v4, v4, v5
	ds_bpermute_b32 v5, v49, v4
	s_waitcnt lgkmcnt(0)
	v_add_f32_e32 v4, v4, v5
	ds_bpermute_b32 v5, v50, v4
	s_and_saveexec_b64 s[10:11], vcc
	s_cbranch_execz .LBB0_170
	s_load_dwordx2 s[14:15], s[12:13], 0x40
	v_add_f32_e32 v2, v2, v3
	v_add_f32_e32 v14, v14, v16
	v_cndmask_b32_e64 v2, 0, v2, s[72:73]
	v_add_f32_e32 v17, v17, v18
	s_waitcnt lgkmcnt(0)
	v_lshl_add_u64 v[6:7], v[26:27], 2, s[14:15]
	global_load_dword v6, v[6:7], off
	v_cndmask_b32_e64 v2, v2, v14, s[70:71]
	v_add_f32_e32 v19, v19, v20
	v_cndmask_b32_e64 v2, v2, v17, s[68:69]
	v_add_f32_e32 v21, v21, v22
	v_cndmask_b32_e64 v2, v2, v19, s[66:67]
	v_add_f32_e32 v23, v23, v39
	v_cndmask_b32_e64 v2, v2, v21, s[64:65]
	v_add_f32_e32 v15, v41, v42
	v_cndmask_b32_e64 v2, v2, v23, s[62:63]
	v_add_f32_e32 v13, v43, v44
	v_cndmask_b32_e64 v2, v2, v15, s[60:61]
	v_add_f32_e32 v12, v45, v54
	v_cndmask_b32_e64 v2, v2, v13, s[58:59]
	v_add_f32_e32 v11, v55, v56
	v_cndmask_b32_e64 v2, v2, v12, s[56:57]
	v_add_f32_e32 v10, v57, v58
	v_cndmask_b32_e64 v2, v2, v11, s[54:55]
	v_add_f32_e32 v9, v59, v60
	v_cndmask_b32_e64 v2, v2, v10, s[52:53]
	v_add_f32_e32 v8, v61, v62
	v_cndmask_b32_e64 v2, v2, v9, s[50:51]
	v_add_f32_e32 v7, v63, v64
	v_cndmask_b32_e64 v2, v2, v8, s[48:49]
	v_add_f32_e32 v4, v4, v5
	v_add_f32_e32 v5, v65, v66
	v_cndmask_b32_e64 v2, v2, v7, s[46:47]
	v_cndmask_b32_e64 v2, v2, v5, s[44:45]
	v_cndmask_b32_e64 v2, v2, v4, s[42:43]
	s_waitcnt vmcnt(0)
	v_add_f32_e32 v2, v2, v6
	s_and_saveexec_b64 s[14:15], s[40:41]
	s_cbranch_execz .LBB0_169
	s_mov_b32 s6, 0xbfb8aa3b
	v_mul_f32_e64 v3, |v2|, s6
	v_exp_f32_e32 v3, v3
	s_mov_b32 s6, 0x3f317217
	v_max_f32_e32 v2, v2, v2
	v_min_f32_e32 v2, 0, v2
	v_add_f32_e32 v3, 1.0, v3
	v_cmp_gt_f32_e64 s[74:75], s90, v3
	s_nop 1
	v_cndmask_b32_e64 v4, 0, 32, s[74:75]
	v_ldexp_f32 v3, v3, v4
	v_log_f32_e32 v3, v3
	s_nop 0
	v_mul_f32_e32 v4, 0x3f317217, v3
	v_fma_f32 v4, v3, s6, -v4
	v_fmac_f32_e32 v4, 0x3377d1cf, v3
	s_mov_b32 s6, 0x7f800000
	v_fmac_f32_e32 v4, 0x3f317217, v3
	v_cmp_lt_f32_e64 s[76:77], |v3|, s6
	s_nop 1
	v_cndmask_b32_e64 v3, v3, v4, s[76:77]
	v_mov_b32_e32 v4, 0x41b17218
	v_cndmask_b32_e64 v4, 0, v4, s[74:75]
	v_sub_f32_e32 v3, v3, v4
	v_sub_f32_e32 v2, v2, v3
	s_branch .LBB0_169
.LBB0_178:
	s_waitcnt vmcnt(0)
	s_or_b64 exec, exec, s[78:79]
	v_readlane_b32 s12, v253, 1
	v_readlane_b32 s14, v255, 12
	v_readlane_b32 s13, v253, 2
	v_readlane_b32 s15, v255, 13
	s_or_b64 s[12:13], s[14:15], s[12:13]
	s_mov_b64 s[10:11], s[0:1]
	s_and_b64 vcc, exec, s[12:13]
	s_waitcnt lgkmcnt(0)
	s_barrier
	s_cbranch_vccnz .LBB0_189
	v_readlane_b32 s12, v255, 14
	v_readlane_b32 s13, v255, 15
	s_lshl_b32 s30, s12, 20
	s_mul_i32 s12, s12, 0xd04000
	s_mov_b32 s13, s31
	s_lshl_b64 s[14:15], s[30:31], 2
	v_readlane_b32 s6, v254, 36
	s_mov_b32 s18, s2
	s_branch .LBB0_181

.LBB0_385:
	s_or_b64 exec, exec, s[10:11]
	v_ashrrev_i32_e32 v1, 6, v35
	v_readlane_b32 s6, v253, 0
	s_waitcnt lgkmcnt(0)
	s_barrier
	v_add_u32_e32 v34, s6, v1
	s_movk_i32 s6, 0x4400
	v_cmp_gt_i32_e32 vcc, s6, v34
	s_and_saveexec_b64 s[10:11], vcc
	s_cbranch_execz .LBB0_392
	s_load_dwordx4 s[40:43], s[12:13], 0x50
	v_readlane_b32 s14, v255, 14
	v_and_b32_e32 v1, 3, v35
	s_lshl_b32 s6, s14, 6
	v_lshl_or_b32 v2, v1, 4, s6
	v_mov_b32_e32 v3, v0
	v_lshlrev_b64 v[18:19], 2, v[2:3]
	s_waitcnt lgkmcnt(0)
	v_lshl_add_u64 v[14:15], s[42:43], 0, v[18:19]
	v_lshl_add_u64 v[30:31], s[40:41], 0, v[18:19]
	global_load_dwordx4 v[2:5], v[14:15], off offset:48
	global_load_dwordx4 v[6:9], v[14:15], off offset:32
	global_load_dwordx4 v[10:13], v[14:15], off offset:16
	s_nop 0
	global_load_dwordx4 v[14:17], v[14:15], off
	s_nop 0
	global_load_dwordx4 v[18:21], v[30:31], off offset:48
	global_load_dwordx4 v[22:25], v[30:31], off offset:32
	global_load_dwordx4 v[26:29], v[30:31], off offset:16
	s_nop 0
	global_load_dwordx4 v[30:33], v[30:31], off
	s_load_dwordx2 s[12:13], s[12:13], 0xb0
	v_cmp_lt_i32_e64 s[40:41], v231, v225
	v_cmp_gt_u32_e32 vcc, 2, v1
	v_mov_b32_e32 v37, v0
	v_cndmask_b32_e64 v1, v223, v231, s[40:41]
	v_cmp_lt_i32_e64 s[40:41], v230, v225
	v_lshlrev_b32_e32 v1, 2, v1
	v_readlane_b32 s15, v255, 15
	v_cndmask_b32_e64 v36, v223, v230, s[40:41]
	v_lshlrev_b32_e32 v60, 2, v36
	v_and_b32_e32 v36, 1, v35
	v_lshlrev_b32_e32 v35, 5, v35
	v_cmp_eq_u32_e64 s[40:41], 0, v36
	v_and_b32_e32 v36, 0x7e0, v35
	s_waitcnt lgkmcnt(0)
	v_lshl_add_u64 v[38:39], s[12:13], 0, v[36:37]
	s_mov_b64 s[12:13], 0x14610000
	v_lshl_add_u64 v[36:37], v[38:39], 0, s[12:13]
	s_mov_b64 s[12:13], 0x16810000
	v_lshl_add_u64 v[38:39], v[38:39], 0, s[12:13]
	s_mov_b64 s[12:13], 0
	v_ashrrev_i32_e32 v35, 31, v34
	v_lshlrev_b64 v[40:41], 11, v[34:35]
	v_lshl_add_u64 v[96:97], v[36:37], 0, v[40:41]
	v_lshl_add_u64 v[98:99], v[38:39], 0, v[40:41]
	global_load_dwordx4 v[100:103], v[96:97], off offset:16
	global_load_dwordx4 v[104:107], v[96:97], off
	global_load_dwordx4 v[108:111], v[98:99], off offset:16
	global_load_dwordx4 v[112:115], v[98:99], off
	v_readlane_b32 s100, v254, 47
	s_mov_b32 s101, 0
	s_lshl_b32 s100, s100, 11
	s_waitcnt vmcnt(0)
	s_branch .LBB0_388

.LBB0_388:
	v_ashrrev_i32_e32 v35, 31, v34
	v_lshlrev_b64 v[40:41], 11, v[34:35]
	v_lshl_add_u64 v[42:43], v[36:37], 0, v[40:41]
	s_waitcnt vmcnt(6)
	v_mov_b32_e32 v44, v100
	v_mov_b32_e32 v45, v101
	v_mov_b32_e32 v46, v102
	v_mov_b32_e32 v47, v103
	v_mov_b32_e32 v48, v104
	v_mov_b32_e32 v49, v105
	v_mov_b32_e32 v50, v106
	v_mov_b32_e32 v51, v107
	v_lshl_add_u64 v[96:97], s[100:101], 0, v[42:43]
	global_load_dwordx4 v[100:103], v[96:97], off offset:16
	global_load_dwordx4 v[104:107], v[96:97], off
	s_mov_b32 s6, 0x78787879
	v_mul_hi_i32 v35, v34, s6
	s_movk_i32 s6, 0xff
	v_lshlrev_b32_e32 v58, 16, v44
	v_lshlrev_b32_e32 v54, 16, v48
	v_and_b32_e32 v55, 0xffff0000, v48
	v_lshlrev_b32_e32 v48, 16, v49
	v_and_b32_e32 v49, 0xffff0000, v49
	v_pk_mul_f32 v[64:65], v[54:55], v[54:55]
	v_pk_mul_f32 v[66:67], v[48:49], v[48:49]
	v_add_f32_e32 v61, v64, v65
	v_lshlrev_b32_e32 v56, 16, v50
	v_and_b32_e32 v57, 0xffff0000, v50
	v_add_f32_e32 v61, v66, v61
	v_pk_mul_f32 v[68:69], v[56:57], v[56:57]
	v_add_f32_e32 v61, v67, v61
	v_lshlrev_b32_e32 v50, 16, v51
	v_and_b32_e32 v51, 0xffff0000, v51
	v_add_f32_e32 v61, v68, v61
	v_pk_mul_f32 v[70:71], v[50:51], v[50:51]
	v_add_f32_e32 v61, v69, v61
	v_and_b32_e32 v59, 0xffff0000, v44
	v_add_f32_e32 v61, v70, v61
	v_pk_mul_f32 v[72:73], v[58:59], v[58:59]
	v_add_f32_e32 v61, v71, v61
	v_lshlrev_b32_e32 v44, 16, v45
	v_and_b32_e32 v45, 0xffff0000, v45
	v_add_f32_e32 v61, v72, v61
	v_pk_mul_f32 v[74:75], v[44:45], v[44:45]
	v_add_f32_e32 v61, v73, v61
	v_lshlrev_b32_e32 v62, 16, v46
	v_and_b32_e32 v63, 0xffff0000, v46
	v_add_f32_e32 v61, v74, v61
	v_pk_mul_f32 v[76:77], v[62:63], v[62:63]
	v_add_f32_e32 v61, v75, v61
	v_and_b32_e32 v52, 0xffff0000, v47
	v_lshlrev_b32_e32 v53, 16, v47
	v_add_f32_e32 v61, v76, v61
	v_pk_mul_f32 v[46:47], v[52:53], v[52:53]
	v_add_f32_e32 v61, v77, v61
	v_add_f32_e32 v47, v47, v61
	v_add_f32_e32 v46, v46, v47
	ds_bpermute_b32 v47, v1, v46
	v_lshrrev_b32_e32 v61, 31, v35
	v_ashrrev_i32_e32 v35, 11, v35
	v_add_u32_e32 v35, v35, v61
	v_mul_i32_i24_e32 v35, 0x1100, v35
	s_waitcnt lgkmcnt(0)
	v_add_f32_e32 v46, v46, v47
	ds_bpermute_b32 v47, v60, v46
	v_sub_u32_e32 v35, v34, v35
	v_add_u32_e32 v61, 0xffffff00, v35
	v_cmp_lt_i32_e64 s[42:43], s6, v35
	v_and_b32_e32 v35, 63, v35
	s_waitcnt lgkmcnt(0)
	v_add_f32_e32 v46, v46, v47
	v_fmamk_f32 v46, v46, 0x3c800000, v234
	v_mul_f32_e32 v47, 0x4b800000, v46
	v_cmp_gt_f32_e64 s[44:45], s90, v46
	s_nop 1
	v_cndmask_b32_e64 v46, v46, v47, s[44:45]
	v_rsq_f32_e32 v46, v46
	v_ashrrev_i32_e32 v47, 6, v61
	v_cndmask_b32_e32 v35, v35, v47, vcc
	v_lshlrev_b32_e32 v35, 4, v35
	v_mul_f32_e32 v47, 0x45800000, v46
	v_cndmask_b32_e64 v46, v46, v47, s[44:45]
	v_pk_mul_f32 v[54:55], v[46:47], v[54:55] op_sel_hi:[0,1]
	v_pk_mul_f32 v[48:49], v[46:47], v[48:49] op_sel_hi:[0,1]
	v_pk_mul_f32 v[64:65], v[46:47], v[56:57] op_sel_hi:[0,1]
	v_pk_mul_f32 v[50:51], v[46:47], v[50:51] op_sel_hi:[0,1]
	v_pk_mul_f32 v[66:67], v[46:47], v[58:59] op_sel_hi:[0,1]
	v_pk_mul_f32 v[44:45], v[46:47], v[44:45] op_sel_hi:[0,1]
	v_pk_mul_f32 v[62:63], v[46:47], v[62:63] op_sel_hi:[0,1]
	v_pk_mul_f32 v[68:69], v[46:47], v[52:53] op_sel_hi:[0,1]
	v_pk_mul_f32 v[58:59], v[30:31], v[54:55]
	v_pk_mul_f32 v[56:57], v[32:33], v[48:49]
	v_pk_mul_f32 v[54:55], v[26:27], v[64:65]
	v_pk_mul_f32 v[52:53], v[28:29], v[50:51]
	v_pk_mul_f32 v[50:51], v[22:23], v[66:67]
	v_pk_mul_f32 v[48:49], v[24:25], v[44:45]
	v_pk_mul_f32 v[46:47], v[18:19], v[62:63]
	v_pk_mul_f32 v[44:45], v[20:21], v[68:69] op_sel:[0,1] op_sel_hi:[1,0]
	v_lshl_add_u32 v35, v35, 2, 0
	s_and_saveexec_b64 s[14:15], s[42:43]
	s_cbranch_execz .LBB0_390
	ds_bpermute_b32 v82, v1, v58
	ds_bpermute_b32 v83, v1, v59
	ds_read_b128 v[62:65], v35
	ds_read_b128 v[66:69], v35 offset:16
	ds_read_b128 v[70:73], v35 offset:32
	ds_read_b128 v[74:77], v35 offset:48
	ds_read_b128 v[78:81], v35 offset:4096
	ds_bpermute_b32 v86, v1, v54
	ds_bpermute_b32 v87, v1, v55
	ds_bpermute_b32 v90, v1, v50
	ds_bpermute_b32 v91, v1, v51
	s_waitcnt lgkmcnt(4)
	v_pk_mul_f32 v[82:83], v[78:79], v[82:83]
	ds_bpermute_b32 v78, v1, v56
	ds_bpermute_b32 v79, v1, v57
	ds_bpermute_b32 v94, v1, v46
	ds_bpermute_b32 v95, v1, v47
	v_cndmask_b32_e64 v83, v83, -v83, s[40:41]
	v_cndmask_b32_e64 v82, v82, -v82, s[40:41]
	s_waitcnt lgkmcnt(2)
	v_pk_mul_f32 v[84:85], v[80:81], v[78:79]
	ds_read_b128 v[78:81], v35 offset:4112
	v_cndmask_b32_e64 v85, v85, -v85, s[40:41]
	v_cndmask_b32_e64 v84, v84, -v84, s[40:41]
	v_pk_fma_f32 v[56:57], v[56:57], v[64:65], v[84:85]
	v_pk_fma_f32 v[58:59], v[58:59], v[62:63], v[82:83]
	s_waitcnt lgkmcnt(0)
	v_pk_mul_f32 v[86:87], v[78:79], v[86:87]
	ds_bpermute_b32 v78, v1, v52
	ds_bpermute_b32 v79, v1, v53
	v_cndmask_b32_e64 v87, v87, -v87, s[40:41]
	v_cndmask_b32_e64 v86, v86, -v86, s[40:41]
	v_pk_fma_f32 v[54:55], v[54:55], v[66:67], v[86:87]
	s_waitcnt lgkmcnt(0)
	v_pk_mul_f32 v[88:89], v[80:81], v[78:79]
	ds_read_b128 v[78:81], v35 offset:4128
	v_cndmask_b32_e64 v88, v88, -v88, s[40:41]
	v_cndmask_b32_e64 v89, v89, -v89, s[40:41]
	v_pk_fma_f32 v[52:53], v[52:53], v[68:69], v[88:89]
	s_waitcnt lgkmcnt(0)
	v_pk_mul_f32 v[90:91], v[78:79], v[90:91]
	ds_bpermute_b32 v78, v1, v48
	ds_bpermute_b32 v79, v1, v49
	v_cndmask_b32_e64 v90, v90, -v90, s[40:41]
	v_cndmask_b32_e64 v91, v91, -v91, s[40:41]
	v_pk_fma_f32 v[50:51], v[50:51], v[70:71], v[90:91]
	s_waitcnt lgkmcnt(0)
	v_pk_mul_f32 v[92:93], v[80:81], v[78:79]
	ds_read_b128 v[78:81], v35 offset:4144
	v_cndmask_b32_e64 v92, v92, -v92, s[40:41]
	v_cndmask_b32_e64 v93, v93, -v93, s[40:41]
	v_pk_fma_f32 v[48:49], v[48:49], v[72:73], v[92:93]
	s_waitcnt lgkmcnt(0)
	v_pk_mul_f32 v[78:79], v[78:79], v[94:95]
	ds_bpermute_b32 v94, v1, v44
	ds_bpermute_b32 v95, v1, v45
	v_cndmask_b32_e64 v78, v78, -v78, s[40:41]
	v_cndmask_b32_e64 v79, v79, -v79, s[40:41]
	v_pk_fma_f32 v[46:47], v[46:47], v[74:75], v[78:79]
	s_waitcnt lgkmcnt(0)
	v_pk_mul_f32 v[80:81], v[80:81], v[94:95]
	s_nop 0
	v_cndmask_b32_e64 v80, v80, -v80, s[40:41]
	v_cndmask_b32_e64 v81, v81, -v81, s[40:41]
	v_pk_fma_f32 v[44:45], v[44:45], v[76:77], v[80:81]
.LBB0_390:
	s_or_b64 exec, exec, s[14:15]
	v_mul_f32_e32 v50, 0x3e38aa3b, v50
	v_mul_f32_e32 v47, 0x3e38aa3b, v47
	v_mul_f32_e32 v58, 0x3e38aa3b, v58
	v_mul_f32_e32 v59, 0x3e38aa3b, v59
	v_mul_f32_e32 v56, 0x3e38aa3b, v56
	v_mul_f32_e32 v57, 0x3e38aa3b, v57
	v_mul_f32_e32 v54, 0x3e38aa3b, v54
	v_mul_f32_e32 v55, 0x3e38aa3b, v55
	v_mul_f32_e32 v52, 0x3e38aa3b, v52
	v_mul_f32_e32 v53, 0x3e38aa3b, v53
	v_mul_f32_e32 v51, 0x3e38aa3b, v51
	v_mul_f32_e32 v61, 0x3e38aa3b, v48
	v_mul_f32_e32 v49, 0x3e38aa3b, v49
	v_mul_f32_e32 v62, 0x3e38aa3b, v46
	v_mul_f32_e32 v63, 0x3e38aa3b, v44
	v_mul_f32_e32 v64, 0x3e38aa3b, v45
	s_nop 1
	v_cvt_pk_bf16_f32 v44, v58, v59
	s_nop 1
	v_cvt_pk_bf16_f32 v48, v50, v51
	s_nop 1
	v_cvt_pk_bf16_f32 v45, v56, v57
	s_nop 1
	v_cvt_pk_bf16_f32 v46, v54, v55
	s_nop 1
	v_cvt_pk_bf16_f32 v50, v62, v47
	s_nop 1
	v_cvt_pk_bf16_f32 v47, v52, v53
	s_nop 1
	v_cvt_pk_bf16_f32 v49, v61, v49
	s_nop 1
	v_cvt_pk_bf16_f32 v51, v63, v64
	global_store_dwordx4 v[42:43], v[44:47], off
	global_store_dwordx4 v[42:43], v[48:51], off offset:16
	v_lshl_add_u64 v[40:41], v[38:39], 0, v[40:41]
	s_waitcnt vmcnt(6)
	s_nop 1
	v_mov_b32_e32 v42, v108
	v_mov_b32_e32 v43, v109
	v_mov_b32_e32 v44, v110
	v_mov_b32_e32 v45, v111
	v_mov_b32_e32 v46, v112
	v_mov_b32_e32 v47, v113
	v_mov_b32_e32 v48, v114
	v_mov_b32_e32 v49, v115
	v_lshl_add_u64 v[96:97], s[100:101], 0, v[40:41]
	global_load_dwordx4 v[108:111], v[96:97], off offset:16
	global_load_dwordx4 v[112:115], v[96:97], off
	v_lshlrev_b32_e32 v68, 16, v42
	v_lshlrev_b32_e32 v52, 16, v46
	v_and_b32_e32 v53, 0xffff0000, v46
	v_pk_mul_f32 v[54:55], v[52:53], v[52:53]
	v_lshlrev_b32_e32 v46, 16, v47
	v_and_b32_e32 v47, 0xffff0000, v47
	v_pk_mul_f32 v[58:59], v[46:47], v[46:47]
	v_add_f32_e32 v54, v54, v55
	v_lshlrev_b32_e32 v62, 16, v48
	v_and_b32_e32 v63, 0xffff0000, v48
	v_add_f32_e32 v54, v58, v54
	v_pk_mul_f32 v[64:65], v[62:63], v[62:63]
	v_add_f32_e32 v54, v59, v54
	v_lshlrev_b32_e32 v48, 16, v49
	v_and_b32_e32 v49, 0xffff0000, v49
	v_add_f32_e32 v54, v64, v54
	v_pk_mul_f32 v[66:67], v[48:49], v[48:49]
	v_add_f32_e32 v54, v65, v54
	v_and_b32_e32 v69, 0xffff0000, v42
	v_add_f32_e32 v54, v66, v54
	v_pk_mul_f32 v[70:71], v[68:69], v[68:69]
	v_add_f32_e32 v54, v67, v54
	v_lshlrev_b32_e32 v72, 16, v43
	v_and_b32_e32 v73, 0xffff0000, v43
	v_add_f32_e32 v54, v70, v54
	v_pk_mul_f32 v[42:43], v[72:73], v[72:73]
	v_add_f32_e32 v54, v71, v54
	v_lshlrev_b32_e32 v74, 16, v44
	v_and_b32_e32 v75, 0xffff0000, v44
	v_add_f32_e32 v42, v42, v54
	v_and_b32_e32 v56, 0xffff0000, v45
	v_lshlrev_b32_e32 v57, 16, v45
	v_pk_mul_f32 v[44:45], v[74:75], v[74:75]
	v_add_f32_e32 v42, v43, v42
	v_add_f32_e32 v42, v44, v42
	v_pk_mul_f32 v[50:51], v[56:57], v[56:57]
	v_add_f32_e32 v42, v45, v42
	v_add_f32_e32 v42, v51, v42
	v_add_f32_e32 v42, v50, v42
	ds_bpermute_b32 v43, v1, v42
	s_waitcnt lgkmcnt(0)
	v_add_f32_e32 v42, v42, v43
	ds_bpermute_b32 v43, v60, v42
	s_waitcnt lgkmcnt(0)
	v_add_f32_e32 v42, v42, v43
	v_fmamk_f32 v42, v42, 0x3c800000, v234
	v_cmp_gt_f32_e64 s[44:45], s90, v42
	v_mul_f32_e32 v43, 0x4b800000, v42
	s_nop 0
	v_cndmask_b32_e64 v42, v42, v43, s[44:45]
	v_rsq_f32_e32 v42, v42
	s_nop 0
	v_mul_f32_e32 v43, 0x45800000, v42
	v_cndmask_b32_e64 v58, v42, v43, s[44:45]
	v_pk_mul_f32 v[42:43], v[58:59], v[52:53] op_sel_hi:[0,1]
	v_pk_mul_f32 v[44:45], v[58:59], v[46:47] op_sel_hi:[0,1]
	v_pk_mul_f32 v[46:47], v[58:59], v[62:63] op_sel_hi:[0,1]
	v_pk_mul_f32 v[48:49], v[58:59], v[48:49] op_sel_hi:[0,1]
	v_pk_mul_f32 v[50:51], v[58:59], v[68:69] op_sel_hi:[0,1]
	v_pk_mul_f32 v[52:53], v[58:59], v[72:73] op_sel_hi:[0,1]
	v_pk_mul_f32 v[54:55], v[58:59], v[74:75] op_sel_hi:[0,1]
	v_pk_mul_f32 v[56:57], v[58:59], v[56:57] op_sel_hi:[0,1]
	v_pk_mul_f32 v[42:43], v[14:15], v[42:43]
	v_pk_mul_f32 v[44:45], v[16:17], v[44:45]
	v_pk_mul_f32 v[46:47], v[10:11], v[46:47]
	v_pk_mul_f32 v[48:49], v[12:13], v[48:49]
	v_pk_mul_f32 v[50:51], v[6:7], v[50:51]
	v_pk_mul_f32 v[52:53], v[8:9], v[52:53]
	v_pk_mul_f32 v[54:55], v[2:3], v[54:55]
	v_pk_mul_f32 v[56:57], v[4:5], v[56:57] op_sel:[0,1] op_sel_hi:[1,0]
	s_and_saveexec_b64 s[14:15], s[42:43]
	s_cbranch_execz .LBB0_387
	ds_bpermute_b32 v58, v1, v42
	ds_bpermute_b32 v59, v1, v43
	ds_read_b128 v[62:65], v35
	ds_read_b128 v[66:69], v35 offset:16
	ds_read_b128 v[70:73], v35 offset:32
	ds_read_b128 v[74:77], v35 offset:48
	ds_read_b128 v[78:81], v35 offset:4096
	ds_bpermute_b32 v84, v1, v46
	ds_bpermute_b32 v85, v1, v47
	ds_bpermute_b32 v88, v1, v50
	ds_bpermute_b32 v89, v1, v51
	s_waitcnt lgkmcnt(4)
	v_pk_mul_f32 v[58:59], v[78:79], v[58:59]
	ds_bpermute_b32 v78, v1, v44
	ds_bpermute_b32 v79, v1, v45
	ds_bpermute_b32 v92, v1, v54
	ds_bpermute_b32 v93, v1, v55
	v_cndmask_b32_e64 v59, v59, -v59, s[40:41]
	v_cndmask_b32_e64 v58, v58, -v58, s[40:41]
	s_waitcnt lgkmcnt(2)
	v_pk_mul_f32 v[82:83], v[80:81], v[78:79]
	ds_read_b128 v[78:81], v35 offset:4112
	v_cndmask_b32_e64 v83, v83, -v83, s[40:41]
	v_cndmask_b32_e64 v82, v82, -v82, s[40:41]
	v_pk_fma_f32 v[44:45], v[44:45], v[64:65], v[82:83]
	v_pk_fma_f32 v[42:43], v[42:43], v[62:63], v[58:59]
	s_waitcnt lgkmcnt(0)
	v_pk_mul_f32 v[84:85], v[78:79], v[84:85]
	ds_bpermute_b32 v78, v1, v48
	ds_bpermute_b32 v79, v1, v49
	v_cndmask_b32_e64 v85, v85, -v85, s[40:41]
	v_cndmask_b32_e64 v84, v84, -v84, s[40:41]
	v_pk_fma_f32 v[46:47], v[46:47], v[66:67], v[84:85]
	s_waitcnt lgkmcnt(0)
	v_pk_mul_f32 v[86:87], v[80:81], v[78:79]
	ds_read_b128 v[78:81], v35 offset:4128
	v_cndmask_b32_e64 v86, v86, -v86, s[40:41]
	v_cndmask_b32_e64 v87, v87, -v87, s[40:41]
	v_pk_fma_f32 v[48:49], v[48:49], v[68:69], v[86:87]
	s_waitcnt lgkmcnt(0)
	v_pk_mul_f32 v[88:89], v[78:79], v[88:89]
	ds_bpermute_b32 v78, v1, v52
	ds_bpermute_b32 v79, v1, v53
	v_cndmask_b32_e64 v88, v88, -v88, s[40:41]
	v_cndmask_b32_e64 v89, v89, -v89, s[40:41]
	v_pk_fma_f32 v[50:51], v[50:51], v[70:71], v[88:89]
	s_waitcnt lgkmcnt(0)
	v_pk_mul_f32 v[90:91], v[80:81], v[78:79]
	ds_read_b128 v[78:81], v35 offset:4144
	v_cndmask_b32_e64 v90, v90, -v90, s[40:41]
	v_cndmask_b32_e64 v91, v91, -v91, s[40:41]
	v_pk_fma_f32 v[52:53], v[52:53], v[72:73], v[90:91]
	s_waitcnt lgkmcnt(0)
	v_pk_mul_f32 v[78:79], v[78:79], v[92:93]
	ds_bpermute_b32 v92, v1, v56
	ds_bpermute_b32 v93, v1, v57
	v_cndmask_b32_e64 v78, v78, -v78, s[40:41]
	v_cndmask_b32_e64 v79, v79, -v79, s[40:41]
	v_pk_fma_f32 v[54:55], v[54:55], v[74:75], v[78:79]
	s_waitcnt lgkmcnt(0)
	v_pk_mul_f32 v[80:81], v[80:81], v[92:93]
	s_nop 0
	v_cndmask_b32_e64 v80, v80, -v80, s[40:41]
	v_cndmask_b32_e64 v81, v81, -v81, s[40:41]
	v_pk_fma_f32 v[56:57], v[56:57], v[76:77], v[80:81]
	s_branch .LBB0_387
.LBB0_392:
	s_or_b64 exec, exec, s[10:11]
	s_waitcnt vmcnt(0)
	v_readlane_b32 s12, v253, 61
	s_mov_b64 s[10:11], s[0:1]
	v_mov_b32_e32 v2, v232
	v_readlane_b32 s13, v253, 62
	s_barrier
	s_andn2_b64 vcc, exec, s[12:13]
	v_readfirstlane_b32 s18, v2
	s_cbranch_vccnz .LBB0_402
	v_lshlrev_b32_e32 v1, 4, v2
	v_add_u32_e32 v3, 0x2000, v1
	v_ashrrev_i32_e32 v4, 31, v3
	v_lshrrev_b32_e32 v4, 22, v4
	v_add_u32_e32 v4, v3, v4
	v_ashrrev_i32_e32 v4, 10, v4
	v_mul_i32_i24_e32 v5, 0x400, v4
	v_sub_u32_e32 v3, v3, v5
	v_lshrrev_b32_e32 v5, 4, v3
	v_bitop3_b32 v3, v5, v3, 32 bitop3:0x6c
	v_ashrrev_i32_e32 v5, 31, v3
	v_lshrrev_b32_e32 v5, 26, v5
	v_add_u32_e32 v5, v3, v5
	v_lshlrev_b32_e32 v7, 3, v4
	v_ashrrev_i32_e32 v6, 6, v5
	v_and_b32_e32 v7, -16, v7
	v_add_u32_e32 v7, v6, v7
	v_lshrrev_b32_e32 v8, 2, v7
	v_and_b32_e32 v8, 4, v8
	v_and_b32_e32 v5, 0xc0, v5
	v_and_or_b32 v6, v6, 3, v8
	v_and_b32_e32 v8, 0xffffe0, v7
	v_lshlrev_b32_e32 v9, 1, v7
	v_sub_u32_e32 v3, v3, v5
	v_and_or_b32 v8, v9, 24, v8
	v_lshlrev_b32_e32 v4, 5, v4
	v_ashrrev_i16_sdwa v3, v233, sext(v3) dst_sel:DWORD dst_unused:UNUSED_PAD src0_sel:DWORD src1_sel:BYTE_0
	v_lshrrev_b32_e32 v8, 3, v8
	v_and_b32_e32 v4, 32, v4
	v_bfe_i32 v3, v3, 0, 16
	v_lshl_add_u32 v6, v6, 6, v8
	v_add_lshl_u32 v3, v4, v3, 1
	v_lshl_add_u32 v78, v6, 11, v3
	v_lshl_add_u32 v80, v7, 9, v3
	v_bfe_i32 v3, v2, 27, 1
	v_lshrrev_b32_e32 v3, 22, v3
	s_load_dwordx2 s[10:11], s[10:11], 0xb0
	v_add_u32_e32 v3, v1, v3
	v_and_b32_e32 v3, 0xfffffc00, v3
	v_sub_u32_e32 v1, v1, v3
	v_ashrrev_i32_e32 v4, 31, v2
	v_lshrrev_b32_e32 v3, 4, v1
	v_lshrrev_b32_e32 v4, 26, v4
	v_bitop3_b32 v3, v3, v1, 32 bitop3:0x6c
	v_ashrrev_i32_e32 v1, 31, v1
	v_add_u32_e32 v4, v2, v4
	s_waitcnt lgkmcnt(0)
	s_add_u32 s34, s10, 0x4c000
	v_lshrrev_b32_e32 v1, 26, v1
	v_ashrrev_i32_e32 v4, 6, v4
	s_addc_u32 s35, s11, 0
	v_add_u32_e32 v1, v3, v1
	v_lshlrev_b32_e32 v5, 3, v4
	s_add_u32 s46, s10, 0x1ac10000
	v_ashrrev_i32_e32 v1, 6, v1
	v_and_b32_e32 v5, -16, v5
	s_addc_u32 s47, s11, 0
	s_ashr_i32 s12, s18, 6
	v_add_u32_e32 v5, v1, v5
	s_ashr_i32 s6, s18, 8
	s_lshl_b32 s48, s12, 10
	v_lshrrev_b32_e32 v6, 2, v5
	v_readlane_b32 s13, v254, 2
	v_and_b32_e32 v6, 4, v6
	s_add_u32 s44, s34, s13
	v_and_or_b32 v6, v1, 3, v6
	v_mul_i32_i24_e32 v1, 64, v1
	s_addc_u32 s45, s35, 0
	v_readlane_b32 s13, v254, 4
	v_and_b32_e32 v7, 0xffffe0, v5
	v_lshlrev_b32_e32 v8, 1, v5
	v_sub_u32_e32 v1, v3, v1
	s_add_u32 s13, s46, s13
	v_and_or_b32 v7, v8, 24, v7
	v_lshlrev_b32_e32 v4, 5, v4
	v_ashrrev_i16_sdwa v1, v233, sext(v1) dst_sel:DWORD dst_unused:UNUSED_PAD src0_sel:DWORD src1_sel:BYTE_0
	s_addc_u32 s15, s47, 0
	v_readlane_b32 s26, v254, 5
	v_lshrrev_b32_e32 v7, 3, v7
	v_and_b32_e32 v4, 32, v4
	v_bfe_i32 v1, v1, 0, 16
	v_readlane_b32 s27, v254, 6
	s_add_u32 s14, s13, s26
	v_lshl_add_u32 v6, v6, 6, v7
	v_add_lshl_u32 v1, v4, v1, 1
	s_addc_u32 s15, s15, s27
	s_add_i32 s49, s48, 0
	v_lshl_add_u32 v82, v6, 11, v1
	s_add_i32 m0, s49, 0x10000
	v_lshl_add_u32 v84, v5, 9, v1
	global_load_lds_dwordx4 v82, s[14:15]
	s_add_i32 m0, s49, 0x12000
	s_add_i32 s50, s49, 0x2000
	global_load_lds_dwordx4 v78, s[14:15]
	s_mov_b32 m0, s49
	s_add_u32 s26, s14, 0x8000
	global_load_lds_dwordx4 v84, s[44:45]
	s_mov_b32 m0, s50
	s_addc_u32 s27, s15, 0
	global_load_lds_dwordx4 v80, s[44:45]
	s_add_i32 m0, s49, 0x14000
	v_not_b32_e32 v252, 31
	global_load_lds_dwordx4 v82, s[26:27]
	s_add_i32 m0, s49, 0x16000
	v_mov_b32_e32 v222, 1
	global_load_lds_dwordx4 v78, s[26:27]
	s_add_u32 s26, s44, 0x10000
	s_addc_u32 s27, s45, 0
	s_add_i32 s51, s49, 0x4000
	s_mov_b32 m0, s51
	s_add_i32 s52, s49, 0x6000
	global_load_lds_dwordx4 v84, s[26:27]
	s_mov_b32 m0, s52
	s_cmp_lg_u32 s6, 1
	global_load_lds_dwordx4 v80, s[26:27]
	s_cbranch_scc1 .LBB0_395
	s_barrier

.LBB0_722:
	global_load_dword v1, v0, s[12:13] offset:2304 sc1
	s_mov_b64 s[14:15], -1
	s_waitcnt vmcnt(0)
	v_cmp_lt_u32_e32 vcc, 63, v1
	s_cbranch_vccnz .LBB0_721
	s_sleep 2
	global_load_dword v1, v0, s[12:13] offset:2304 sc1
	s_waitcnt vmcnt(0)
	v_cmp_gt_u32_e32 vcc, 64, v1
	s_cbranch_vccz .LBB0_721
	s_sleep 2
	global_load_dword v1, v0, s[12:13] offset:2304 sc1
	s_waitcnt vmcnt(0)
	v_cmp_gt_u32_e32 vcc, 64, v1
	s_cbranch_vccz .LBB0_721
	s_sleep 2
	global_load_dword v1, v0, s[12:13] offset:2304 sc1
	s_waitcnt vmcnt(0)
	v_cmp_gt_u32_e32 vcc, 64, v1
	s_cbranch_vccz .LBB0_721
	s_sleep 2
	global_load_dword v1, v0, s[12:13] offset:2304 sc1
	s_waitcnt vmcnt(0)
	v_cmp_gt_u32_e32 vcc, 64, v1
	s_cbranch_vccz .LBB0_721
	s_add_i32 s6, s6, -5
	s_cmp_eq_u32 s6, 0
	s_cselect_b64 s[14:15], -1, 0
	s_sleep 2
	s_branch .LBB0_721

.Lattn_nf_loop:
	s_and_b32 s10, s15, 1
	s_mul_i32 s6, s10, 0x8800
	v_add_u32_e32 v136, s6, v137
	v_add_u32_e32 v170, s6, v183
	s_sub_u32 s10, 0x8800, s6
	ds_read_b128 v[98:101], v136 offset:0
	ds_read_b128 v[102:105], v136 offset:64
	ds_read_b128 v[106:109], v136 offset:4352
	ds_read_b128 v[110:113], v136 offset:4416
	v_add_u32_e32 v171, s10, v126
	v_add_u32_e32 v173, s10, v127
	global_load_dwordx4 v[82:85], v124, s[64:65]
	global_load_dwordx4 v[86:89], v124, s[66:67]
	global_load_dwordx4 v[90:93], v124, s[68:69]
	global_load_dwordx4 v[94:97], v124, s[70:71]
	v_add_u32_e32 v124, s36, v124
	s_waitcnt lgkmcnt(3)
	v_mfma_f32_16x16x32_bf16 v[138:141], v[98:101], v[10:13], 0
	v_mfma_f32_16x16x32_bf16 v[142:145], v[98:101], v[14:17], 0
	s_waitcnt lgkmcnt(2)
	v_mfma_f32_16x16x32_bf16 v[138:141], v[102:105], v[2:5], v[138:141]
	v_mfma_f32_16x16x32_bf16 v[142:145], v[102:105], v[6:9], v[142:145]
	ds_read_b128 v[98:101], v136 offset:8704
	ds_read_b128 v[102:105], v136 offset:8768
	s_waitcnt lgkmcnt(3)
	v_mfma_f32_16x16x32_bf16 v[146:149], v[106:109], v[10:13], 0
	v_mfma_f32_16x16x32_bf16 v[150:153], v[106:109], v[14:17], 0
	s_waitcnt lgkmcnt(2)
	v_mfma_f32_16x16x32_bf16 v[146:149], v[110:113], v[2:5], v[146:149]
	v_mfma_f32_16x16x32_bf16 v[150:153], v[110:113], v[6:9], v[150:153]
	ds_read_b128 v[106:109], v136 offset:13056
	ds_read_b128 v[110:113], v136 offset:13120
	v_exp_f32_e32 v138, v138
	v_exp_f32_e32 v139, v139
	v_exp_f32_e32 v140, v140
	v_exp_f32_e32 v141, v141
	v_exp_f32_e32 v142, v142
	v_exp_f32_e32 v143, v143
	v_exp_f32_e32 v144, v144
	v_exp_f32_e32 v145, v145
	v_add_f32_e32 v123, v138, v123
	v_add_f32_e32 v122, v142, v122
	v_add_f32_e32 v123, v139, v123
	v_add_f32_e32 v122, v143, v122
	v_add_f32_e32 v123, v140, v123
	v_add_f32_e32 v122, v144, v122
	v_add_f32_e32 v123, v141, v123
	v_add_f32_e32 v122, v145, v122
	s_waitcnt lgkmcnt(3)
	v_mfma_f32_16x16x32_bf16 v[154:157], v[98:101], v[10:13], 0
	v_exp_f32_e32 v146, v146
	v_exp_f32_e32 v147, v147
	v_mfma_f32_16x16x32_bf16 v[158:161], v[98:101], v[14:17], 0
	v_exp_f32_e32 v148, v148
	v_exp_f32_e32 v149, v149
	s_waitcnt lgkmcnt(2)
	v_mfma_f32_16x16x32_bf16 v[154:157], v[102:105], v[2:5], v[154:157]
	v_exp_f32_e32 v150, v150
	v_exp_f32_e32 v151, v151
	v_mfma_f32_16x16x32_bf16 v[158:161], v[102:105], v[6:9], v[158:161]
	v_exp_f32_e32 v152, v152
	v_exp_f32_e32 v153, v153
	v_cvt_pk_bf16_f32 v114, v138, v139
	v_cvt_pk_bf16_f32 v115, v140, v141
	v_cvt_pk_bf16_f32 v118, v142, v143
	v_cvt_pk_bf16_f32 v119, v144, v145
	ds_read_b128 v[138:141], v170 offset:0
	ds_read_b128 v[142:145], v170 offset:4352
	s_waitcnt lgkmcnt(3)
	v_mfma_f32_16x16x32_bf16 v[162:165], v[106:109], v[10:13], 0
	v_add_f32_e32 v123, v146, v123
	v_add_f32_e32 v122, v150, v122
	v_add_f32_e32 v123, v147, v123
	v_mfma_f32_16x16x32_bf16 v[166:169], v[106:109], v[14:17], 0
	v_add_f32_e32 v122, v151, v122
	v_add_f32_e32 v123, v148, v123
	v_add_f32_e32 v122, v152, v122
	s_waitcnt lgkmcnt(2)
	v_mfma_f32_16x16x32_bf16 v[162:165], v[110:113], v[2:5], v[162:165]
	v_add_f32_e32 v123, v149, v123
	v_add_f32_e32 v122, v153, v122
	v_cvt_pk_bf16_f32 v116, v146, v147
	v_cvt_pk_bf16_f32 v117, v148, v149
	v_mfma_f32_16x16x32_bf16 v[166:169], v[110:113], v[6:9], v[166:169]
	v_cvt_pk_bf16_f32 v120, v150, v151
	v_cvt_pk_bf16_f32 v121, v152, v153
	ds_read_b128 v[146:149], v170 offset:8704
	ds_read_b128 v[150:153], v170 offset:13056
	ds_read_b128 v[98:101], v170 offset:17408
	ds_read_b128 v[102:105], v170 offset:21760
	ds_read_b128 v[106:109], v170 offset:26112
	ds_read_b128 v[110:113], v170 offset:30464
	v_exp_f32_e32 v154, v154
	v_exp_f32_e32 v155, v155
	v_exp_f32_e32 v156, v156
	v_exp_f32_e32 v157, v157
	v_exp_f32_e32 v158, v158
	v_exp_f32_e32 v159, v159
	v_exp_f32_e32 v160, v160
	v_exp_f32_e32 v161, v161
	s_waitcnt lgkmcnt(7)
	v_mfma_f32_16x16x32_bf16 v[78:81], v[138:141], v[114:117], v[78:81]
	v_mfma_f32_16x16x32_bf16 v[74:77], v[138:141], v[118:121], v[74:77]
	v_exp_f32_e32 v162, v162
	v_exp_f32_e32 v163, v163
	v_exp_f32_e32 v164, v164
	v_exp_f32_e32 v165, v165
	s_waitcnt lgkmcnt(6)
	v_mfma_f32_16x16x32_bf16 v[70:73], v[142:145], v[114:117], v[70:73]
	v_mfma_f32_16x16x32_bf16 v[62:65], v[142:145], v[118:121], v[62:65]
	v_exp_f32_e32 v166, v166
	v_exp_f32_e32 v167, v167
	v_exp_f32_e32 v168, v168
	v_exp_f32_e32 v169, v169
	s_waitcnt lgkmcnt(5)
	v_mfma_f32_16x16x32_bf16 v[66:69], v[146:149], v[114:117], v[66:69]
	v_mfma_f32_16x16x32_bf16 v[46:49], v[146:149], v[118:121], v[46:49]
	v_add_f32_e32 v123, v154, v123
	v_add_f32_e32 v122, v158, v122
	v_add_f32_e32 v123, v155, v123
	v_add_f32_e32 v122, v159, v122
	v_add_f32_e32 v123, v156, v123
	v_add_f32_e32 v122, v160, v122
	v_add_f32_e32 v123, v157, v123
	v_add_f32_e32 v122, v161, v122
	s_waitcnt lgkmcnt(4)
	v_mfma_f32_16x16x32_bf16 v[58:61], v[150:153], v[114:117], v[58:61]
	v_mfma_f32_16x16x32_bf16 v[38:41], v[150:153], v[118:121], v[38:41]
	ds_read_b128 v[138:141], v170 offset:17472
	ds_read_b128 v[142:145], v170 offset:21824
	ds_read_b128 v[146:149], v170 offset:26176
	ds_read_b128 v[150:153], v170 offset:30528
	v_cvt_pk_bf16_f32 v184, v154, v155
	v_cvt_pk_bf16_f32 v185, v156, v157
	v_cvt_pk_bf16_f32 v128, v158, v159
	v_cvt_pk_bf16_f32 v129, v160, v161
	s_waitcnt lgkmcnt(7)
	v_mfma_f32_16x16x32_bf16 v[54:57], v[98:101], v[114:117], v[54:57]
	v_mfma_f32_16x16x32_bf16 v[30:33], v[98:101], v[118:121], v[30:33]
	v_add_f32_e32 v123, v162, v123
	v_add_f32_e32 v122, v166, v122
	v_add_f32_e32 v123, v163, v123
	v_add_f32_e32 v122, v167, v122
	v_add_f32_e32 v123, v164, v123
	v_add_f32_e32 v122, v168, v122
	v_add_f32_e32 v123, v165, v123
	v_add_f32_e32 v122, v169, v122
	s_waitcnt lgkmcnt(6)
	v_mfma_f32_16x16x32_bf16 v[50:53], v[102:105], v[114:117], v[50:53]
	v_mfma_f32_16x16x32_bf16 v[26:29], v[102:105], v[118:121], v[26:29]
	v_cvt_pk_bf16_f32 v186, v162, v163
	v_cvt_pk_bf16_f32 v187, v164, v165
	v_cvt_pk_bf16_f32 v130, v166, v167
	v_cvt_pk_bf16_f32 v131, v168, v169
	ds_read_b128 v[154:157], v170 offset:64
	ds_read_b128 v[158:161], v170 offset:4416
	ds_read_b128 v[162:165], v170 offset:8768
	ds_read_b128 v[166:169], v170 offset:13120
	s_waitcnt lgkmcnt(9)
	v_mfma_f32_16x16x32_bf16 v[42:45], v[106:109], v[114:117], v[42:45]
	v_mfma_f32_16x16x32_bf16 v[22:25], v[106:109], v[118:121], v[22:25]
	s_waitcnt lgkmcnt(8)
	v_mfma_f32_16x16x32_bf16 v[34:37], v[110:113], v[114:117], v[34:37]
	v_mfma_f32_16x16x32_bf16 v[18:21], v[110:113], v[118:121], v[18:21]
	ds_read_b128 v[98:101], v136 offset:17408
	ds_read_b128 v[102:105], v136 offset:17472
	ds_read_b128 v[106:109], v136 offset:21760
	ds_read_b128 v[110:113], v136 offset:21824
	s_waitcnt lgkmcnt(7)
	v_mfma_f32_16x16x32_bf16 v[78:81], v[154:157], v[184:187], v[78:81]
	v_mfma_f32_16x16x32_bf16 v[74:77], v[154:157], v[128:131], v[74:77]
	s_waitcnt lgkmcnt(6)
	v_mfma_f32_16x16x32_bf16 v[70:73], v[158:161], v[184:187], v[70:73]
	v_mfma_f32_16x16x32_bf16 v[62:65], v[158:161], v[128:131], v[62:65]
	s_waitcnt vmcnt(3)
	ds_write_b128 v171, v[82:85] offset:0
	s_waitcnt vmcnt(2)
	ds_write_b128 v171, v[86:89] offset:8704
	s_waitcnt vmcnt(1)
	ds_write_b128 v171, v[90:93] offset:17408
	s_waitcnt vmcnt(0)
	ds_write_b128 v171, v[94:97] offset:26112
	s_waitcnt lgkmcnt(9)
	v_mfma_f32_16x16x32_bf16 v[66:69], v[162:165], v[184:187], v[66:69]
	v_mfma_f32_16x16x32_bf16 v[46:49], v[162:165], v[128:131], v[46:49]
	s_waitcnt lgkmcnt(8)
	v_mfma_f32_16x16x32_bf16 v[58:61], v[166:169], v[184:187], v[58:61]
	v_mfma_f32_16x16x32_bf16 v[38:41], v[166:169], v[128:131], v[38:41]
	global_load_dwordx4 v[82:85], v125, s[72:73]
	global_load_dwordx4 v[86:89], v125, s[74:75]
	global_load_dwordx4 v[90:93], v125, s[76:77]
	global_load_dwordx4 v[94:97], v125, s[78:79]
	v_add_u32_e32 v125, s38, v125
	v_mfma_f32_16x16x32_bf16 v[54:57], v[138:141], v[184:187], v[54:57]
	v_mfma_f32_16x16x32_bf16 v[30:33], v[138:141], v[128:131], v[30:33]
	v_mfma_f32_16x16x32_bf16 v[50:53], v[142:145], v[184:187], v[50:53]
	v_mfma_f32_16x16x32_bf16 v[26:29], v[142:145], v[128:131], v[26:29]
	v_mfma_f32_16x16x32_bf16 v[42:45], v[146:149], v[184:187], v[42:45]
	v_mfma_f32_16x16x32_bf16 v[22:25], v[146:149], v[128:131], v[22:25]
	v_mfma_f32_16x16x32_bf16 v[34:37], v[150:153], v[184:187], v[34:37]
	v_mfma_f32_16x16x32_bf16 v[18:21], v[150:153], v[128:131], v[18:21]
	s_waitcnt lgkmcnt(7)
	v_mfma_f32_16x16x32_bf16 v[138:141], v[98:101], v[10:13], 0
	v_mfma_f32_16x16x32_bf16 v[142:145], v[98:101], v[14:17], 0
	s_waitcnt lgkmcnt(6)
	v_mfma_f32_16x16x32_bf16 v[138:141], v[102:105], v[2:5], v[138:141]
	v_mfma_f32_16x16x32_bf16 v[142:145], v[102:105], v[6:9], v[142:145]
	ds_read_b128 v[98:101], v136 offset:26112
	ds_read_b128 v[102:105], v136 offset:26176
	s_waitcnt lgkmcnt(7)
	v_mfma_f32_16x16x32_bf16 v[146:149], v[106:109], v[10:13], 0
	v_mfma_f32_16x16x32_bf16 v[150:153], v[106:109], v[14:17], 0
	s_waitcnt lgkmcnt(6)
	v_mfma_f32_16x16x32_bf16 v[146:149], v[110:113], v[2:5], v[146:149]
	v_mfma_f32_16x16x32_bf16 v[150:153], v[110:113], v[6:9], v[150:153]
	ds_read_b128 v[106:109], v136 offset:30464
	ds_read_b128 v[110:113], v136 offset:30528
	v_exp_f32_e32 v138, v138
	v_exp_f32_e32 v139, v139
	v_exp_f32_e32 v140, v140
	v_exp_f32_e32 v141, v141
	v_exp_f32_e32 v142, v142
	v_exp_f32_e32 v143, v143
	v_exp_f32_e32 v144, v144
	v_exp_f32_e32 v145, v145
	v_add_f32_e32 v123, v138, v123
	v_add_f32_e32 v122, v142, v122
	v_add_f32_e32 v123, v139, v123
	v_add_f32_e32 v122, v143, v122
	v_add_f32_e32 v123, v140, v123
	v_add_f32_e32 v122, v144, v122
	v_add_f32_e32 v123, v141, v123
	v_add_f32_e32 v122, v145, v122
	s_waitcnt lgkmcnt(3)
	v_mfma_f32_16x16x32_bf16 v[154:157], v[98:101], v[10:13], 0
	v_exp_f32_e32 v146, v146
	v_exp_f32_e32 v147, v147
	v_mfma_f32_16x16x32_bf16 v[158:161], v[98:101], v[14:17], 0
	v_exp_f32_e32 v148, v148
	v_exp_f32_e32 v149, v149
	s_waitcnt lgkmcnt(2)
	v_mfma_f32_16x16x32_bf16 v[154:157], v[102:105], v[2:5], v[154:157]
	v_exp_f32_e32 v150, v150
	v_exp_f32_e32 v151, v151
	v_mfma_f32_16x16x32_bf16 v[158:161], v[102:105], v[6:9], v[158:161]
	v_exp_f32_e32 v152, v152
	v_exp_f32_e32 v153, v153
	v_cvt_pk_bf16_f32 v114, v138, v139
	v_cvt_pk_bf16_f32 v115, v140, v141
	v_cvt_pk_bf16_f32 v118, v142, v143
	v_cvt_pk_bf16_f32 v119, v144, v145
	ds_read_b128 v[138:141], v170 offset:128
	ds_read_b128 v[142:145], v170 offset:4480
	s_waitcnt lgkmcnt(3)
	v_mfma_f32_16x16x32_bf16 v[162:165], v[106:109], v[10:13], 0
	v_add_f32_e32 v123, v146, v123
	v_add_f32_e32 v122, v150, v122
	v_add_f32_e32 v123, v147, v123
	v_mfma_f32_16x16x32_bf16 v[166:169], v[106:109], v[14:17], 0
	v_add_f32_e32 v122, v151, v122
	v_add_f32_e32 v123, v148, v123
	v_add_f32_e32 v122, v152, v122
	s_waitcnt lgkmcnt(2)
	v_mfma_f32_16x16x32_bf16 v[162:165], v[110:113], v[2:5], v[162:165]
	v_add_f32_e32 v123, v149, v123
	v_add_f32_e32 v122, v153, v122
	v_cvt_pk_bf16_f32 v116, v146, v147
	v_cvt_pk_bf16_f32 v117, v148, v149
	v_mfma_f32_16x16x32_bf16 v[166:169], v[110:113], v[6:9], v[166:169]
	v_cvt_pk_bf16_f32 v120, v150, v151
	v_cvt_pk_bf16_f32 v121, v152, v153
	ds_read_b128 v[146:149], v170 offset:8832
	ds_read_b128 v[150:153], v170 offset:13184
	ds_read_b128 v[98:101], v170 offset:17536
	ds_read_b128 v[102:105], v170 offset:21888
	ds_read_b128 v[106:109], v170 offset:26240
	ds_read_b128 v[110:113], v170 offset:30592
	v_exp_f32_e32 v154, v154
	v_exp_f32_e32 v155, v155
	v_exp_f32_e32 v156, v156
	v_exp_f32_e32 v157, v157
	v_exp_f32_e32 v158, v158
	v_exp_f32_e32 v159, v159
	v_exp_f32_e32 v160, v160
	v_exp_f32_e32 v161, v161
	s_waitcnt lgkmcnt(7)
	v_mfma_f32_16x16x32_bf16 v[78:81], v[138:141], v[114:117], v[78:81]
	v_mfma_f32_16x16x32_bf16 v[74:77], v[138:141], v[118:121], v[74:77]
	v_exp_f32_e32 v162, v162
	v_exp_f32_e32 v163, v163
	v_exp_f32_e32 v164, v164
	v_exp_f32_e32 v165, v165
	s_waitcnt lgkmcnt(6)
	v_mfma_f32_16x16x32_bf16 v[70:73], v[142:145], v[114:117], v[70:73]
	v_mfma_f32_16x16x32_bf16 v[62:65], v[142:145], v[118:121], v[62:65]
	v_exp_f32_e32 v166, v166
	v_exp_f32_e32 v167, v167
	v_exp_f32_e32 v168, v168
	v_exp_f32_e32 v169, v169
	s_waitcnt lgkmcnt(5)
	v_mfma_f32_16x16x32_bf16 v[66:69], v[146:149], v[114:117], v[66:69]
	v_mfma_f32_16x16x32_bf16 v[46:49], v[146:149], v[118:121], v[46:49]
	v_add_f32_e32 v123, v154, v123
	v_add_f32_e32 v122, v158, v122
	v_add_f32_e32 v123, v155, v123
	v_add_f32_e32 v122, v159, v122
	v_add_f32_e32 v123, v156, v123
	v_add_f32_e32 v122, v160, v122
	v_add_f32_e32 v123, v157, v123
	v_add_f32_e32 v122, v161, v122
	s_waitcnt lgkmcnt(4)
	v_mfma_f32_16x16x32_bf16 v[58:61], v[150:153], v[114:117], v[58:61]
	v_mfma_f32_16x16x32_bf16 v[38:41], v[150:153], v[118:121], v[38:41]
	ds_read_b128 v[138:141], v170 offset:17600
	ds_read_b128 v[142:145], v170 offset:21952
	ds_read_b128 v[146:149], v170 offset:26304
	ds_read_b128 v[150:153], v170 offset:30656
	v_cvt_pk_bf16_f32 v184, v154, v155
	v_cvt_pk_bf16_f32 v185, v156, v157
	v_cvt_pk_bf16_f32 v128, v158, v159
	v_cvt_pk_bf16_f32 v129, v160, v161
	s_waitcnt lgkmcnt(7)
	v_mfma_f32_16x16x32_bf16 v[54:57], v[98:101], v[114:117], v[54:57]
	v_mfma_f32_16x16x32_bf16 v[30:33], v[98:101], v[118:121], v[30:33]
	v_add_f32_e32 v123, v162, v123
	v_add_f32_e32 v122, v166, v122
	v_add_f32_e32 v123, v163, v123
	v_add_f32_e32 v122, v167, v122
	v_add_f32_e32 v123, v164, v123
	v_add_f32_e32 v122, v168, v122
	v_add_f32_e32 v123, v165, v123
	v_add_f32_e32 v122, v169, v122
	s_waitcnt lgkmcnt(6)
	v_mfma_f32_16x16x32_bf16 v[50:53], v[102:105], v[114:117], v[50:53]
	v_mfma_f32_16x16x32_bf16 v[26:29], v[102:105], v[118:121], v[26:29]
	v_cvt_pk_bf16_f32 v186, v162, v163
	v_cvt_pk_bf16_f32 v187, v164, v165
	v_cvt_pk_bf16_f32 v130, v166, v167
	v_cvt_pk_bf16_f32 v131, v168, v169
	ds_read_b128 v[154:157], v170 offset:192
	ds_read_b128 v[158:161], v170 offset:4544
	ds_read_b128 v[162:165], v170 offset:8896
	ds_read_b128 v[166:169], v170 offset:13248
	s_waitcnt lgkmcnt(9)
	v_mfma_f32_16x16x32_bf16 v[42:45], v[106:109], v[114:117], v[42:45]
	v_mfma_f32_16x16x32_bf16 v[22:25], v[106:109], v[118:121], v[22:25]
	s_waitcnt lgkmcnt(8)
	v_mfma_f32_16x16x32_bf16 v[34:37], v[110:113], v[114:117], v[34:37]
	v_mfma_f32_16x16x32_bf16 v[18:21], v[110:113], v[118:121], v[18:21]
	s_waitcnt lgkmcnt(3)
	v_mfma_f32_16x16x32_bf16 v[78:81], v[154:157], v[184:187], v[78:81]
	v_mfma_f32_16x16x32_bf16 v[74:77], v[154:157], v[128:131], v[74:77]
	s_waitcnt lgkmcnt(2)
	v_mfma_f32_16x16x32_bf16 v[70:73], v[158:161], v[184:187], v[70:73]
	v_mfma_f32_16x16x32_bf16 v[62:65], v[158:161], v[128:131], v[62:65]
	s_waitcnt lgkmcnt(1)
	v_mfma_f32_16x16x32_bf16 v[66:69], v[162:165], v[184:187], v[66:69]
	v_mfma_f32_16x16x32_bf16 v[46:49], v[162:165], v[128:131], v[46:49]
	s_waitcnt lgkmcnt(0)
	v_mfma_f32_16x16x32_bf16 v[58:61], v[166:169], v[184:187], v[58:61]
	v_mfma_f32_16x16x32_bf16 v[38:41], v[166:169], v[128:131], v[38:41]
	s_waitcnt vmcnt(3)
	ds_write_b128 v173, v[82:85] offset:0
	s_waitcnt vmcnt(2)
	ds_write_b128 v173, v[86:89] offset:8704
	s_waitcnt vmcnt(1)
	ds_write_b128 v173, v[90:93] offset:17408
	s_waitcnt vmcnt(0)
	ds_write_b128 v173, v[94:97] offset:26112
	v_mfma_f32_16x16x32_bf16 v[54:57], v[138:141], v[184:187], v[54:57]
	v_mfma_f32_16x16x32_bf16 v[30:33], v[138:141], v[128:131], v[30:33]
	v_mfma_f32_16x16x32_bf16 v[50:53], v[142:145], v[184:187], v[50:53]
	v_mfma_f32_16x16x32_bf16 v[26:29], v[142:145], v[128:131], v[26:29]
	v_mfma_f32_16x16x32_bf16 v[42:45], v[146:149], v[184:187], v[42:45]
	v_mfma_f32_16x16x32_bf16 v[22:25], v[146:149], v[128:131], v[22:25]
	v_mfma_f32_16x16x32_bf16 v[34:37], v[150:153], v[184:187], v[34:37]
	v_mfma_f32_16x16x32_bf16 v[18:21], v[150:153], v[128:131], v[18:21]
	s_waitcnt lgkmcnt(0)
	s_barrier
	s_add_i32 s15, s15, 1
	s_cmp_eq_u32 s15, 33
	s_cbranch_scc0 .Lattn_nf_loop
	v_readlane_b32 s64, v175, 0
	v_readlane_b32 s65, v175, 1
	v_readlane_b32 s66, v175, 2
	v_readlane_b32 s67, v175, 3
	v_readlane_b32 s68, v175, 4
	v_readlane_b32 s69, v175, 5
	v_readlane_b32 s70, v175, 6
	v_readlane_b32 s71, v175, 7
	v_readlane_b32 s72, v175, 8
	v_readlane_b32 s73, v175, 9
	v_readlane_b32 s74, v175, 10
	v_readlane_b32 s75, v175, 11
	v_readlane_b32 s76, v175, 12
	v_readlane_b32 s77, v175, 13
	v_readlane_b32 s78, v175, 14
	v_readlane_b32 s79, v175, 15
	s_nop 4
	ds_read_b128 v[82:85], v137 offset:34816
	ds_read_b128 v[90:93], v137 offset:34880
	v_add_f32_e32 v186, v132, v134
	v_add_f32_e32 v184, v133, v135
	ds_bpermute_b32 v187, v172, v186
	ds_bpermute_b32 v185, v172, v184
	s_mov_b32 s10, 0x3fb8aa3b
	s_mov_b32 s11, 0xc2ce8ed0
	s_mov_b32 s6, 0x42b17218
	s_waitcnt lgkmcnt(3)
	v_mfma_f32_16x16x32_bf16 v[86:89], v[82:85], v[10:13], 0
	v_cmp_eq_u32_e64 s[40:41], 0, v179
	s_lshl_b32 s30, s14, 1
	v_lshlrev_b32_e32 v196, 3, v178
	v_mov_b32_e32 v197, 0
	v_lshlrev_b32_e32 v198, 4, v179
	v_or3_b32 v198, v198, v177, v180
	v_ashrrev_i32_e32 v199, 31, v198
	v_lshlrev_b64 v[198:199], 11, v[198:199]
	s_mov_b64 s[100:101], 0x18a10000
	v_lshl_add_u64 v[198:199], s[42:43], 0, v[198:199]
	v_lshl_add_u64 v[198:199], v[198:199], 0, s[30:31]
	v_lshl_add_u64 v[198:199], v[198:199], 0, v[196:197]
	v_lshl_add_u64 v[198:199], v[198:199], 0, s[100:101]
	global_load_dwordx2 v[146:147], v[198:199], off
	global_load_dwordx2 v[148:149], v[198:199], off offset:32
	global_load_dwordx2 v[150:151], v[198:199], off offset:64
	global_load_dwordx2 v[152:153], v[198:199], off offset:96
	global_load_dwordx2 v[188:189], v[198:199], off offset:128
	global_load_dwordx2 v[190:191], v[198:199], off offset:160
	global_load_dwordx2 v[192:193], v[198:199], off offset:192
	global_load_dwordx2 v[194:195], v[198:199], off offset:224
	s_load_dwordx2 s[100:101], s[44:45], 0x80
	v_readlane_b32 s14, v255, 36
	v_mfma_f32_16x16x32_bf16 v[82:85], v[82:85], v[14:17], 0
	ds_read_b128 v[98:101], v137 offset:39232
	v_readlane_b32 s15, v255, 37
	s_lshl_b64 s[14:15], s[14:15], 2
	s_waitcnt lgkmcnt(3)
	v_mfma_f32_16x16x32_bf16 v[86:89], v[90:93], v[2:5], v[86:89]
	ds_read_b128 v[142:145], v137 offset:47936
	v_mfma_f32_16x16x32_bf16 v[82:85], v[90:93], v[6:9], v[82:85]
	ds_read_b128 v[90:93], v137 offset:39168
	s_nop 4
	v_exp_f32_e32 v116, v86
	v_exp_f32_e32 v114, v87
	s_waitcnt lgkmcnt(0)
	v_mfma_f32_16x16x32_bf16 v[94:97], v[90:93], v[10:13], 0
	v_exp_f32_e32 v134, v82
	v_exp_f32_e32 v132, v83
	v_exp_f32_e32 v130, v84
	v_mfma_f32_16x16x32_bf16 v[90:93], v[90:93], v[14:17], 0
	v_exp_f32_e32 v128, v85
	ds_read_b128 v[82:85], v137 offset:43520
	v_exp_f32_e32 v112, v88
	v_mfma_f32_16x16x32_bf16 v[90:93], v[98:101], v[6:9], v[90:93]
	v_exp_f32_e32 v110, v89
	v_mfma_f32_16x16x32_bf16 v[94:97], v[98:101], v[2:5], v[94:97]
	s_nop 1
	v_cvt_pk_bf16_f32 v98, v134, v132
	s_nop 1
	s_nop 5
	v_exp_f32_e32 v126, v90
	v_exp_f32_e32 v124, v91
	v_exp_f32_e32 v120, v92
	v_exp_f32_e32 v118, v93
	ds_read_b128 v[90:93], v137 offset:43584
	s_waitcnt lgkmcnt(1)
	v_mfma_f32_16x16x32_bf16 v[86:89], v[82:85], v[10:13], 0
	v_exp_f32_e32 v108, v94
	v_exp_f32_e32 v106, v95
	v_exp_f32_e32 v104, v96
	v_mfma_f32_16x16x32_bf16 v[82:85], v[82:85], v[14:17], 0
	v_exp_f32_e32 v102, v97
	s_nop 1
	v_cvt_pk_bf16_f32 v94, v116, v114
	s_nop 1
	s_nop 1
	v_cvt_pk_bf16_f32 v95, v112, v110
	s_nop 1
	s_waitcnt lgkmcnt(0)
	v_mfma_f32_16x16x32_bf16 v[82:85], v[90:93], v[6:9], v[82:85]
	s_nop 1
	v_cvt_pk_bf16_f32 v96, v108, v106
	s_nop 1
	s_nop 1
	v_cvt_pk_bf16_f32 v97, v104, v102
	s_nop 1
	s_nop 1
	v_cvt_pk_bf16_f32 v99, v130, v128
	s_nop 1
	v_mfma_f32_16x16x32_bf16 v[86:89], v[90:93], v[2:5], v[86:89]
	ds_read_b128 v[90:93], v137 offset:47872
	s_nop 5
	v_exp_f32_e32 v135, v82
	v_exp_f32_e32 v133, v83
	v_exp_f32_e32 v131, v84
	v_exp_f32_e32 v129, v85
	ds_read_b128 v[82:85], v183 offset:34816
	s_nop 1
	v_cvt_pk_bf16_f32 v100, v126, v124
	s_nop 1
	s_nop 1
	v_cvt_pk_bf16_f32 v101, v120, v118
	s_nop 1
	s_waitcnt lgkmcnt(0)
	v_mfma_f32_16x16x32_bf16 v[78:81], v[82:85], v[94:97], v[78:81]
	v_exp_f32_e32 v117, v86
	v_exp_f32_e32 v115, v87
	v_exp_f32_e32 v113, v88
	v_mfma_f32_16x16x32_bf16 v[74:77], v[82:85], v[98:101], v[74:77]
	ds_read_b128 v[82:85], v183 offset:34880
	v_exp_f32_e32 v111, v89
	v_mfma_f32_16x16x32_bf16 v[138:141], v[90:93], v[10:13], 0
	v_mfma_f32_16x16x32_bf16 v[90:93], v[90:93], v[14:17], 0
	v_mfma_f32_16x16x32_bf16 v[90:93], v[142:145], v[6:9], v[90:93]
	v_mfma_f32_16x16x32_bf16 v[138:141], v[142:145], v[2:5], v[138:141]
	s_nop 1
	v_cvt_pk_bf16_f32 v142, v135, v133
	s_nop 1
	s_nop 6
	v_exp_f32_e32 v127, v90
	v_exp_f32_e32 v125, v91
	v_exp_f32_e32 v121, v92
	v_exp_f32_e32 v119, v93
	s_nop 1
	v_cvt_pk_bf16_f32 v143, v131, v129
	s_nop 1
	s_nop 1
	v_cvt_pk_bf16_f32 v144, v127, v125
	s_nop 1
	s_nop 1
	v_cvt_pk_bf16_f32 v145, v121, v119
	s_nop 1
	v_exp_f32_e32 v109, v138
	s_waitcnt lgkmcnt(0)
	v_mfma_f32_16x16x32_bf16 v[90:93], v[82:85], v[142:145], v[74:77]
	v_exp_f32_e32 v107, v139
	v_exp_f32_e32 v105, v140
	v_exp_f32_e32 v103, v141
	ds_read_b128 v[74:77], v183 offset:39168
	s_waitcnt lgkmcnt(0)
	v_mfma_f32_16x16x32_bf16 v[70:73], v[74:77], v[94:97], v[70:73]
	s_nop 1
	v_cvt_pk_bf16_f32 v138, v117, v115
	s_nop 1
	s_nop 1
	v_cvt_pk_bf16_f32 v139, v113, v111
	s_nop 1
	s_nop 1
	v_cvt_pk_bf16_f32 v140, v109, v107
	s_nop 1
	v_mfma_f32_16x16x32_bf16 v[62:65], v[74:77], v[98:101], v[62:65]
	ds_read_b128 v[74:77], v183 offset:39232
	s_nop 1
	v_cvt_pk_bf16_f32 v141, v105, v103
	s_nop 1
	s_waitcnt lgkmcnt(0)
	v_mfma_f32_16x16x32_bf16 v[86:89], v[74:77], v[142:145], v[62:65]
	s_nop 4
	ds_read_b128 v[62:65], v183 offset:43520
	s_waitcnt lgkmcnt(0)
	v_mfma_f32_16x16x32_bf16 v[66:69], v[62:65], v[94:97], v[66:69]
	v_mfma_f32_16x16x32_bf16 v[46:49], v[62:65], v[98:101], v[46:49]
	ds_read_b128 v[62:65], v183 offset:43584
	v_mfma_f32_16x16x32_bf16 v[78:81], v[82:85], v[138:141], v[78:81]
	v_mfma_f32_16x16x32_bf16 v[82:85], v[74:77], v[138:141], v[70:73]
	s_waitcnt lgkmcnt(0)
	v_mfma_f32_16x16x32_bf16 v[74:77], v[62:65], v[142:145], v[46:49]
	s_nop 2
	ds_read_b128 v[46:49], v183 offset:47872
	s_waitcnt lgkmcnt(0)
	v_mfma_f32_16x16x32_bf16 v[58:61], v[46:49], v[94:97], v[58:61]
	v_mfma_f32_16x16x32_bf16 v[38:41], v[46:49], v[98:101], v[38:41]
	ds_read_b128 v[46:49], v183 offset:47936
	v_mfma_f32_16x16x32_bf16 v[70:73], v[62:65], v[138:141], v[66:69]
	s_waitcnt lgkmcnt(0)
	v_mfma_f32_16x16x32_bf16 v[66:69], v[46:49], v[142:145], v[38:41]
	s_nop 3
	ds_read_b128 v[38:41], v183 offset:52224
	v_mfma_f32_16x16x32_bf16 v[62:65], v[46:49], v[138:141], v[58:61]
	s_waitcnt lgkmcnt(0)
	v_mfma_f32_16x16x32_bf16 v[46:49], v[38:41], v[94:97], v[54:57]
	v_mfma_f32_16x16x32_bf16 v[30:33], v[38:41], v[98:101], v[30:33]
	ds_read_b128 v[38:41], v183 offset:52288
	s_waitcnt lgkmcnt(0)
	v_mfma_f32_16x16x32_bf16 v[58:61], v[38:41], v[142:145], v[30:33]
	s_nop 4
	ds_read_b128 v[30:33], v183 offset:56576
	v_mfma_f32_16x16x32_bf16 v[54:57], v[38:41], v[138:141], v[46:49]
	s_waitcnt lgkmcnt(0)
	v_mfma_f32_16x16x32_bf16 v[38:41], v[30:33], v[94:97], v[50:53]
	s_nop 2
	ds_read_b128 v[50:53], v137 offset:52288
	v_mfma_f32_16x16x32_bf16 v[26:29], v[30:33], v[98:101], v[26:29]
	ds_read_b128 v[30:33], v183 offset:56640
	s_waitcnt lgkmcnt(0)
	v_mfma_f32_16x16x32_bf16 v[46:49], v[30:33], v[142:145], v[26:29]
	s_nop 4
	ds_read_b128 v[26:29], v183 offset:60928
	v_mfma_f32_16x16x32_bf16 v[38:41], v[30:33], v[138:141], v[38:41]
	s_waitcnt lgkmcnt(0)
	v_mfma_f32_16x16x32_bf16 v[30:33], v[26:29], v[94:97], v[42:45]
	s_nop 2
	ds_read_b128 v[42:45], v183 offset:60992
	v_mfma_f32_16x16x32_bf16 v[22:25], v[26:29], v[98:101], v[22:25]
	s_waitcnt lgkmcnt(0)
	v_mfma_f32_16x16x32_bf16 v[26:29], v[42:45], v[138:141], v[30:33]
	v_mfma_f32_16x16x32_bf16 v[30:33], v[42:45], v[142:145], v[22:25]
	ds_read_b128 v[42:45], v183 offset:65344
	s_nop 3
	ds_read_b128 v[22:25], v183 offset:65280
	s_waitcnt lgkmcnt(0)
	v_mfma_f32_16x16x32_bf16 v[34:37], v[22:25], v[94:97], v[34:37]
	v_mfma_f32_16x16x32_bf16 v[22:25], v[22:25], v[98:101], v[18:21]
	ds_read_b128 v[98:101], v137 offset:56640
	v_mfma_f32_16x16x32_bf16 v[18:21], v[42:45], v[138:141], v[34:37]
	s_nop 4
	ds_read_b128 v[34:37], v137 offset:52224
	v_mfma_f32_16x16x32_bf16 v[22:25], v[42:45], v[142:145], v[22:25]
	s_waitcnt lgkmcnt(0)
	v_mfma_f32_16x16x32_bf16 v[42:45], v[34:37], v[10:13], 0
	v_mfma_f32_16x16x32_bf16 v[34:37], v[34:37], v[14:17], 0
	v_mfma_f32_16x16x32_bf16 v[42:45], v[50:53], v[2:5], v[42:45]
	v_mfma_f32_16x16x32_bf16 v[34:37], v[50:53], v[6:9], v[34:37]
	ds_read_b128 v[50:53], v137 offset:56576
	s_nop 5
	v_exp_f32_e32 v158, v42
	v_exp_f32_e32 v156, v43
	s_waitcnt lgkmcnt(0)
	v_mfma_f32_16x16x32_bf16 v[94:97], v[50:53], v[10:13], 0
	v_exp_f32_e32 v172, v34
	v_exp_f32_e32 v174, v35
	v_pk_add_f32 v[34:35], v[134:135], 0 op_sel_hi:[1,0]
	v_mfma_f32_16x16x32_bf16 v[50:53], v[50:53], v[14:17], 0
	v_add_f32_e64 v34, v132, v34
	v_add_f32_e64 v35, v133, v35
	v_exp_f32_e32 v170, v36
	v_pk_add_f32 v[34:35], v[130:131], v[34:35]
	v_mfma_f32_16x16x32_bf16 v[50:53], v[98:101], v[6:9], v[50:53]
	v_add_f32_e64 v34, v128, v34
	v_add_f32_e64 v35, v129, v35
	v_exp_f32_e32 v166, v37
	v_pk_add_f32 v[34:35], v[34:35], v[126:127]
	v_exp_f32_e32 v154, v44
	v_pk_add_f32 v[34:35], v[124:125], v[34:35]
	s_nop 1
	v_exp_f32_e32 v168, v50
	v_pk_add_f32 v[34:35], v[120:121], v[34:35]
	v_exp_f32_e32 v164, v51
	v_pk_add_f32 v[118:119], v[118:119], v[34:35]
	ds_read_b128 v[34:37], v137 offset:60928
	v_exp_f32_e32 v160, v52
	v_exp_f32_e32 v162, v53
	ds_read_b128 v[50:53], v137 offset:60992
	v_exp_f32_e32 v144, v45
	s_waitcnt lgkmcnt(1)
	v_mfma_f32_16x16x32_bf16 v[42:45], v[34:37], v[10:13], 0
	v_mfma_f32_16x16x32_bf16 v[34:37], v[34:37], v[14:17], 0
	s_waitcnt lgkmcnt(0)
	v_mfma_f32_16x16x32_bf16 v[42:45], v[50:53], v[2:5], v[42:45]
	v_mfma_f32_16x16x32_bf16 v[34:37], v[50:53], v[6:9], v[34:37]
	ds_read_b128 v[50:53], v137 offset:65280
	s_nop 5
	v_exp_f32_e32 v159, v42
	v_exp_f32_e32 v157, v43
	s_waitcnt lgkmcnt(0)
	v_mfma_f32_16x16x32_bf16 v[10:13], v[50:53], v[10:13], 0
	v_exp_f32_e32 v173, v34
	v_exp_f32_e32 v175, v35
	v_exp_f32_e32 v171, v36
	v_mfma_f32_16x16x32_bf16 v[14:17], v[50:53], v[14:17], 0
	ds_read_b128 v[50:53], v137 offset:65344
	v_exp_f32_e32 v167, v37
	s_nop 1
	v_cvt_pk_bf16_f32 v128, v173, v175
	s_nop 1
	v_mfma_f32_16x16x32_bf16 v[94:97], v[98:101], v[2:5], v[94:97]
	s_nop 1
	v_cvt_pk_bf16_f32 v98, v172, v174
	s_nop 1
	s_nop 1
	v_cvt_pk_bf16_f32 v99, v170, v166
	s_nop 1
	s_nop 1
	v_cvt_pk_bf16_f32 v100, v168, v164
	s_nop 1
	s_waitcnt lgkmcnt(0)
	v_mfma_f32_16x16x32_bf16 v[2:5], v[50:53], v[2:5], v[10:13]
	s_nop 1
	v_cvt_pk_bf16_f32 v101, v160, v162
	s_nop 1
	s_nop 5
	v_exp_f32_e32 v142, v94
	ds_read_b128 v[10:13], v183 offset:35008
	v_exp_f32_e32 v143, v2
	v_exp_f32_e32 v141, v3
	v_exp_f32_e32 v139, v4
	v_exp_f32_e32 v137, v5
	ds_read_b128 v[2:5], v183 offset:34944
	v_mfma_f32_16x16x32_bf16 v[6:9], v[50:53], v[6:9], v[14:17]
	v_exp_f32_e32 v140, v95
	v_exp_f32_e32 v138, v96
	v_exp_f32_e32 v136, v97
	s_nop 1
	v_cvt_pk_bf16_f32 v94, v158, v156
	s_nop 1
	s_nop 1
	v_cvt_pk_bf16_f32 v95, v154, v144
	s_nop 1
	s_nop 1
	v_cvt_pk_bf16_f32 v96, v142, v140
	s_nop 1
	s_nop 1
	v_cvt_pk_bf16_f32 v97, v138, v136
	s_nop 1
	s_nop 4
	v_exp_f32_e32 v169, v6
	v_exp_f32_e32 v165, v7
	v_exp_f32_e32 v161, v8
	v_exp_f32_e32 v163, v9
	s_waitcnt lgkmcnt(0)
	v_mfma_f32_16x16x32_bf16 v[6:9], v[2:5], v[94:97], v[78:81]
	s_nop 1
	v_cvt_pk_bf16_f32 v129, v171, v167
	s_nop 1
	s_nop 1
	v_cvt_pk_bf16_f32 v130, v169, v165
	s_nop 1
	s_nop 1
	v_cvt_pk_bf16_f32 v131, v161, v163
	s_nop 1
	v_mfma_f32_16x16x32_bf16 v[2:5], v[2:5], v[98:101], v[90:93]
	v_exp_f32_e32 v155, v44
	v_exp_f32_e32 v145, v45
	s_nop 1
	v_cvt_pk_bf16_f32 v124, v159, v157
	s_nop 1
	v_mfma_f32_16x16x32_bf16 v[90:93], v[10:13], v[128:131], v[2:5]
	s_nop 1
	v_cvt_pk_bf16_f32 v125, v155, v145
	s_nop 1
	s_nop 1
	v_cvt_pk_bf16_f32 v126, v143, v141
	s_nop 1
	s_nop 1
	v_cvt_pk_bf16_f32 v127, v139, v137
	s_nop 1
	s_nop 0
	v_mfma_f32_16x16x32_bf16 v[78:81], v[10:13], v[124:127], v[6:9]
	s_nop 2
	ds_read_b128 v[2:5], v183 offset:39296
	ds_read_b128 v[10:13], v183 offset:39360
	s_waitcnt lgkmcnt(1)
	v_mfma_f32_16x16x32_bf16 v[6:9], v[2:5], v[94:97], v[82:85]
	v_mfma_f32_16x16x32_bf16 v[2:5], v[2:5], v[98:101], v[86:89]
	s_waitcnt lgkmcnt(0)
	v_mfma_f32_16x16x32_bf16 v[50:53], v[10:13], v[128:131], v[2:5]
	v_mfma_f32_16x16x32_bf16 v[14:17], v[10:13], v[124:127], v[6:9]
	s_nop 4
	ds_read_b128 v[2:5], v183 offset:43648
	ds_read_b128 v[10:13], v183 offset:43712
	s_waitcnt lgkmcnt(1)
	v_mfma_f32_16x16x32_bf16 v[6:9], v[2:5], v[94:97], v[70:73]
	v_mfma_f32_16x16x32_bf16 v[2:5], v[2:5], v[98:101], v[74:77]
	s_waitcnt lgkmcnt(0)
	v_mfma_f32_16x16x32_bf16 v[34:37], v[10:13], v[128:131], v[2:5]
	v_mfma_f32_16x16x32_bf16 v[6:9], v[10:13], v[124:127], v[6:9]
	s_nop 4
	ds_read_b128 v[2:5], v183 offset:48000
	s_waitcnt lgkmcnt(0)
	v_mfma_f32_16x16x32_bf16 v[10:13], v[2:5], v[94:97], v[62:65]
	s_nop 2
	ds_read_b128 v[62:65], v183 offset:48064
	v_mfma_f32_16x16x32_bf16 v[42:45], v[2:5], v[98:101], v[66:69]
	s_waitcnt lgkmcnt(0)
	v_mfma_f32_16x16x32_bf16 v[2:5], v[62:65], v[124:127], v[10:13]
	v_mfma_f32_16x16x32_bf16 v[10:13], v[62:65], v[128:131], v[42:45]
	ds_read_b128 v[62:65], v183 offset:52416
	s_nop 3
	ds_read_b128 v[42:45], v183 offset:52352
	s_waitcnt lgkmcnt(0)
	v_mfma_f32_16x16x32_bf16 v[54:57], v[42:45], v[94:97], v[54:57]
	v_mfma_f32_16x16x32_bf16 v[58:61], v[42:45], v[98:101], v[58:61]
	v_mfma_f32_16x16x32_bf16 v[42:45], v[62:65], v[124:127], v[54:57]
	v_mfma_f32_16x16x32_bf16 v[54:57], v[62:65], v[128:131], v[58:61]
	s_nop 5
	ds_read_b128 v[58:61], v183 offset:56704
	s_waitcnt lgkmcnt(0)
	v_mfma_f32_16x16x32_bf16 v[38:41], v[58:61], v[94:97], v[38:41]
	v_mfma_f32_16x16x32_bf16 v[46:49], v[58:61], v[98:101], v[46:49]
	ds_read_b128 v[58:61], v183 offset:56768
	s_waitcnt lgkmcnt(0)
	v_mfma_f32_16x16x32_bf16 v[38:41], v[58:61], v[124:127], v[38:41]
	v_mfma_f32_16x16x32_bf16 v[46:49], v[58:61], v[128:131], v[46:49]
	ds_read_b128 v[58:61], v183 offset:61056
	s_waitcnt lgkmcnt(0)
	v_mfma_f32_16x16x32_bf16 v[26:29], v[58:61], v[94:97], v[26:29]
	v_mfma_f32_16x16x32_bf16 v[30:33], v[58:61], v[98:101], v[30:33]
	ds_read_b128 v[58:61], v183 offset:61120
	s_waitcnt lgkmcnt(0)
	v_mfma_f32_16x16x32_bf16 v[26:29], v[58:61], v[124:127], v[26:29]
	v_mfma_f32_16x16x32_bf16 v[30:33], v[58:61], v[128:131], v[30:33]
	ds_read_b128 v[58:61], v183 offset:65408
	s_waitcnt lgkmcnt(0)
	v_mfma_f32_16x16x32_bf16 v[18:21], v[58:61], v[94:97], v[18:21]
	v_mfma_f32_16x16x32_bf16 v[22:25], v[58:61], v[98:101], v[22:25]
	ds_read_b128 v[58:61], v183 offset:65472
	s_waitcnt lgkmcnt(0)
	s_barrier
	v_mfma_f32_16x16x32_bf16 v[18:21], v[58:61], v[124:127], v[18:21]
	v_mfma_f32_16x16x32_bf16 v[22:25], v[58:61], v[128:131], v[22:25]
	v_add_f32_e64 v58, v172, 0
	v_add_f32_e64 v59, v173, 0
	v_add_f32_e32 v60, v122, v118
	v_pk_add_f32 v[58:59], v[174:175], v[58:59]
	v_add_f32_e32 v60, v60, v119
	v_pk_add_f32 v[58:59], v[170:171], v[58:59]
	s_nop 0
	v_pk_add_f32 v[58:59], v[166:167], v[58:59]
	s_nop 0
	v_pk_add_f32 v[58:59], v[58:59], v[168:169]
	s_nop 0
	v_pk_add_f32 v[58:59], v[164:165], v[58:59]
	s_nop 0
	v_pk_add_f32 v[58:59], v[160:161], v[58:59]
	s_nop 0
	v_pk_add_f32 v[58:59], v[162:163], v[58:59]
	s_nop 0
	v_add_f32_e32 v58, v60, v58
	v_pk_add_f32 v[60:61], v[116:117], 0 op_sel_hi:[1,0]
	v_add_f32_e32 v62, v58, v59
	v_pk_add_f32 v[60:61], v[114:115], v[60:61]
	v_pk_add_f32 v[58:59], v[158:159], 0 op_sel_hi:[1,0]
	v_pk_add_f32 v[60:61], v[112:113], v[60:61]
	v_pk_add_f32 v[58:59], v[156:157], v[58:59]
	v_pk_add_f32 v[60:61], v[110:111], v[60:61]
	v_pk_add_f32 v[58:59], v[154:155], v[58:59]
	v_pk_add_f32 v[60:61], v[60:61], v[108:109]
	v_pk_add_f32 v[58:59], v[144:145], v[58:59]
	v_pk_add_f32 v[60:61], v[106:107], v[60:61]
	v_pk_add_f32 v[58:59], v[58:59], v[142:143]
	v_pk_add_f32 v[60:61], v[104:105], v[60:61]
	v_pk_add_f32 v[58:59], v[140:141], v[58:59]
	v_pk_add_f32 v[60:61], v[102:103], v[60:61]
	v_pk_add_f32 v[58:59], v[138:139], v[58:59]
	v_add_f32_e32 v60, v123, v60
	v_pk_add_f32 v[58:59], v[136:137], v[58:59]
	v_add_f32_e32 v60, v60, v61
	v_add_f32_e32 v58, v60, v58
	v_add_f32_e32 v58, v58, v59
	v_add_f32_e32 v59, v186, v187
	v_mul_f32_e32 v60, 0x3fb8aa3b, v59
	v_fma_f32 v61, v59, s10, -v60
	v_rndne_f32_e32 v63, v60
	v_fmac_f32_e32 v61, 0x32a5705f, v59
	v_sub_f32_e32 v60, v60, v63
	v_add_f32_e32 v60, v60, v61
	v_exp_f32_e32 v60, v60
	v_cvt_i32_f32_e32 v61, v63
	v_cmp_ngt_f32_e32 vcc, s11, v59
	v_ldexp_f32 v60, v60, v61
	s_nop 0
	v_cndmask_b32_e32 v60, 0, v60, vcc
	v_cmp_nlt_f32_e32 vcc, s6, v59
	s_nop 1
	v_cndmask_b32_e32 v59, v220, v60, vcc
	v_add_f32_e32 v60, v184, v185
	v_mul_f32_e32 v61, 0x3fb8aa3b, v60
	v_fma_f32 v63, v60, s10, -v61
	v_rndne_f32_e32 v64, v61
	v_fmac_f32_e32 v63, 0x32a5705f, v60
	v_sub_f32_e32 v61, v61, v64
	v_add_f32_e32 v61, v61, v63
	v_exp_f32_e32 v61, v61
	v_cvt_i32_f32_e32 v63, v64
	v_cmp_ngt_f32_e32 vcc, s11, v60
	v_ldexp_f32 v61, v61, v63
	s_nop 0
	v_cndmask_b32_e32 v61, 0, v61, vcc
	v_cmp_nlt_f32_e32 vcc, s6, v60
	s_movk_i32 s6, 0x200
	s_nop 0
	v_cndmask_b32_e32 v60, v220, v61, vcc
	v_sub_f32_e32 v59, v59, v60
	ds_bpermute_b32 v60, v176, v58
	v_add_f32_e32 v59, v236, v59
	v_cndmask_b32_e64 v59, -v59, 1.0, s[40:41]
	s_waitcnt lgkmcnt(0)
	v_add_f32_e32 v58, v58, v60
	ds_bpermute_b32 v60, v1, v58
	s_waitcnt lgkmcnt(0)
	v_add_f32_e32 v58, v58, v60
	ds_bpermute_b32 v60, v176, v62
	s_waitcnt lgkmcnt(0)
	v_add_f32_e32 v60, v62, v60
	ds_bpermute_b32 v61, v1, v60
	s_waitcnt lgkmcnt(0)
	v_add_f32_e32 v60, v60, v61
	v_div_scale_f32 v61, s[10:11], v58, v58, v59
	v_rcp_f32_e32 v62, v61
	s_nop 0
	v_fma_f32 v63, -v61, v62, 1.0
	v_fmac_f32_e32 v62, v63, v62
	v_div_scale_f32 v63, vcc, v59, v58, v59
	v_mul_f32_e32 v64, v63, v62
	v_fma_f32 v65, -v61, v64, v63
	v_fmac_f32_e32 v64, v65, v62
	v_fma_f32 v61, -v61, v64, v63
	v_div_fmas_f32 v61, v61, v62, v64
	v_div_fixup_f32 v62, v61, v58, v59
	v_div_scale_f32 v58, s[10:11], v60, v60, v59
	v_rcp_f32_e32 v61, v58
	s_nop 0
	v_fma_f32 v63, -v58, v61, 1.0
	v_fmac_f32_e32 v61, v63, v61
	v_div_scale_f32 v63, vcc, v59, v60, v59
	v_mul_f32_e32 v64, v63, v61
	v_fma_f32 v65, -v58, v64, v63
	v_fmac_f32_e32 v64, v65, v61
	v_fma_f32 v58, -v58, v64, v63
	v_div_fmas_f32 v58, v58, v61, v64
	v_div_fixup_f32 v64, v58, v60, v59
	v_lshlrev_b32_e32 v58, 13, v182
	v_lshlrev_b32_e32 v59, 4, v181
	v_pk_mul_f32 v[66:67], v[90:91], v[64:65] op_sel_hi:[1,0]
	v_pk_mul_f32 v[68:69], v[92:93], v[64:65] op_sel_hi:[1,0]
	v_pk_mul_f32 v[70:71], v[78:79], v[62:63] op_sel_hi:[1,0]
	v_pk_mul_f32 v[72:73], v[80:81], v[62:63] op_sel_hi:[1,0]
	v_pk_mul_f32 v[74:75], v[10:11], v[64:65] op_sel_hi:[1,0]
	v_pk_mul_f32 v[76:77], v[12:13], v[64:65] op_sel_hi:[1,0]
	v_pk_mul_f32 v[78:79], v[2:3], v[62:63] op_sel_hi:[1,0]
	v_pk_mul_f32 v[80:81], v[4:5], v[62:63] op_sel_hi:[1,0]
	v_add3_u32 v84, 0, v58, v59
	v_cndmask_b32_e64 v61, v73, v69, s[40:41]
	v_cndmask_b32_e64 v60, v72, v68, s[40:41]
	v_cndmask_b32_e64 v59, v71, v67, s[40:41]
	v_cndmask_b32_e64 v58, v70, v66, s[40:41]
	v_cndmask_b32_e64 v5, v81, v77, s[40:41]
	v_cndmask_b32_e64 v4, v80, v76, s[40:41]
	v_cndmask_b32_e64 v3, v79, v75, s[40:41]
	v_cndmask_b32_e64 v2, v78, v74, s[40:41]
	v_pk_mul_f32 v[54:55], v[54:55], v[64:65] op_sel_hi:[1,0]
	v_pk_mul_f32 v[56:57], v[56:57], v[64:65] op_sel_hi:[1,0]
	v_pk_mul_f32 v[42:43], v[42:43], v[62:63] op_sel_hi:[1,0]
	v_pk_mul_f32 v[44:45], v[44:45], v[62:63] op_sel_hi:[1,0]
	ds_write_b128 v84, v[58:61]
	v_pk_mul_f32 v[50:51], v[50:51], v[64:65] op_sel_hi:[1,0]
	v_pk_mul_f32 v[52:53], v[52:53], v[64:65] op_sel_hi:[1,0]
	v_pk_mul_f32 v[58:59], v[14:15], v[62:63] op_sel_hi:[1,0]
	v_pk_mul_f32 v[60:61], v[16:17], v[62:63] op_sel_hi:[1,0]
	ds_write_b128 v84, v[2:5] offset:3072
	v_cndmask_b32_e64 v5, v45, v57, s[40:41]
	v_cndmask_b32_e64 v4, v44, v56, s[40:41]
	v_cndmask_b32_e64 v3, v43, v55, s[40:41]
	v_cndmask_b32_e64 v2, v42, v54, s[40:41]
	v_pk_mul_f32 v[46:47], v[46:47], v[64:65] op_sel_hi:[1,0]
	v_pk_mul_f32 v[48:49], v[48:49], v[64:65] op_sel_hi:[1,0]
	v_pk_mul_f32 v[38:39], v[38:39], v[62:63] op_sel_hi:[1,0]
	v_pk_mul_f32 v[82:83], v[40:41], v[62:63] op_sel_hi:[1,0]
	v_cndmask_b32_e64 v17, v61, v53, s[40:41]
	v_cndmask_b32_e64 v16, v60, v52, s[40:41]
	v_cndmask_b32_e64 v15, v59, v51, s[40:41]
	v_cndmask_b32_e64 v14, v58, v50, s[40:41]
	ds_write_b128 v84, v[2:5] offset:4096
	v_cndmask_b32_e64 v5, v83, v49, s[40:41]
	v_cndmask_b32_e64 v4, v82, v48, s[40:41]
	v_cndmask_b32_e64 v3, v39, v47, s[40:41]
	v_cndmask_b32_e64 v2, v38, v46, s[40:41]
	v_pk_mul_f32 v[30:31], v[30:31], v[64:65] op_sel_hi:[1,0]
	v_pk_mul_f32 v[32:33], v[32:33], v[64:65] op_sel_hi:[1,0]
	v_pk_mul_f32 v[26:27], v[26:27], v[62:63] op_sel_hi:[1,0]
	v_pk_mul_f32 v[28:29], v[28:29], v[62:63] op_sel_hi:[1,0]
	ds_write_b128 v84, v[14:17] offset:1024
	v_pk_mul_f32 v[14:15], v[34:35], v[64:65] op_sel_hi:[1,0]
	v_pk_mul_f32 v[16:17], v[36:37], v[64:65] op_sel_hi:[1,0]
	v_pk_mul_f32 v[34:35], v[6:7], v[62:63] op_sel_hi:[1,0]
	v_pk_mul_f32 v[36:37], v[8:9], v[62:63] op_sel_hi:[1,0]
	ds_write_b128 v84, v[2:5] offset:5120
	v_cndmask_b32_e64 v5, v29, v33, s[40:41]
	v_cndmask_b32_e64 v4, v28, v32, s[40:41]
	v_cndmask_b32_e64 v3, v27, v31, s[40:41]
	v_cndmask_b32_e64 v2, v26, v30, s[40:41]
	v_pk_mul_f32 v[22:23], v[22:23], v[64:65] op_sel_hi:[1,0]
	v_pk_mul_f32 v[24:25], v[24:25], v[64:65] op_sel_hi:[1,0]
	v_pk_mul_f32 v[64:65], v[18:19], v[62:63] op_sel_hi:[1,0]
	v_pk_mul_f32 v[62:63], v[20:21], v[62:63] op_sel_hi:[1,0]
	ds_write_b128 v84, v[2:5] offset:6144
	v_cndmask_b32_e64 v5, v63, v25, s[40:41]
	v_cndmask_b32_e64 v4, v62, v24, s[40:41]
	v_cndmask_b32_e64 v3, v65, v23, s[40:41]
	v_cndmask_b32_e64 v2, v64, v22, s[40:41]
	ds_write_b128 v84, v[2:5] offset:7168
	v_lshlrev_b32_e32 v2, 9, v182
	v_cndmask_b32_e64 v9, v37, v17, s[40:41]
	v_cndmask_b32_e64 v8, v36, v16, s[40:41]
	v_cndmask_b32_e64 v7, v35, v15, s[40:41]
	v_cndmask_b32_e64 v6, v34, v14, s[40:41]
	v_bitop3_b32 v2, v2, s6, v181 bitop3:0x36
	ds_write_b128 v84, v[6:9] offset:2048
	v_lshl_add_u32 v84, v2, 4, 0
	s_waitcnt lgkmcnt(0)
	s_barrier
	s_add_u32 s100, s100, s14
	s_addc_u32 s101, s101, s15
	v_lshlrev_b32_e32 v132, 4, v178
	global_load_dwordx4 v[100:103], v132, s[100:101]
	global_load_dwordx4 v[104:107], v132, s[100:101] offset:64
	global_load_dwordx4 v[108:111], v132, s[100:101] offset:128
	global_load_dwordx4 v[112:115], v132, s[100:101] offset:192
	global_load_dwordx4 v[116:119], v132, s[100:101] offset:256
	global_load_dwordx4 v[120:123], v132, s[100:101] offset:320
	global_load_dwordx4 v[124:127], v132, s[100:101] offset:384
	global_load_dwordx4 v[128:131], v132, s[100:101] offset:448
	ds_read_b128 v[2:5], v84
	ds_read_b128 v[6:9], v84 offset:1024
	v_cndmask_b32_e64 v67, v67, v71, s[40:41]
	v_cndmask_b32_e64 v66, v66, v70, s[40:41]
	v_cndmask_b32_e64 v69, v69, v73, s[40:41]
	v_cndmask_b32_e64 v68, v68, v72, s[40:41]
	v_cndmask_b32_e64 v73, v75, v79, s[40:41]
	v_cndmask_b32_e64 v72, v74, v78, s[40:41]
	v_cndmask_b32_e64 v75, v77, v81, s[40:41]
	v_cndmask_b32_e64 v74, v76, v80, s[40:41]
	v_cndmask_b32_e64 v77, v47, v39, s[40:41]
	v_cndmask_b32_e64 v76, v46, v38, s[40:41]
	s_waitcnt lgkmcnt(1)
	v_pk_add_f32 v[38:39], v[66:67], v[2:3]
	v_cndmask_b32_e64 v71, v17, v37, s[40:41]
	v_mul_f32_e32 v66, v39, v39
	v_cndmask_b32_e64 v70, v16, v36, s[40:41]
	v_pk_add_f32 v[36:37], v[68:69], v[4:5]
	v_fmac_f32_e32 v66, v38, v38
	v_cndmask_b32_e64 v59, v51, v59, s[40:41]
	v_cndmask_b32_e64 v58, v50, v58, s[40:41]
	ds_read_b128 v[10:13], v84 offset:2048
	v_fmac_f32_e32 v66, v36, v36
	v_cndmask_b32_e64 v53, v53, v61, s[40:41]
	v_cndmask_b32_e64 v52, v52, v60, s[40:41]
	v_cndmask_b32_e64 v61, v15, v35, s[40:41]
	v_cndmask_b32_e64 v60, v14, v34, s[40:41]
	v_fmac_f32_e32 v66, v37, v37
	s_waitcnt lgkmcnt(1)
	v_pk_add_f32 v[34:35], v[58:59], v[6:7]
	v_cndmask_b32_e64 v79, v49, v83, s[40:41]
	v_fmac_f32_e32 v66, v34, v34
	v_cndmask_b32_e64 v78, v48, v82, s[40:41]
	v_cndmask_b32_e64 v83, v33, v29, s[40:41]
	v_cndmask_b32_e64 v82, v32, v28, s[40:41]
	v_pk_add_f32 v[32:33], v[52:53], v[8:9]
	v_fmac_f32_e32 v66, v35, v35
	ds_read_b128 v[14:17], v84 offset:3072
	v_fmac_f32_e32 v66, v32, v32
	v_cndmask_b32_e64 v81, v31, v27, s[40:41]
	v_cndmask_b32_e64 v80, v30, v26, s[40:41]
	v_fmac_f32_e32 v66, v33, v33
	s_waitcnt lgkmcnt(1)
	v_pk_add_f32 v[30:31], v[60:61], v[10:11]
	v_pk_add_f32 v[28:29], v[70:71], v[12:13]
	v_fmac_f32_e32 v66, v30, v30
	v_fmac_f32_e32 v66, v31, v31
	ds_read_b128 v[18:21], v84 offset:4096
	v_fmac_f32_e32 v66, v28, v28
	v_fmac_f32_e32 v66, v29, v29
	s_waitcnt lgkmcnt(1)
	v_pk_add_f32 v[26:27], v[72:73], v[14:15]
	v_cndmask_b32_e64 v63, v25, v63, s[40:41]
	v_fmac_f32_e32 v66, v26, v26
	v_cndmask_b32_e64 v62, v24, v62, s[40:41]
	v_pk_add_f32 v[24:25], v[74:75], v[16:17]
	v_fmac_f32_e32 v66, v27, v27
	v_cndmask_b32_e64 v55, v55, v43, s[40:41]
	v_cndmask_b32_e64 v54, v54, v42, s[40:41]
	ds_read_b128 v[40:43], v84 offset:5120
	v_fmac_f32_e32 v66, v24, v24
	v_cndmask_b32_e64 v65, v23, v65, s[40:41]
	v_cndmask_b32_e64 v64, v22, v64, s[40:41]
	v_fmac_f32_e32 v66, v25, v25
	s_waitcnt lgkmcnt(1)
	v_pk_add_f32 v[22:23], v[54:55], v[18:19]
	v_cndmask_b32_e64 v57, v57, v45, s[40:41]
	v_cndmask_b32_e64 v56, v56, v44, s[40:41]
	v_fmac_f32_e32 v66, v22, v22
	ds_read_b128 v[44:47], v84 offset:6144
	ds_read_b128 v[48:51], v84 offset:7168
	v_pk_add_f32 v[20:21], v[56:57], v[20:21]
	v_fmac_f32_e32 v66, v23, v23
	v_fmac_f32_e32 v66, v20, v20
	v_fmac_f32_e32 v66, v21, v21
	s_waitcnt lgkmcnt(2)
	v_pk_add_f32 v[18:19], v[76:77], v[40:41]
	v_pk_add_f32 v[16:17], v[78:79], v[42:43]
	v_fmac_f32_e32 v66, v18, v18
	v_fmac_f32_e32 v66, v19, v19
	v_fmac_f32_e32 v66, v16, v16
	s_waitcnt lgkmcnt(1)
	v_pk_add_f32 v[14:15], v[80:81], v[44:45]
	v_fmac_f32_e32 v66, v17, v17
	v_pk_mul_f32 v[4:5], v[14:15], v[14:15]
	v_pk_add_f32 v[12:13], v[82:83], v[46:47]
	v_add_f32_e32 v4, v4, v66
	v_pk_mul_f32 v[2:3], v[12:13], v[12:13]
	v_add_f32_e32 v4, v5, v4
	v_add_f32_e32 v2, v2, v4
	s_waitcnt lgkmcnt(0)
	v_pk_add_f32 v[8:9], v[64:65], v[48:49]
	v_add_f32_e32 v10, v3, v2
	v_pk_mul_f32 v[4:5], v[8:9], v[8:9]
	v_pk_add_f32 v[6:7], v[62:63], v[50:51]
	v_add_f32_e32 v4, v4, v10
	v_pk_mul_f32 v[2:3], v[6:7], v[6:7]
	v_add_f32_e32 v4, v5, v4
	v_add_f32_e32 v2, v2, v4
	v_add_f32_e32 v2, v3, v2
	ds_bpermute_b32 v3, v176, v2
	s_load_dwordx2 s[10:11], s[44:45], 0x80
	v_lshlrev_b32_e32 v4, 3, v178
	v_mov_b32_e32 v5, v0
	s_mov_b32 s6, 0x18a10000
	s_waitcnt lgkmcnt(0)
	v_add_f32_e32 v2, v2, v3
	ds_bpermute_b32 v1, v1, v2
	s_add_u32 s10, s10, s14
	s_addc_u32 s11, s11, s15
	s_mov_b64 s[14:15], 0x18a10000
	v_lshlrev_b32_e32 v44, 4, v178
	s_waitcnt lgkmcnt(0)
	v_add_f32_e32 v1, v2, v1
	v_fmamk_f32 v1, v1, 0x3c000000, v234
	v_cmp_gt_f32_e32 vcc, s90, v1
	v_mul_f32_e32 v2, 0x4b800000, v1
	s_nop 0
	v_cndmask_b32_e32 v1, v1, v2, vcc
	v_rsq_f32_e32 v1, v1
	s_nop 0
	v_mul_f32_e32 v2, 0x45800000, v1
	v_cndmask_b32_e32 v1, v1, v2, vcc
	v_lshlrev_b32_e32 v2, 4, v179
	v_or3_b32 v2, v2, v177, v180
	v_ashrrev_i32_e32 v3, 31, v2
	v_lshlrev_b64 v[2:3], 11, v[2:3]
	v_lshl_add_u64 v[2:3], s[42:43], 0, v[2:3]
	v_lshl_add_u64 v[2:3], v[2:3], 0, s[30:31]
	v_lshl_add_u64 v[2:3], v[2:3], 0, v[4:5]
	v_add_co_u32_e32 v40, vcc, s6, v2
	v_lshl_add_u64 v[10:11], v[2:3], 0, s[14:15]
	s_nop 0
	v_addc_co_u32_e32 v41, vcc, 0, v3, vcc
	v_mul_f32_e32 v1, v227, v1
	v_mul_f32_e32 v38, v38, v1
	v_mul_f32_e32 v36, v36, v1
	v_mul_f32_e32 v34, v34, v1
	v_mul_f32_e32 v32, v32, v1
	v_mul_f32_e32 v30, v30, v1
	v_mul_f32_e32 v28, v28, v1
	v_mul_f32_e32 v26, v26, v1
	v_mul_f32_e32 v24, v24, v1
	v_mul_f32_e32 v22, v22, v1
	v_mul_f32_e32 v20, v20, v1
	v_mul_f32_e32 v18, v18, v1
	v_mul_f32_e32 v16, v16, v1
	v_mul_f32_e32 v14, v14, v1
	v_mul_f32_e32 v12, v12, v1
	s_waitcnt vmcnt(0)
	v_mov_b32_e32 v42, v146
	v_mov_b32_e32 v43, v147
	v_mov_b32_e32 v2, v100
	v_mov_b32_e32 v3, v101
	v_mov_b32_e32 v4, v102
	v_mov_b32_e32 v5, v103
	v_mul_f32_e32 v2, v2, v38
	v_lshlrev_b32_e32 v38, 16, v42
	v_mul_f32_e32 v2, v2, v38
	v_mul_f32_e32 v38, v39, v1
	v_mul_f32_e32 v4, v4, v36
	v_lshlrev_b32_e32 v36, 16, v43
	v_mul_f32_e32 v3, v3, v38
	v_and_b32_e32 v38, 0xffff0000, v42
	v_mul_f32_e32 v4, v4, v36
	v_mul_f32_e32 v36, v37, v1
	v_mul_f32_e32 v3, v3, v38
	v_mul_f32_e32 v5, v5, v36
	v_and_b32_e32 v36, 0xffff0000, v43
	v_mul_f32_e32 v5, v5, v36
	s_nop 1
	v_cvt_pk_bf16_f32 v2, v2, v3
	s_nop 1
	v_cvt_pk_bf16_f32 v3, v4, v5
	global_store_dwordx2 v[40:41], v[2:3], off
	v_mov_b32_e32 v36, v148
	v_mov_b32_e32 v37, v149
	s_nop 0
	v_mov_b32_e32 v2, v104
	v_mov_b32_e32 v3, v105
	v_mov_b32_e32 v4, v106
	v_mov_b32_e32 v5, v107
	v_mul_f32_e32 v2, v2, v34
	v_lshlrev_b32_e32 v34, 16, v36
	v_mul_f32_e32 v2, v2, v34
	v_mul_f32_e32 v34, v35, v1
	v_mul_f32_e32 v4, v4, v32
	v_lshlrev_b32_e32 v32, 16, v37
	v_mul_f32_e32 v3, v3, v34
	v_and_b32_e32 v34, 0xffff0000, v36
	v_mul_f32_e32 v4, v4, v32
	v_mul_f32_e32 v32, v33, v1
	v_mul_f32_e32 v3, v3, v34
	v_mul_f32_e32 v5, v5, v32
	v_and_b32_e32 v32, 0xffff0000, v37
	v_mul_f32_e32 v5, v5, v32
	s_nop 1
	v_cvt_pk_bf16_f32 v2, v2, v3
	s_nop 1
	v_cvt_pk_bf16_f32 v3, v4, v5
	global_store_dwordx2 v[10:11], v[2:3], off offset:32
	v_mov_b32_e32 v32, v150
	v_mov_b32_e32 v33, v151
	s_nop 0
	v_mov_b32_e32 v2, v108
	v_mov_b32_e32 v3, v109
	v_mov_b32_e32 v4, v110
	v_mov_b32_e32 v5, v111
	v_mul_f32_e32 v2, v2, v30
	v_lshlrev_b32_e32 v30, 16, v32
	v_mul_f32_e32 v2, v2, v30
	v_mul_f32_e32 v30, v31, v1
	v_mul_f32_e32 v4, v4, v28
	v_lshlrev_b32_e32 v28, 16, v33
	v_mul_f32_e32 v3, v3, v30
	v_and_b32_e32 v30, 0xffff0000, v32
	v_mul_f32_e32 v4, v4, v28
	v_mul_f32_e32 v28, v29, v1
	v_mul_f32_e32 v3, v3, v30
	v_mul_f32_e32 v5, v5, v28
	v_and_b32_e32 v28, 0xffff0000, v33
	v_mul_f32_e32 v5, v5, v28
	s_nop 1
	v_cvt_pk_bf16_f32 v2, v2, v3
	s_nop 1
	v_cvt_pk_bf16_f32 v3, v4, v5
	global_store_dwordx2 v[10:11], v[2:3], off offset:64
	v_mov_b32_e32 v28, v152
	v_mov_b32_e32 v29, v153
	s_nop 0
	v_mov_b32_e32 v2, v112
	v_mov_b32_e32 v3, v113
	v_mov_b32_e32 v4, v114
	v_mov_b32_e32 v5, v115
	v_mul_f32_e32 v2, v2, v26
	v_lshlrev_b32_e32 v26, 16, v28
	v_mul_f32_e32 v2, v2, v26
	v_mul_f32_e32 v26, v27, v1
	v_mul_f32_e32 v4, v4, v24
	v_lshlrev_b32_e32 v24, 16, v29
	v_mul_f32_e32 v3, v3, v26
	v_and_b32_e32 v26, 0xffff0000, v28
	v_mul_f32_e32 v4, v4, v24
	v_mul_f32_e32 v24, v25, v1
	v_mul_f32_e32 v3, v3, v26
	v_mul_f32_e32 v5, v5, v24
	v_and_b32_e32 v24, 0xffff0000, v29
	v_mul_f32_e32 v5, v5, v24
	s_nop 1
	v_cvt_pk_bf16_f32 v2, v2, v3
	s_nop 1
	v_cvt_pk_bf16_f32 v3, v4, v5
	global_store_dwordx2 v[10:11], v[2:3], off offset:96
	v_mov_b32_e32 v24, v188
	v_mov_b32_e32 v25, v189
	s_nop 0
	v_mov_b32_e32 v2, v116
	v_mov_b32_e32 v3, v117
	v_mov_b32_e32 v4, v118
	v_mov_b32_e32 v5, v119
	v_mul_f32_e32 v2, v2, v22
	v_lshlrev_b32_e32 v22, 16, v24
	v_mul_f32_e32 v2, v2, v22
	v_mul_f32_e32 v22, v23, v1
	v_mul_f32_e32 v4, v4, v20
	v_lshlrev_b32_e32 v20, 16, v25
	v_mul_f32_e32 v3, v3, v22
	v_and_b32_e32 v22, 0xffff0000, v24
	v_mul_f32_e32 v4, v4, v20
	v_mul_f32_e32 v20, v21, v1
	v_mul_f32_e32 v3, v3, v22
	v_mul_f32_e32 v5, v5, v20
	v_and_b32_e32 v20, 0xffff0000, v25
	v_mul_f32_e32 v5, v5, v20
	s_nop 1
	v_cvt_pk_bf16_f32 v2, v2, v3
	s_nop 1
	v_cvt_pk_bf16_f32 v3, v4, v5
	global_store_dwordx2 v[10:11], v[2:3], off offset:128
	v_mov_b32_e32 v20, v190
	v_mov_b32_e32 v21, v191
	s_nop 0
	v_mov_b32_e32 v2, v120
	v_mov_b32_e32 v3, v121
	v_mov_b32_e32 v4, v122
	v_mov_b32_e32 v5, v123
	v_mul_f32_e32 v2, v2, v18
	v_lshlrev_b32_e32 v18, 16, v20
	v_mul_f32_e32 v2, v2, v18
	v_mul_f32_e32 v18, v19, v1
	v_mul_f32_e32 v4, v4, v16
	v_lshlrev_b32_e32 v16, 16, v21
	v_mul_f32_e32 v3, v3, v18
	v_and_b32_e32 v18, 0xffff0000, v20
	v_mul_f32_e32 v4, v4, v16
	v_mul_f32_e32 v16, v17, v1
	v_mul_f32_e32 v3, v3, v18
	v_mul_f32_e32 v5, v5, v16
	v_and_b32_e32 v16, 0xffff0000, v21
	v_mul_f32_e32 v5, v5, v16
	s_nop 1
	v_cvt_pk_bf16_f32 v2, v2, v3
	s_nop 1
	v_cvt_pk_bf16_f32 v3, v4, v5
	global_store_dwordx2 v[10:11], v[2:3], off offset:160
	v_mov_b32_e32 v16, v192
	v_mov_b32_e32 v17, v193
	s_nop 0
	v_mov_b32_e32 v2, v124
	v_mov_b32_e32 v3, v125
	v_mov_b32_e32 v4, v126
	v_mov_b32_e32 v5, v127
	v_mul_f32_e32 v2, v2, v14
	v_lshlrev_b32_e32 v14, 16, v16
	v_mul_f32_e32 v2, v2, v14
	v_mul_f32_e32 v14, v15, v1
	v_mul_f32_e32 v4, v4, v12
	v_lshlrev_b32_e32 v12, 16, v17
	v_mul_f32_e32 v3, v3, v14
	v_and_b32_e32 v14, 0xffff0000, v16
	v_mul_f32_e32 v4, v4, v12
	v_mul_f32_e32 v12, v13, v1
	v_mul_f32_e32 v3, v3, v14
	v_mul_f32_e32 v5, v5, v12
	v_and_b32_e32 v12, 0xffff0000, v17
	v_mul_f32_e32 v5, v5, v12
	s_nop 1
	v_cvt_pk_bf16_f32 v2, v2, v3
	s_nop 1
	v_cvt_pk_bf16_f32 v3, v4, v5
	global_store_dwordx2 v[10:11], v[2:3], off offset:192
	v_mov_b32_e32 v2, v194
	v_mov_b32_e32 v3, v195
	s_nop 0
	v_mov_b32_e32 v12, v128
	v_mov_b32_e32 v13, v129
	v_mov_b32_e32 v14, v130
	v_mov_b32_e32 v15, v131
	v_mul_f32_e32 v4, v8, v1
	v_lshlrev_b32_e32 v5, 16, v2
	v_mul_f32_e32 v4, v4, v12
	v_mul_f32_e32 v4, v4, v5
	v_mul_f32_e32 v5, v9, v1
	v_mul_f32_e32 v5, v5, v13
	v_and_b32_e32 v2, 0xffff0000, v2
	v_mul_f32_e32 v2, v5, v2
	v_mul_f32_e32 v5, v6, v1
	v_mul_f32_e32 v1, v7, v1
	v_mul_f32_e32 v5, v5, v14
	v_lshlrev_b32_e32 v6, 16, v3
	v_mul_f32_e32 v1, v1, v15
	v_and_b32_e32 v3, 0xffff0000, v3
	v_mul_f32_e32 v5, v5, v6
	v_mul_f32_e32 v1, v1, v3
	s_nop 1
	v_cvt_pk_bf16_f32 v2, v4, v2
	s_nop 1
	v_cvt_pk_bf16_f32 v3, v5, v1
	global_store_dwordx2 v[10:11], v[2:3], off offset:224
	s_barrier

.LBB0_786:
	s_add_i32 s30, s30, 64
	s_cmpk_lg_i32 s6, 0x44
	s_mov_b32 s35, s6
	s_waitcnt lgkmcnt(0)
	s_barrier
	s_cbranch_scc0 .LBB0_840
	s_cmp_eq_u32 s35, 4
	s_cbranch_scc0 .Lctxpub_done
	s_waitcnt vmcnt(0)
	s_barrier
	s_mov_b64 s[100:101], exec
	s_and_b64 exec, exec, s[4:5]
	s_cbranch_execz .Lctxpub_skip
	v_mov_b32_e32 v1, 1
	global_atomic_add v0, v1, s[12:13] offset:2304
.Lctxpub_skip:
	s_mov_b64 exec, s[100:101]
.Lctxpub_done:
.LBB0_787:
	v_cndmask_b32_e64 v1, 0, 1, s[36:37]
	v_cmp_ne_u32_e64 s[84:85], 1, v1
	s_andn2_b64 vcc, exec, s[36:37]
	s_mov_b32 s18, s30
	s_cbranch_vccnz .LBB0_792
	s_lshl_b32 s6, s35, 6
	s_cmp_gt_u32 s35, 3
	s_mov_b64 s[10:11], -1
	s_cbranch_scc0 .LBB0_790
	s_sub_i32 s18, 0x11c0, s6
	s_mov_b64 s[10:11], 0

.LBB0_844:
	s_or_b64 exec, exec, s[10:11]
	s_waitcnt vmcnt(0)
	v_mov_b32_e32 v18, v232
	s_waitcnt vmcnt(0) lgkmcnt(0)
	s_barrier
	s_nop 0
	v_ashrrev_i32_e32 v19, 6, v18
	v_cmp_gt_i32_e32 vcc, 64, v19
	s_and_saveexec_b64 s[10:11], vcc
	s_mov_b64 s[36:37], 0x4000
	s_mov_b64 s[40:41], 0x2200000
	s_cbranch_execz .LBB0_847
	s_load_dwordx2 s[14:15], s[44:45], 0x48
	v_readlane_b32 s26, v255, 32
	v_lshlrev_b32_e32 v1, 6, v18
	v_readlane_b32 s27, v255, 33
	v_and_b32_e32 v1, 0xfc0, v1
	s_waitcnt lgkmcnt(0)
	s_add_u32 s14, s14, s26
	s_addc_u32 s15, s15, s27
	global_load_dwordx4 v[2:5], v1, s[14:15]
	global_load_dwordx4 v[6:9], v1, s[14:15] offset:16
	global_load_dwordx4 v[10:13], v1, s[14:15] offset:32
	global_load_dwordx4 v[14:17], v1, s[14:15] offset:48
	v_readlane_b32 s6, v255, 30
	s_sub_i32 s6, s62, s6
	s_lshr_b32 s14, s6, 6
	s_lshl_b32 s6, s6, 6
	s_mul_i32 s15, s14, 0x1100
	s_and_b32 s6, s6, 0xfc0
	v_cmp_lt_i32_e32 vcc, v231, v225
	s_add_i32 s14, s15, s6
	s_and_b32 s6, s62, 63
	v_cndmask_b32_e32 v1, v223, v231, vcc
	v_cmp_lt_i32_e32 vcc, v230, v225
	s_lshl_b32 s6, s6, 6
	s_add_i32 s6, s6, s15
	v_cndmask_b32_e32 v20, v223, v230, vcc
	v_cmp_lt_i32_e32 vcc, v229, v225
	v_lshlrev_b32_e32 v26, 2, v20
	s_load_dwordx2 s[26:27], s[44:45], 0xb0
	v_cndmask_b32_e32 v20, v223, v229, vcc
	v_cmp_lt_i32_e32 vcc, v222, v225
	v_lshlrev_b32_e32 v27, 2, v20
	v_add_u32_e32 v19, s6, v19
	v_cndmask_b32_e32 v20, v223, v222, vcc
	v_lshlrev_b32_e32 v28, 2, v20
	v_add_u32_e32 v20, 0x100, v19
	v_ashrrev_i32_e32 v21, 31, v20
	v_lshlrev_b64 v[20:21], 11, v[20:21]
	v_and_b32_e32 v18, 63, v18
	v_lshl_or_b32 v20, v18, 5, v20
	v_add_u32_e32 v29, 0xf8, v19
	s_waitcnt lgkmcnt(0)
	v_lshl_add_u64 v[18:19], s[26:27], 0, v[20:21]
	s_mov_b64 s[26:27], 0x25610000
	v_lshlrev_b32_e32 v1, 2, v1
	s_addk_i32 s14, 0x138
	v_lshl_add_u64 v[18:19], v[18:19], 0, s[26:27]
	s_mov_b64 s[26:27], 0
	v_lshl_add_u64 v[62:63], v[18:19], 0, s[40:41]
	global_load_dwordx4 v[100:103], v[18:19], off offset:16
	global_load_dwordx4 v[104:107], v[18:19], off
	global_load_dwordx4 v[108:111], v[62:63], off
	global_load_dwordx4 v[112:115], v[62:63], off offset:16
	v_add_co_u32_e32 v64, vcc, s92, v18
	s_nop 0
	v_addc_co_u32_e32 v65, vcc, -1, v19, vcc
	global_load_dwordx4 v[116:119], v[64:65], off
	v_add_co_u32_e32 v64, vcc, s93, v18
	s_nop 0
	v_addc_co_u32_e32 v65, vcc, -1, v19, vcc
	global_load_dwordx4 v[120:123], v[64:65], off
	v_add_co_u32_e32 v64, vcc, s94, v18
	s_nop 0
	v_addc_co_u32_e32 v65, vcc, -1, v19, vcc
	global_load_dwordx4 v[124:127], v[64:65], off offset:-4080
	v_add_co_u32_e32 v64, vcc, s95, v18
	s_nop 0
	v_addc_co_u32_e32 v65, vcc, -1, v19, vcc
	global_load_dwordx4 v[128:131], v[64:65], off offset:-4080
	s_waitcnt vmcnt(0)
.LBB0_846:
	s_waitcnt vmcnt(2)
	v_mov_b32_e32 v20, v100
	v_mov_b32_e32 v21, v101
	v_mov_b32_e32 v22, v102
	v_mov_b32_e32 v23, v103
	v_mov_b32_e32 v30, v104
	v_mov_b32_e32 v31, v105
	v_mov_b32_e32 v32, v106
	v_mov_b32_e32 v33, v107
	v_mov_b32_e32 v34, v108
	v_mov_b32_e32 v35, v109
	v_mov_b32_e32 v36, v110
	v_mov_b32_e32 v37, v111
	v_mov_b32_e32 v38, v112
	v_mov_b32_e32 v39, v113
	v_mov_b32_e32 v40, v114
	v_mov_b32_e32 v41, v115
	v_mov_b32_e32 v132, v116
	v_mov_b32_e32 v133, v117
	v_mov_b32_e32 v134, v118
	v_mov_b32_e32 v135, v119
	v_mov_b32_e32 v136, v120
	v_mov_b32_e32 v137, v121
	v_mov_b32_e32 v138, v122
	v_mov_b32_e32 v139, v123
	v_mov_b32_e32 v140, v124
	v_mov_b32_e32 v141, v125
	v_mov_b32_e32 v142, v126
	v_mov_b32_e32 v143, v127
	v_mov_b32_e32 v144, v128
	v_mov_b32_e32 v145, v129
	v_mov_b32_e32 v146, v130
	v_mov_b32_e32 v147, v131
	v_lshl_add_u64 v[60:61], v[18:19], 0, s[36:37]
	v_lshl_add_u64 v[62:63], v[60:61], 0, s[40:41]
	global_load_dwordx4 v[100:103], v[60:61], off offset:16
	global_load_dwordx4 v[104:107], v[60:61], off
	global_load_dwordx4 v[108:111], v[62:63], off
	global_load_dwordx4 v[112:115], v[62:63], off offset:16
	v_add_co_u32_e32 v64, vcc, s92, v60
	s_nop 0
	v_addc_co_u32_e32 v65, vcc, -1, v61, vcc
	global_load_dwordx4 v[116:119], v[64:65], off
	v_add_co_u32_e32 v64, vcc, s93, v60
	s_nop 0
	v_addc_co_u32_e32 v65, vcc, -1, v61, vcc
	global_load_dwordx4 v[120:123], v[64:65], off
	v_add_co_u32_e32 v64, vcc, s94, v60
	s_nop 0
	v_addc_co_u32_e32 v65, vcc, -1, v61, vcc
	global_load_dwordx4 v[124:127], v[64:65], off offset:-4080
	v_add_co_u32_e32 v64, vcc, s95, v60
	s_nop 0
	v_addc_co_u32_e32 v65, vcc, -1, v61, vcc
	global_load_dwordx4 v[128:131], v[64:65], off offset:-4080
	v_add_u32_e32 v29, 8, v29
	v_lshlrev_b32_e32 v25, 16, v30
	v_lshlrev_b32_e32 v24, 16, v34
	v_add_f32_e32 v44, v24, v25
	v_and_b32_e32 v24, 0xffff0000, v34
	v_and_b32_e32 v25, 0xffff0000, v30
	v_add_f32_e32 v45, v24, v25
	v_lshlrev_b32_e32 v24, 16, v35
	v_lshlrev_b32_e32 v25, 16, v31
	v_add_f32_e32 v46, v24, v25
	v_and_b32_e32 v24, 0xffff0000, v35
	v_and_b32_e32 v25, 0xffff0000, v31
	v_add_f32_e32 v47, v24, v25
	v_lshlrev_b32_e32 v24, 16, v36
	v_lshlrev_b32_e32 v25, 16, v32
	v_add_f32_e32 v48, v24, v25
	v_and_b32_e32 v24, 0xffff0000, v36
	v_and_b32_e32 v25, 0xffff0000, v32
	v_add_f32_e32 v49, v24, v25
	v_lshlrev_b32_e32 v24, 16, v37
	v_lshlrev_b32_e32 v25, 16, v33
	v_add_f32_e32 v50, v24, v25
	v_and_b32_e32 v24, 0xffff0000, v37
	v_and_b32_e32 v25, 0xffff0000, v33
	v_add_f32_e32 v51, v24, v25
	v_lshlrev_b32_e32 v24, 16, v20
	v_lshlrev_b32_e32 v25, 16, v38
	v_add_f32_e32 v31, v25, v24
	v_and_b32_e32 v24, 0xffff0000, v38
	v_and_b32_e32 v20, 0xffff0000, v20
	v_add_f32_e32 v30, v24, v20
	v_lshlrev_b32_e32 v25, 16, v21
	v_lshlrev_b32_e32 v33, 16, v39
	v_and_b32_e32 v32, 0xffff0000, v39
	v_and_b32_e32 v24, 0xffff0000, v21
	v_lshlrev_b32_e32 v21, 16, v22
	v_lshlrev_b32_e32 v35, 16, v40
	v_and_b32_e32 v34, 0xffff0000, v40
	v_and_b32_e32 v20, 0xffff0000, v22
	v_lshlrev_b32_e32 v37, 16, v23
	v_lshlrev_b32_e32 v39, 16, v41
	v_and_b32_e32 v38, 0xffff0000, v41
	v_and_b32_e32 v36, 0xffff0000, v23
	v_pk_add_f32 v[22:23], v[20:21], v[34:35]
	v_pk_add_f32 v[20:21], v[36:37], v[38:39]
	v_mul_f32_e32 v38, v44, v44
	v_fmac_f32_e32 v38, v45, v45
	v_fmac_f32_e32 v38, v46, v46
	v_fmac_f32_e32 v38, v47, v47
	v_fmac_f32_e32 v38, v48, v48
	v_fmac_f32_e32 v38, v49, v49
	v_fmac_f32_e32 v38, v50, v50
	v_fmac_f32_e32 v38, v51, v51
	v_pk_add_f32 v[24:25], v[24:25], v[32:33]
	v_fmac_f32_e32 v38, v31, v31
	v_pk_mul_f32 v[32:33], v[24:25], v[24:25]
	v_fmac_f32_e32 v38, v30, v30
	v_add_f32_e32 v33, v33, v38
	v_pk_mul_f32 v[34:35], v[22:23], v[22:23]
	v_add_f32_e32 v32, v32, v33
	v_add_f32_e32 v32, v35, v32
	v_pk_mul_f32 v[36:37], v[20:21], v[20:21]
	v_add_f32_e32 v32, v34, v32
	v_add_f32_e32 v32, v37, v32
	v_add_f32_e32 v32, v36, v32
	ds_bpermute_b32 v33, v1, v32
	s_waitcnt lgkmcnt(0)
	v_add_f32_e32 v32, v32, v33
	ds_bpermute_b32 v33, v26, v32
	s_waitcnt lgkmcnt(0)
	v_add_f32_e32 v32, v32, v33
	ds_bpermute_b32 v33, v27, v32
	s_waitcnt lgkmcnt(0)
	v_add_f32_e32 v32, v32, v33
	ds_bpermute_b32 v33, v28, v32
	s_waitcnt lgkmcnt(0)
	v_add_f32_e32 v32, v32, v33
	v_fmamk_f32 v32, v32, 0x3b800000, v234
	v_cmp_gt_f32_e32 vcc, s90, v32
	v_mul_f32_e32 v33, 0x4b800000, v32
	s_nop 0
	v_cndmask_b32_e32 v32, v32, v33, vcc
	v_rsq_f32_e32 v32, v32
	s_nop 0
	v_mul_f32_e32 v33, 0x45800000, v32
	v_cndmask_b32_e32 v32, v32, v33, vcc
	v_add_co_u32_e32 v42, vcc, s92, v18
	v_mul_f32_e32 v33, v44, v32
	s_nop 0
	v_addc_co_u32_e32 v43, vcc, -1, v19, vcc
	v_add_co_u32_e32 v38, vcc, s93, v18
	v_mov_b32_e32 v34, v132
	v_mov_b32_e32 v35, v133
	v_mov_b32_e32 v36, v134
	v_mov_b32_e32 v37, v135
	s_nop 0
	v_addc_co_u32_e32 v39, vcc, -1, v19, vcc
	v_mov_b32_e32 v38, v136
	v_mov_b32_e32 v39, v137
	v_mov_b32_e32 v40, v138
	v_mov_b32_e32 v41, v139
	v_mul_f32_e32 v33, v2, v33
	v_mul_f32_e32 v31, v31, v32
	v_mul_f32_e32 v31, v10, v31
	v_mul_f32_e32 v30, v30, v32
	v_mul_f32_e32 v30, v11, v30
	v_mul_f32_e32 v25, v25, v32
	v_mul_f32_e32 v25, v12, v25
	v_mul_f32_e32 v24, v24, v32
	v_mul_f32_e32 v24, v13, v24
	v_mul_f32_e32 v23, v23, v32
	v_mul_f32_e32 v23, v14, v23
	v_mul_f32_e32 v22, v22, v32
	v_mul_f32_e32 v22, v15, v22
	v_mul_f32_e32 v21, v21, v32
	v_mul_f32_e32 v21, v16, v21
	v_mul_f32_e32 v20, v20, v32
	v_mul_f32_e32 v20, v17, v20
	v_lshlrev_b32_e32 v44, 16, v34
	v_mul_f32_e32 v33, v33, v44
	v_and_b32_e32 v34, 0xffff0000, v34
	v_lshlrev_b32_e32 v44, 16, v38
	v_mul_f32_e32 v33, v33, v44
	v_mul_f32_e32 v44, v45, v32
	v_mul_f32_e32 v44, v3, v44
	v_mul_f32_e32 v34, v44, v34
	v_and_b32_e32 v38, 0xffff0000, v38
	v_mul_f32_e32 v34, v34, v38
	s_nop 1
	v_cvt_pk_bf16_f32 v34, v33, v34
	v_mul_f32_e32 v33, v46, v32
	v_mul_f32_e32 v33, v4, v33
	v_lshlrev_b32_e32 v38, 16, v35
	v_mul_f32_e32 v33, v33, v38
	v_lshlrev_b32_e32 v38, 16, v39
	v_mul_f32_e32 v33, v33, v38
	v_mul_f32_e32 v38, v47, v32
	v_mul_f32_e32 v38, v5, v38
	v_and_b32_e32 v35, 0xffff0000, v35
	v_mul_f32_e32 v35, v38, v35
	v_and_b32_e32 v38, 0xffff0000, v39
	v_mul_f32_e32 v35, v35, v38
	s_nop 1
	v_cvt_pk_bf16_f32 v35, v33, v35
	v_mul_f32_e32 v33, v48, v32
	v_mul_f32_e32 v33, v6, v33
	v_lshlrev_b32_e32 v38, 16, v36
	v_mul_f32_e32 v33, v33, v38
	v_lshlrev_b32_e32 v38, 16, v40
	v_mul_f32_e32 v33, v33, v38
	v_mul_f32_e32 v38, v49, v32
	v_mul_f32_e32 v38, v7, v38
	v_and_b32_e32 v36, 0xffff0000, v36
	v_mul_f32_e32 v36, v38, v36
	v_and_b32_e32 v38, 0xffff0000, v40
	v_mul_f32_e32 v36, v36, v38
	s_nop 1
	v_cvt_pk_bf16_f32 v36, v33, v36
	v_mul_f32_e32 v33, v50, v32
	v_mul_f32_e32 v33, v8, v33
	v_lshlrev_b32_e32 v38, 16, v37
	v_mul_f32_e32 v33, v33, v38
	v_lshlrev_b32_e32 v38, 16, v41
	v_mul_f32_e32 v33, v33, v38
	v_mul_f32_e32 v38, v51, v32
	v_mul_f32_e32 v38, v9, v38
	v_and_b32_e32 v37, 0xffff0000, v37
	v_mul_f32_e32 v37, v38, v37
	v_and_b32_e32 v38, 0xffff0000, v41
	v_mul_f32_e32 v37, v37, v38
	s_nop 1
	v_cvt_pk_bf16_f32 v37, v33, v37
	global_store_dwordx4 v[42:43], v[34:37], off
	v_add_co_u32_e32 v42, vcc, s94, v18
	s_nop 1
	v_addc_co_u32_e32 v43, vcc, -1, v19, vcc
	v_add_co_u32_e32 v38, vcc, s95, v18
	v_mov_b32_e32 v34, v140
	v_mov_b32_e32 v35, v141
	v_mov_b32_e32 v36, v142
	v_mov_b32_e32 v37, v143
	s_nop 0
	v_addc_co_u32_e32 v39, vcc, -1, v19, vcc
	v_mov_b32_e32 v38, v144
	v_mov_b32_e32 v39, v145
	v_mov_b32_e32 v40, v146
	v_mov_b32_e32 v41, v147
	v_cmp_le_i32_e32 vcc, s14, v29
	v_lshl_add_u64 v[18:19], v[18:19], 0, s[36:37]
	s_or_b64 s[26:27], vcc, s[26:27]
	v_lshlrev_b32_e32 v33, 16, v34
	v_mul_f32_e32 v31, v31, v33
	v_lshlrev_b32_e32 v33, 16, v38
	v_mul_f32_e32 v31, v31, v33
	v_and_b32_e32 v33, 0xffff0000, v34
	v_mul_f32_e32 v30, v30, v33
	v_and_b32_e32 v33, 0xffff0000, v38
	v_mul_f32_e32 v30, v30, v33
	s_nop 1
	v_cvt_pk_bf16_f32 v34, v31, v30
	v_lshlrev_b32_e32 v30, 16, v35
	v_mul_f32_e32 v25, v25, v30
	v_lshlrev_b32_e32 v30, 16, v39
	v_mul_f32_e32 v25, v25, v30
	v_and_b32_e32 v30, 0xffff0000, v35
	v_mul_f32_e32 v24, v24, v30
	v_and_b32_e32 v30, 0xffff0000, v39
	v_mul_f32_e32 v24, v24, v30
	s_nop 1
	v_cvt_pk_bf16_f32 v35, v25, v24
	v_lshlrev_b32_e32 v24, 16, v36
	v_mul_f32_e32 v23, v23, v24
	v_lshlrev_b32_e32 v24, 16, v40
	v_mul_f32_e32 v23, v23, v24
	v_and_b32_e32 v24, 0xffff0000, v36
	v_mul_f32_e32 v22, v22, v24
	v_and_b32_e32 v24, 0xffff0000, v40
	v_mul_f32_e32 v22, v22, v24
	s_nop 1
	v_cvt_pk_bf16_f32 v36, v23, v22
	v_lshlrev_b32_e32 v22, 16, v37
	v_mul_f32_e32 v21, v21, v22
	v_lshlrev_b32_e32 v22, 16, v41
	v_mul_f32_e32 v21, v21, v22
	v_and_b32_e32 v22, 0xffff0000, v37
	v_mul_f32_e32 v20, v20, v22
	v_and_b32_e32 v22, 0xffff0000, v41
	v_mul_f32_e32 v20, v20, v22
	s_nop 1
	v_cvt_pk_bf16_f32 v37, v21, v20
	global_store_dwordx4 v[42:43], v[34:37], off offset:-4080
	s_andn2_b64 exec, exec, s[26:27]
	s_cbranch_execnz .LBB0_846
.LBB0_847:
	s_or_b64 exec, exec, s[10:11]
	s_waitcnt vmcnt(0)
	s_cbranch_execz .LBB0_532
	s_branch .LBB0_553

.LBB0_918:
	v_lshl_add_u32 v1, s18, 8, v166
	s_lshl_b32 s64, s71, 10
	v_mov_b64_e32 v[160:161], s[50:51]
	v_lshl_or_b32 v2, s6, 8, v168
	s_ashr_i32 s65, s64, 31
	v_mad_i64_i32 v[160:161], s[10:11], v1, s17, v[160:161]
	v_ashrrev_i32_e32 v3, 31, v2
	v_lshl_add_u64 v[160:161], s[64:65], 1, v[160:161]
	v_mov_b32_e32 v162, v1
	v_ashrrev_i32_e32 v163, 31, v1
	v_lshl_add_u64 v[160:161], v[2:3], 1, v[160:161]
	v_lshlrev_b64 v[162:163], 11, v[162:163]
	s_lshl_b32 s14, s17, 4
	s_mov_b32 s15, 0
	v_lshl_add_u64 v[162:163], s[52:53], 0, v[162:163]
	s_cmp_lt_i32 s71, 2
	v_lshl_add_u64 v[162:163], v[2:3], 1, v[162:163]
	s_cbranch_scc0 .Lm1_final
	global_load_dwordx4 v[170:173], v[160:161], off
	global_load_dwordx4 v[174:177], v[160:161], off offset:2048
	global_load_dwordx4 v[178:181], v[160:161], off offset:256
	global_load_dwordx4 v[182:185], v[160:161], off offset:2304
	v_lshl_add_u64 v[160:161], s[14:15], 0, v[160:161]
	global_load_dwordx4 v[186:189], v[160:161], off
	global_load_dwordx4 v[190:193], v[160:161], off offset:2048
	global_load_dwordx4 v[194:197], v[160:161], off offset:256
	global_load_dwordx4 v[198:201], v[160:161], off offset:2304
	v_lshl_add_u64 v[160:161], s[14:15], 0, v[160:161]
	global_load_dwordx4 v[202:205], v[160:161], off
	global_load_dwordx4 v[206:209], v[160:161], off offset:2048
	global_load_dwordx4 v[210:213], v[160:161], off offset:256
	global_load_dwordx4 v[214:217], v[160:161], off offset:2304
	v_lshl_add_u64 v[160:161], s[14:15], 0, v[160:161]
	global_load_dwordx4 v[146:149], v[160:161], off
	global_load_dwordx4 v[150:153], v[160:161], off offset:2048
	s_waitcnt vmcnt(12)
	v_lshlrev_b32_e32 v132, 16, v174
	v_and_b32_e32 v133, 0xffff0000, v174
	v_lshlrev_b32_e32 v134, 16, v175
	v_and_b32_e32 v135, 0xffff0000, v175
	v_lshlrev_b32_e32 v136, 16, v176
	v_and_b32_e32 v137, 0xffff0000, v176
	v_lshlrev_b32_e32 v138, 16, v177
	v_and_b32_e32 v139, 0xffff0000, v177
	v_max_f32_e32 v132, 0xda24260, v132
	v_max_f32_e32 v133, 0xda24260, v133
	v_max_f32_e32 v134, 0xda24260, v134
	v_max_f32_e32 v135, 0xda24260, v135
	v_max_f32_e32 v136, 0xda24260, v136
	v_max_f32_e32 v137, 0xda24260, v137
	v_max_f32_e32 v138, 0xda24260, v138
	v_max_f32_e32 v139, 0xda24260, v139
	v_rcp_f32_e32 v132, v132
	v_rcp_f32_e32 v133, v133
	v_rcp_f32_e32 v134, v134
	v_rcp_f32_e32 v135, v135
	v_rcp_f32_e32 v136, v136
	v_rcp_f32_e32 v137, v137
	v_rcp_f32_e32 v138, v138
	v_rcp_f32_e32 v139, v139
	v_lshlrev_b32_e32 v174, 16, v170
	v_and_b32_e32 v170, 0xffff0000, v170
	v_lshlrev_b32_e32 v175, 16, v171
	v_and_b32_e32 v171, 0xffff0000, v171
	v_lshlrev_b32_e32 v176, 16, v172
	v_and_b32_e32 v172, 0xffff0000, v172
	v_lshlrev_b32_e32 v177, 16, v173
	v_and_b32_e32 v173, 0xffff0000, v173
	v_mul_f32_e32 v174, v132, v174
	v_mul_f32_e32 v170, v133, v170
	v_mul_f32_e32 v175, v134, v175
	v_mul_f32_e32 v171, v135, v171
	v_mul_f32_e32 v176, v136, v176
	v_mul_f32_e32 v172, v137, v172
	v_mul_f32_e32 v177, v138, v177
	v_mul_f32_e32 v173, v139, v173
	v_mul_f32_e32 v128, v128, v174
	v_mul_f32_e32 v129, v129, v170
	v_mul_f32_e32 v130, v130, v175
	v_mul_f32_e32 v131, v131, v171
	v_mul_f32_e32 v124, v124, v176
	v_mul_f32_e32 v125, v125, v172
	v_mul_f32_e32 v126, v126, v177
	v_mul_f32_e32 v127, v127, v173
	global_load_dwordx4 v[170:173], v[160:161], off offset:256
	global_load_dwordx4 v[174:177], v[160:161], off offset:2304
	s_waitcnt vmcnt(12)
	v_lshlrev_b32_e32 v132, 16, v182
	v_and_b32_e32 v133, 0xffff0000, v182
	v_lshlrev_b32_e32 v134, 16, v183
	v_and_b32_e32 v135, 0xffff0000, v183
	v_lshlrev_b32_e32 v136, 16, v184
	v_and_b32_e32 v137, 0xffff0000, v184
	v_lshlrev_b32_e32 v138, 16, v185
	v_and_b32_e32 v139, 0xffff0000, v185
	v_max_f32_e32 v132, 0xda24260, v132
	v_max_f32_e32 v133, 0xda24260, v133
	v_max_f32_e32 v134, 0xda24260, v134
	v_max_f32_e32 v135, 0xda24260, v135
	v_max_f32_e32 v136, 0xda24260, v136
	v_max_f32_e32 v137, 0xda24260, v137
	v_max_f32_e32 v138, 0xda24260, v138
	v_max_f32_e32 v139, 0xda24260, v139
	v_rcp_f32_e32 v132, v132
	v_rcp_f32_e32 v133, v133
	v_rcp_f32_e32 v134, v134
	v_rcp_f32_e32 v135, v135
	v_rcp_f32_e32 v136, v136
	v_rcp_f32_e32 v137, v137
	v_rcp_f32_e32 v138, v138
	v_rcp_f32_e32 v139, v139
	v_lshlrev_b32_e32 v182, 16, v178
	v_and_b32_e32 v178, 0xffff0000, v178
	v_lshlrev_b32_e32 v183, 16, v179
	v_and_b32_e32 v179, 0xffff0000, v179
	v_lshlrev_b32_e32 v184, 16, v180
	v_and_b32_e32 v180, 0xffff0000, v180
	v_lshlrev_b32_e32 v185, 16, v181
	v_and_b32_e32 v181, 0xffff0000, v181
	v_mul_f32_e32 v182, v132, v182
	v_mul_f32_e32 v178, v133, v178
	v_mul_f32_e32 v183, v134, v183
	v_mul_f32_e32 v179, v135, v179
	v_mul_f32_e32 v184, v136, v184
	v_mul_f32_e32 v180, v137, v180
	v_mul_f32_e32 v185, v138, v185
	v_mul_f32_e32 v181, v139, v181
	v_mul_f32_e32 v96, v96, v182
	v_mul_f32_e32 v97, v97, v178
	v_mul_f32_e32 v98, v98, v183
	v_mul_f32_e32 v99, v99, v179
	v_mul_f32_e32 v92, v92, v184
	v_mul_f32_e32 v93, v93, v180
	v_mul_f32_e32 v94, v94, v185
	v_mul_f32_e32 v95, v95, v181
	v_lshl_add_u64 v[160:161], s[14:15], 0, v[160:161]
	v_lshl_add_u64 v[160:161], s[14:15], 0, v[160:161]
	v_lshl_add_u64 v[160:161], s[14:15], 0, v[160:161]
	v_lshl_add_u64 v[160:161], s[14:15], 0, v[160:161]
	v_lshl_add_u64 v[160:161], s[14:15], 0, v[160:161]
	global_load_dwordx4 v[178:181], v[160:161], off
	global_load_dwordx4 v[182:185], v[160:161], off offset:2048
	s_waitcnt vmcnt(12)
	v_lshlrev_b32_e32 v132, 16, v190
	v_and_b32_e32 v133, 0xffff0000, v190
	v_lshlrev_b32_e32 v134, 16, v191
	v_and_b32_e32 v135, 0xffff0000, v191
	v_lshlrev_b32_e32 v136, 16, v192
	v_and_b32_e32 v137, 0xffff0000, v192
	v_lshlrev_b32_e32 v138, 16, v193
	v_and_b32_e32 v139, 0xffff0000, v193
	v_max_f32_e32 v132, 0xda24260, v132
	v_max_f32_e32 v133, 0xda24260, v133
	v_max_f32_e32 v134, 0xda24260, v134
	v_max_f32_e32 v135, 0xda24260, v135
	v_max_f32_e32 v136, 0xda24260, v136
	v_max_f32_e32 v137, 0xda24260, v137
	v_max_f32_e32 v138, 0xda24260, v138
	v_max_f32_e32 v139, 0xda24260, v139
	v_rcp_f32_e32 v132, v132
	v_rcp_f32_e32 v133, v133
	v_rcp_f32_e32 v134, v134
	v_rcp_f32_e32 v135, v135
	v_rcp_f32_e32 v136, v136
	v_rcp_f32_e32 v137, v137
	v_rcp_f32_e32 v138, v138
	v_rcp_f32_e32 v139, v139
	v_lshlrev_b32_e32 v190, 16, v186
	v_and_b32_e32 v186, 0xffff0000, v186
	v_lshlrev_b32_e32 v191, 16, v187
	v_and_b32_e32 v187, 0xffff0000, v187
	v_lshlrev_b32_e32 v192, 16, v188
	v_and_b32_e32 v188, 0xffff0000, v188
	v_lshlrev_b32_e32 v193, 16, v189
	v_and_b32_e32 v189, 0xffff0000, v189
	v_mul_f32_e32 v190, v132, v190
	v_mul_f32_e32 v186, v133, v186
	v_mul_f32_e32 v191, v134, v191
	v_mul_f32_e32 v187, v135, v187
	v_mul_f32_e32 v192, v136, v192
	v_mul_f32_e32 v188, v137, v188
	v_mul_f32_e32 v193, v138, v193
	v_mul_f32_e32 v189, v139, v189
	v_mul_f32_e32 v120, v120, v190
	v_mul_f32_e32 v121, v121, v186
	v_mul_f32_e32 v122, v122, v191
	v_mul_f32_e32 v123, v123, v187
	v_mul_f32_e32 v116, v116, v192
	v_mul_f32_e32 v117, v117, v188
	v_mul_f32_e32 v118, v118, v193
	v_mul_f32_e32 v119, v119, v189
	global_load_dwordx4 v[186:189], v[160:161], off offset:256
	global_load_dwordx4 v[190:193], v[160:161], off offset:2304
	s_waitcnt vmcnt(12)
	v_lshlrev_b32_e32 v132, 16, v198
	v_and_b32_e32 v133, 0xffff0000, v198
	v_lshlrev_b32_e32 v134, 16, v199
	v_and_b32_e32 v135, 0xffff0000, v199
	v_lshlrev_b32_e32 v136, 16, v200
	v_and_b32_e32 v137, 0xffff0000, v200
	v_lshlrev_b32_e32 v138, 16, v201
	v_and_b32_e32 v139, 0xffff0000, v201
	v_max_f32_e32 v132, 0xda24260, v132
	v_max_f32_e32 v133, 0xda24260, v133
	v_max_f32_e32 v134, 0xda24260, v134
	v_max_f32_e32 v135, 0xda24260, v135
	v_max_f32_e32 v136, 0xda24260, v136
	v_max_f32_e32 v137, 0xda24260, v137
	v_max_f32_e32 v138, 0xda24260, v138
	v_max_f32_e32 v139, 0xda24260, v139
	v_rcp_f32_e32 v132, v132
	v_rcp_f32_e32 v133, v133
	v_rcp_f32_e32 v134, v134
	v_rcp_f32_e32 v135, v135
	v_rcp_f32_e32 v136, v136
	v_rcp_f32_e32 v137, v137
	v_rcp_f32_e32 v138, v138
	v_rcp_f32_e32 v139, v139
	v_lshlrev_b32_e32 v198, 16, v194
	v_and_b32_e32 v194, 0xffff0000, v194
	v_lshlrev_b32_e32 v199, 16, v195
	v_and_b32_e32 v195, 0xffff0000, v195
	v_lshlrev_b32_e32 v200, 16, v196
	v_and_b32_e32 v196, 0xffff0000, v196
	v_lshlrev_b32_e32 v201, 16, v197
	v_and_b32_e32 v197, 0xffff0000, v197
	v_mul_f32_e32 v198, v132, v198
	v_mul_f32_e32 v194, v133, v194
	v_mul_f32_e32 v199, v134, v199
	v_mul_f32_e32 v195, v135, v195
	v_mul_f32_e32 v200, v136, v200
	v_mul_f32_e32 v196, v137, v196
	v_mul_f32_e32 v201, v138, v201
	v_mul_f32_e32 v197, v139, v197
	v_mul_f32_e32 v88, v88, v198
	v_mul_f32_e32 v89, v89, v194
	v_mul_f32_e32 v90, v90, v199
	v_mul_f32_e32 v91, v91, v195
	v_mul_f32_e32 v84, v84, v200
	v_mul_f32_e32 v85, v85, v196
	v_mul_f32_e32 v86, v86, v201
	v_mul_f32_e32 v87, v87, v197
	v_lshl_add_u64 v[160:161], s[14:15], 0, v[160:161]
	global_load_dwordx4 v[194:197], v[160:161], off
	global_load_dwordx4 v[198:201], v[160:161], off offset:2048
	s_waitcnt vmcnt(12)
	v_lshlrev_b32_e32 v132, 16, v206
	v_and_b32_e32 v133, 0xffff0000, v206
	v_lshlrev_b32_e32 v134, 16, v207
	v_and_b32_e32 v135, 0xffff0000, v207
	v_lshlrev_b32_e32 v136, 16, v208
	v_and_b32_e32 v137, 0xffff0000, v208
	v_lshlrev_b32_e32 v138, 16, v209
	v_and_b32_e32 v139, 0xffff0000, v209
	v_max_f32_e32 v132, 0xda24260, v132
	v_max_f32_e32 v133, 0xda24260, v133
	v_max_f32_e32 v134, 0xda24260, v134
	v_max_f32_e32 v135, 0xda24260, v135
	v_max_f32_e32 v136, 0xda24260, v136
	v_max_f32_e32 v137, 0xda24260, v137
	v_max_f32_e32 v138, 0xda24260, v138
	v_max_f32_e32 v139, 0xda24260, v139
	v_rcp_f32_e32 v132, v132
	v_rcp_f32_e32 v133, v133
	v_rcp_f32_e32 v134, v134
	v_rcp_f32_e32 v135, v135
	v_rcp_f32_e32 v136, v136
	v_rcp_f32_e32 v137, v137
	v_rcp_f32_e32 v138, v138
	v_rcp_f32_e32 v139, v139
	v_lshlrev_b32_e32 v206, 16, v202
	v_and_b32_e32 v202, 0xffff0000, v202
	v_lshlrev_b32_e32 v207, 16, v203
	v_and_b32_e32 v203, 0xffff0000, v203
	v_lshlrev_b32_e32 v208, 16, v204
	v_and_b32_e32 v204, 0xffff0000, v204
	v_lshlrev_b32_e32 v209, 16, v205
	v_and_b32_e32 v205, 0xffff0000, v205
	v_mul_f32_e32 v206, v132, v206
	v_mul_f32_e32 v202, v133, v202
	v_mul_f32_e32 v207, v134, v207
	v_mul_f32_e32 v203, v135, v203
	v_mul_f32_e32 v208, v136, v208
	v_mul_f32_e32 v204, v137, v204
	v_mul_f32_e32 v209, v138, v209
	v_mul_f32_e32 v205, v139, v205
	v_mul_f32_e32 v112, v112, v206
	v_mul_f32_e32 v113, v113, v202
	v_mul_f32_e32 v114, v114, v207
	v_mul_f32_e32 v115, v115, v203
	v_mul_f32_e32 v108, v108, v208
	v_mul_f32_e32 v109, v109, v204
	v_mul_f32_e32 v110, v110, v209
	v_mul_f32_e32 v111, v111, v205
	global_load_dwordx4 v[202:205], v[160:161], off offset:256
	global_load_dwordx4 v[206:209], v[160:161], off offset:2304
	s_waitcnt vmcnt(12)
	v_lshlrev_b32_e32 v132, 16, v214
	v_and_b32_e32 v133, 0xffff0000, v214
	v_lshlrev_b32_e32 v134, 16, v215
	v_and_b32_e32 v135, 0xffff0000, v215
	v_lshlrev_b32_e32 v136, 16, v216
	v_and_b32_e32 v137, 0xffff0000, v216
	v_lshlrev_b32_e32 v138, 16, v217
	v_and_b32_e32 v139, 0xffff0000, v217
	v_max_f32_e32 v132, 0xda24260, v132
	v_max_f32_e32 v133, 0xda24260, v133
	v_max_f32_e32 v134, 0xda24260, v134
	v_max_f32_e32 v135, 0xda24260, v135
	v_max_f32_e32 v136, 0xda24260, v136
	v_max_f32_e32 v137, 0xda24260, v137
	v_max_f32_e32 v138, 0xda24260, v138
	v_max_f32_e32 v139, 0xda24260, v139
	v_rcp_f32_e32 v132, v132
	v_rcp_f32_e32 v133, v133
	v_rcp_f32_e32 v134, v134
	v_rcp_f32_e32 v135, v135
	v_rcp_f32_e32 v136, v136
	v_rcp_f32_e32 v137, v137
	v_rcp_f32_e32 v138, v138
	v_rcp_f32_e32 v139, v139
	v_lshlrev_b32_e32 v214, 16, v210
	v_and_b32_e32 v210, 0xffff0000, v210
	v_lshlrev_b32_e32 v215, 16, v211
	v_and_b32_e32 v211, 0xffff0000, v211
	v_lshlrev_b32_e32 v216, 16, v212
	v_and_b32_e32 v212, 0xffff0000, v212
	v_lshlrev_b32_e32 v217, 16, v213
	v_and_b32_e32 v213, 0xffff0000, v213
	v_mul_f32_e32 v214, v132, v214
	v_mul_f32_e32 v210, v133, v210
	v_mul_f32_e32 v215, v134, v215
	v_mul_f32_e32 v211, v135, v211
	v_mul_f32_e32 v216, v136, v216
	v_mul_f32_e32 v212, v137, v212
	v_mul_f32_e32 v217, v138, v217
	v_mul_f32_e32 v213, v139, v213
	v_mul_f32_e32 v80, v80, v214
	v_mul_f32_e32 v81, v81, v210
	v_mul_f32_e32 v82, v82, v215
	v_mul_f32_e32 v83, v83, v211
	v_mul_f32_e32 v76, v76, v216
	v_mul_f32_e32 v77, v77, v212
	v_mul_f32_e32 v78, v78, v217
	v_mul_f32_e32 v79, v79, v213
	v_lshl_add_u64 v[160:161], s[14:15], 0, v[160:161]
	global_load_dwordx4 v[210:213], v[160:161], off
	global_load_dwordx4 v[214:217], v[160:161], off offset:2048
	s_waitcnt vmcnt(12)
	v_lshlrev_b32_e32 v132, 16, v150
	v_and_b32_e32 v133, 0xffff0000, v150
	v_lshlrev_b32_e32 v134, 16, v151
	v_and_b32_e32 v135, 0xffff0000, v151
	v_lshlrev_b32_e32 v136, 16, v152
	v_and_b32_e32 v137, 0xffff0000, v152
	v_lshlrev_b32_e32 v138, 16, v153
	v_and_b32_e32 v139, 0xffff0000, v153
	v_max_f32_e32 v132, 0xda24260, v132
	v_max_f32_e32 v133, 0xda24260, v133
	v_max_f32_e32 v134, 0xda24260, v134
	v_max_f32_e32 v135, 0xda24260, v135
	v_max_f32_e32 v136, 0xda24260, v136
	v_max_f32_e32 v137, 0xda24260, v137
	v_max_f32_e32 v138, 0xda24260, v138
	v_max_f32_e32 v139, 0xda24260, v139
	v_rcp_f32_e32 v132, v132
	v_rcp_f32_e32 v133, v133
	v_rcp_f32_e32 v134, v134
	v_rcp_f32_e32 v135, v135
	v_rcp_f32_e32 v136, v136
	v_rcp_f32_e32 v137, v137
	v_rcp_f32_e32 v138, v138
	v_rcp_f32_e32 v139, v139
	v_lshlrev_b32_e32 v150, 16, v146
	v_and_b32_e32 v146, 0xffff0000, v146
	v_lshlrev_b32_e32 v151, 16, v147
	v_and_b32_e32 v147, 0xffff0000, v147
	v_lshlrev_b32_e32 v152, 16, v148
	v_and_b32_e32 v148, 0xffff0000, v148
	v_lshlrev_b32_e32 v153, 16, v149
	v_and_b32_e32 v149, 0xffff0000, v149
	v_mul_f32_e32 v150, v132, v150
	v_mul_f32_e32 v146, v133, v146
	v_mul_f32_e32 v151, v134, v151
	v_mul_f32_e32 v147, v135, v147
	v_mul_f32_e32 v152, v136, v152
	v_mul_f32_e32 v148, v137, v148
	v_mul_f32_e32 v153, v138, v153
	v_mul_f32_e32 v149, v139, v149
	v_mul_f32_e32 v104, v104, v150
	v_mul_f32_e32 v105, v105, v146
	v_mul_f32_e32 v106, v106, v151
	v_mul_f32_e32 v107, v107, v147
	v_mul_f32_e32 v100, v100, v152
	v_mul_f32_e32 v101, v101, v148
	v_mul_f32_e32 v102, v102, v153
	v_mul_f32_e32 v103, v103, v149
	global_load_dwordx4 v[146:149], v[160:161], off offset:256
	global_load_dwordx4 v[150:153], v[160:161], off offset:2304
	s_waitcnt vmcnt(12)
	v_lshlrev_b32_e32 v132, 16, v174
	v_and_b32_e32 v133, 0xffff0000, v174
	v_lshlrev_b32_e32 v134, 16, v175
	v_and_b32_e32 v135, 0xffff0000, v175
	v_lshlrev_b32_e32 v136, 16, v176
	v_and_b32_e32 v137, 0xffff0000, v176
	v_lshlrev_b32_e32 v138, 16, v177
	v_and_b32_e32 v139, 0xffff0000, v177
	v_max_f32_e32 v132, 0xda24260, v132
	v_max_f32_e32 v133, 0xda24260, v133
	v_max_f32_e32 v134, 0xda24260, v134
	v_max_f32_e32 v135, 0xda24260, v135
	v_max_f32_e32 v136, 0xda24260, v136
	v_max_f32_e32 v137, 0xda24260, v137
	v_max_f32_e32 v138, 0xda24260, v138
	v_max_f32_e32 v139, 0xda24260, v139
	v_rcp_f32_e32 v132, v132
	v_rcp_f32_e32 v133, v133
	v_rcp_f32_e32 v134, v134
	v_rcp_f32_e32 v135, v135
	v_rcp_f32_e32 v136, v136
	v_rcp_f32_e32 v137, v137
	v_rcp_f32_e32 v138, v138
	v_rcp_f32_e32 v139, v139
	v_lshlrev_b32_e32 v174, 16, v170
	v_and_b32_e32 v170, 0xffff0000, v170
	v_lshlrev_b32_e32 v175, 16, v171
	v_and_b32_e32 v171, 0xffff0000, v171
	v_lshlrev_b32_e32 v176, 16, v172
	v_and_b32_e32 v172, 0xffff0000, v172
	v_lshlrev_b32_e32 v177, 16, v173
	v_and_b32_e32 v173, 0xffff0000, v173
	v_mul_f32_e32 v174, v132, v174
	v_mul_f32_e32 v170, v133, v170
	v_mul_f32_e32 v175, v134, v175
	v_mul_f32_e32 v171, v135, v171
	v_mul_f32_e32 v176, v136, v176
	v_mul_f32_e32 v172, v137, v172
	v_mul_f32_e32 v177, v138, v177
	v_mul_f32_e32 v173, v139, v173
	v_mul_f32_e32 v72, v72, v174
	v_mul_f32_e32 v73, v73, v170
	v_mul_f32_e32 v74, v74, v175
	v_mul_f32_e32 v75, v75, v171
	v_mul_f32_e32 v68, v68, v176
	v_mul_f32_e32 v69, v69, v172
	v_mul_f32_e32 v70, v70, v177
	v_mul_f32_e32 v71, v71, v173
	v_lshl_add_u64 v[160:161], s[14:15], 0, v[160:161]
	global_load_dwordx4 v[170:173], v[160:161], off
	global_load_dwordx4 v[174:177], v[160:161], off offset:2048
	s_waitcnt vmcnt(12)
	v_lshlrev_b32_e32 v132, 16, v182
	v_and_b32_e32 v133, 0xffff0000, v182
	v_lshlrev_b32_e32 v134, 16, v183
	v_and_b32_e32 v135, 0xffff0000, v183
	v_lshlrev_b32_e32 v136, 16, v184
	v_and_b32_e32 v137, 0xffff0000, v184
	v_lshlrev_b32_e32 v138, 16, v185
	v_and_b32_e32 v139, 0xffff0000, v185
	v_max_f32_e32 v132, 0xda24260, v132
	v_max_f32_e32 v133, 0xda24260, v133
	v_max_f32_e32 v134, 0xda24260, v134
	v_max_f32_e32 v135, 0xda24260, v135
	v_max_f32_e32 v136, 0xda24260, v136
	v_max_f32_e32 v137, 0xda24260, v137
	v_max_f32_e32 v138, 0xda24260, v138
	v_max_f32_e32 v139, 0xda24260, v139
	v_rcp_f32_e32 v132, v132
	v_rcp_f32_e32 v133, v133
	v_rcp_f32_e32 v134, v134
	v_rcp_f32_e32 v135, v135
	v_rcp_f32_e32 v136, v136
	v_rcp_f32_e32 v137, v137
	v_rcp_f32_e32 v138, v138
	v_rcp_f32_e32 v139, v139
	v_lshlrev_b32_e32 v182, 16, v178
	v_and_b32_e32 v178, 0xffff0000, v178
	v_lshlrev_b32_e32 v183, 16, v179
	v_and_b32_e32 v179, 0xffff0000, v179
	v_lshlrev_b32_e32 v184, 16, v180
	v_and_b32_e32 v180, 0xffff0000, v180
	v_lshlrev_b32_e32 v185, 16, v181
	v_and_b32_e32 v181, 0xffff0000, v181
	v_mul_f32_e32 v182, v132, v182
	v_mul_f32_e32 v178, v133, v178
	v_mul_f32_e32 v183, v134, v183
	v_mul_f32_e32 v179, v135, v179
	v_mul_f32_e32 v184, v136, v184
	v_mul_f32_e32 v180, v137, v180
	v_mul_f32_e32 v185, v138, v185
	v_mul_f32_e32 v181, v139, v181
	v_mul_f32_e32 v64, v64, v182
	v_mul_f32_e32 v65, v65, v178
	v_mul_f32_e32 v66, v66, v183
	v_mul_f32_e32 v67, v67, v179
	v_mul_f32_e32 v60, v60, v184
	v_mul_f32_e32 v61, v61, v180
	v_mul_f32_e32 v62, v62, v185
	v_mul_f32_e32 v63, v63, v181
	global_load_dwordx4 v[178:181], v[160:161], off offset:256
	global_load_dwordx4 v[182:185], v[160:161], off offset:2304
	s_waitcnt vmcnt(12)
	v_lshlrev_b32_e32 v132, 16, v190
	v_and_b32_e32 v133, 0xffff0000, v190
	v_lshlrev_b32_e32 v134, 16, v191
	v_and_b32_e32 v135, 0xffff0000, v191
	v_lshlrev_b32_e32 v136, 16, v192
	v_and_b32_e32 v137, 0xffff0000, v192
	v_lshlrev_b32_e32 v138, 16, v193
	v_and_b32_e32 v139, 0xffff0000, v193
	v_max_f32_e32 v132, 0xda24260, v132
	v_max_f32_e32 v133, 0xda24260, v133
	v_max_f32_e32 v134, 0xda24260, v134
	v_max_f32_e32 v135, 0xda24260, v135
	v_max_f32_e32 v136, 0xda24260, v136
	v_max_f32_e32 v137, 0xda24260, v137
	v_max_f32_e32 v138, 0xda24260, v138
	v_max_f32_e32 v139, 0xda24260, v139
	v_rcp_f32_e32 v132, v132
	v_rcp_f32_e32 v133, v133
	v_rcp_f32_e32 v134, v134
	v_rcp_f32_e32 v135, v135
	v_rcp_f32_e32 v136, v136
	v_rcp_f32_e32 v137, v137
	v_rcp_f32_e32 v138, v138
	v_rcp_f32_e32 v139, v139
	v_lshlrev_b32_e32 v190, 16, v186
	v_and_b32_e32 v186, 0xffff0000, v186
	v_lshlrev_b32_e32 v191, 16, v187
	v_and_b32_e32 v187, 0xffff0000, v187
	v_lshlrev_b32_e32 v192, 16, v188
	v_and_b32_e32 v188, 0xffff0000, v188
	v_lshlrev_b32_e32 v193, 16, v189
	v_and_b32_e32 v189, 0xffff0000, v189
	v_mul_f32_e32 v190, v132, v190
	v_mul_f32_e32 v186, v133, v186
	v_mul_f32_e32 v191, v134, v191
	v_mul_f32_e32 v187, v135, v187
	v_mul_f32_e32 v192, v136, v192
	v_mul_f32_e32 v188, v137, v188
	v_mul_f32_e32 v193, v138, v193
	v_mul_f32_e32 v189, v139, v189
	v_mul_f32_e32 v32, v32, v190
	v_mul_f32_e32 v33, v33, v186
	v_mul_f32_e32 v34, v34, v191
	v_mul_f32_e32 v35, v35, v187
	v_mul_f32_e32 v28, v28, v192
	v_mul_f32_e32 v29, v29, v188
	v_mul_f32_e32 v30, v30, v193
	v_mul_f32_e32 v31, v31, v189
	s_waitcnt vmcnt(10)
	v_lshlrev_b32_e32 v132, 16, v198
	v_and_b32_e32 v133, 0xffff0000, v198
	v_lshlrev_b32_e32 v134, 16, v199
	v_and_b32_e32 v135, 0xffff0000, v199
	v_lshlrev_b32_e32 v136, 16, v200
	v_and_b32_e32 v137, 0xffff0000, v200
	v_lshlrev_b32_e32 v138, 16, v201
	v_and_b32_e32 v139, 0xffff0000, v201
	v_max_f32_e32 v132, 0xda24260, v132
	v_max_f32_e32 v133, 0xda24260, v133
	v_max_f32_e32 v134, 0xda24260, v134
	v_max_f32_e32 v135, 0xda24260, v135
	v_max_f32_e32 v136, 0xda24260, v136
	v_max_f32_e32 v137, 0xda24260, v137
	v_max_f32_e32 v138, 0xda24260, v138
	v_max_f32_e32 v139, 0xda24260, v139
	v_rcp_f32_e32 v132, v132
	v_rcp_f32_e32 v133, v133
	v_rcp_f32_e32 v134, v134
	v_rcp_f32_e32 v135, v135
	v_rcp_f32_e32 v136, v136
	v_rcp_f32_e32 v137, v137
	v_rcp_f32_e32 v138, v138
	v_rcp_f32_e32 v139, v139
	v_lshlrev_b32_e32 v198, 16, v194
	v_and_b32_e32 v194, 0xffff0000, v194
	v_lshlrev_b32_e32 v199, 16, v195
	v_and_b32_e32 v195, 0xffff0000, v195
	v_lshlrev_b32_e32 v200, 16, v196
	v_and_b32_e32 v196, 0xffff0000, v196
	v_lshlrev_b32_e32 v201, 16, v197
	v_and_b32_e32 v197, 0xffff0000, v197
	v_mul_f32_e32 v198, v132, v198
	v_mul_f32_e32 v194, v133, v194
	v_mul_f32_e32 v199, v134, v199
	v_mul_f32_e32 v195, v135, v195
	v_mul_f32_e32 v200, v136, v200
	v_mul_f32_e32 v196, v137, v196
	v_mul_f32_e32 v201, v138, v201
	v_mul_f32_e32 v197, v139, v197
	v_mul_f32_e32 v56, v56, v198
	v_mul_f32_e32 v57, v57, v194
	v_mul_f32_e32 v58, v58, v199
	v_mul_f32_e32 v59, v59, v195
	v_mul_f32_e32 v52, v52, v200
	v_mul_f32_e32 v53, v53, v196
	v_mul_f32_e32 v54, v54, v201
	v_mul_f32_e32 v55, v55, v197
	s_waitcnt vmcnt(8)
	v_lshlrev_b32_e32 v132, 16, v206
	v_and_b32_e32 v133, 0xffff0000, v206
	v_lshlrev_b32_e32 v134, 16, v207
	v_and_b32_e32 v135, 0xffff0000, v207
	v_lshlrev_b32_e32 v136, 16, v208
	v_and_b32_e32 v137, 0xffff0000, v208
	v_lshlrev_b32_e32 v138, 16, v209
	v_and_b32_e32 v139, 0xffff0000, v209
	v_max_f32_e32 v132, 0xda24260, v132
	v_max_f32_e32 v133, 0xda24260, v133
	v_max_f32_e32 v134, 0xda24260, v134
	v_max_f32_e32 v135, 0xda24260, v135
	v_max_f32_e32 v136, 0xda24260, v136
	v_max_f32_e32 v137, 0xda24260, v137
	v_max_f32_e32 v138, 0xda24260, v138
	v_max_f32_e32 v139, 0xda24260, v139
	v_rcp_f32_e32 v132, v132
	v_rcp_f32_e32 v133, v133
	v_rcp_f32_e32 v134, v134
	v_rcp_f32_e32 v135, v135
	v_rcp_f32_e32 v136, v136
	v_rcp_f32_e32 v137, v137
	v_rcp_f32_e32 v138, v138
	v_rcp_f32_e32 v139, v139
	v_lshlrev_b32_e32 v206, 16, v202
	v_and_b32_e32 v202, 0xffff0000, v202
	v_lshlrev_b32_e32 v207, 16, v203
	v_and_b32_e32 v203, 0xffff0000, v203
	v_lshlrev_b32_e32 v208, 16, v204
	v_and_b32_e32 v204, 0xffff0000, v204
	v_lshlrev_b32_e32 v209, 16, v205
	v_and_b32_e32 v205, 0xffff0000, v205
	v_mul_f32_e32 v206, v132, v206
	v_mul_f32_e32 v202, v133, v202
	v_mul_f32_e32 v207, v134, v207
	v_mul_f32_e32 v203, v135, v203
	v_mul_f32_e32 v208, v136, v208
	v_mul_f32_e32 v204, v137, v204
	v_mul_f32_e32 v209, v138, v209
	v_mul_f32_e32 v205, v139, v205
	v_mul_f32_e32 v24, v24, v206
	v_mul_f32_e32 v25, v25, v202
	v_mul_f32_e32 v26, v26, v207
	v_mul_f32_e32 v27, v27, v203
	v_mul_f32_e32 v20, v20, v208
	v_mul_f32_e32 v21, v21, v204
	v_mul_f32_e32 v22, v22, v209
	v_mul_f32_e32 v23, v23, v205
	s_waitcnt vmcnt(6)
	v_lshlrev_b32_e32 v132, 16, v214
	v_and_b32_e32 v133, 0xffff0000, v214
	v_lshlrev_b32_e32 v134, 16, v215
	v_and_b32_e32 v135, 0xffff0000, v215
	v_lshlrev_b32_e32 v136, 16, v216
	v_and_b32_e32 v137, 0xffff0000, v216
	v_lshlrev_b32_e32 v138, 16, v217
	v_and_b32_e32 v139, 0xffff0000, v217
	v_max_f32_e32 v132, 0xda24260, v132
	v_max_f32_e32 v133, 0xda24260, v133
	v_max_f32_e32 v134, 0xda24260, v134
	v_max_f32_e32 v135, 0xda24260, v135
	v_max_f32_e32 v136, 0xda24260, v136
	v_max_f32_e32 v137, 0xda24260, v137
	v_max_f32_e32 v138, 0xda24260, v138
	v_max_f32_e32 v139, 0xda24260, v139
	v_rcp_f32_e32 v132, v132
	v_rcp_f32_e32 v133, v133
	v_rcp_f32_e32 v134, v134
	v_rcp_f32_e32 v135, v135
	v_rcp_f32_e32 v136, v136
	v_rcp_f32_e32 v137, v137
	v_rcp_f32_e32 v138, v138
	v_rcp_f32_e32 v139, v139
	v_lshlrev_b32_e32 v214, 16, v210
	v_and_b32_e32 v210, 0xffff0000, v210
	v_lshlrev_b32_e32 v215, 16, v211
	v_and_b32_e32 v211, 0xffff0000, v211
	v_lshlrev_b32_e32 v216, 16, v212
	v_and_b32_e32 v212, 0xffff0000, v212
	v_lshlrev_b32_e32 v217, 16, v213
	v_and_b32_e32 v213, 0xffff0000, v213
	v_mul_f32_e32 v214, v132, v214
	v_mul_f32_e32 v210, v133, v210
	v_mul_f32_e32 v215, v134, v215
	v_mul_f32_e32 v211, v135, v211
	v_mul_f32_e32 v216, v136, v216
	v_mul_f32_e32 v212, v137, v212
	v_mul_f32_e32 v217, v138, v217
	v_mul_f32_e32 v213, v139, v213
	v_mul_f32_e32 v48, v48, v214
	v_mul_f32_e32 v49, v49, v210
	v_mul_f32_e32 v50, v50, v215
	v_mul_f32_e32 v51, v51, v211
	v_mul_f32_e32 v44, v44, v216
	v_mul_f32_e32 v45, v45, v212
	v_mul_f32_e32 v46, v46, v217
	v_mul_f32_e32 v47, v47, v213
	s_waitcnt vmcnt(4)
	v_lshlrev_b32_e32 v132, 16, v150
	v_and_b32_e32 v133, 0xffff0000, v150
	v_lshlrev_b32_e32 v134, 16, v151
	v_and_b32_e32 v135, 0xffff0000, v151
	v_lshlrev_b32_e32 v136, 16, v152
	v_and_b32_e32 v137, 0xffff0000, v152
	v_lshlrev_b32_e32 v138, 16, v153
	v_and_b32_e32 v139, 0xffff0000, v153
	v_max_f32_e32 v132, 0xda24260, v132
	v_max_f32_e32 v133, 0xda24260, v133
	v_max_f32_e32 v134, 0xda24260, v134
	v_max_f32_e32 v135, 0xda24260, v135
	v_max_f32_e32 v136, 0xda24260, v136
	v_max_f32_e32 v137, 0xda24260, v137
	v_max_f32_e32 v138, 0xda24260, v138
	v_max_f32_e32 v139, 0xda24260, v139
	v_rcp_f32_e32 v132, v132
	v_rcp_f32_e32 v133, v133
	v_rcp_f32_e32 v134, v134
	v_rcp_f32_e32 v135, v135
	v_rcp_f32_e32 v136, v136
	v_rcp_f32_e32 v137, v137
	v_rcp_f32_e32 v138, v138
	v_rcp_f32_e32 v139, v139
	v_lshlrev_b32_e32 v150, 16, v146
	v_and_b32_e32 v146, 0xffff0000, v146
	v_lshlrev_b32_e32 v151, 16, v147
	v_and_b32_e32 v147, 0xffff0000, v147
	v_lshlrev_b32_e32 v152, 16, v148
	v_and_b32_e32 v148, 0xffff0000, v148
	v_lshlrev_b32_e32 v153, 16, v149
	v_and_b32_e32 v149, 0xffff0000, v149
	v_mul_f32_e32 v150, v132, v150
	v_mul_f32_e32 v146, v133, v146
	v_mul_f32_e32 v151, v134, v151
	v_mul_f32_e32 v147, v135, v147
	v_mul_f32_e32 v152, v136, v152
	v_mul_f32_e32 v148, v137, v148
	v_mul_f32_e32 v153, v138, v153
	v_mul_f32_e32 v149, v139, v149
	v_mul_f32_e32 v16, v16, v150
	v_mul_f32_e32 v17, v17, v146
	v_mul_f32_e32 v18, v18, v151
	v_mul_f32_e32 v19, v19, v147
	v_mul_f32_e32 v12, v12, v152
	v_mul_f32_e32 v13, v13, v148
	v_mul_f32_e32 v14, v14, v153
	v_mul_f32_e32 v15, v15, v149
	s_waitcnt vmcnt(2)
	v_lshlrev_b32_e32 v132, 16, v174
	v_and_b32_e32 v133, 0xffff0000, v174
	v_lshlrev_b32_e32 v134, 16, v175
	v_and_b32_e32 v135, 0xffff0000, v175
	v_lshlrev_b32_e32 v136, 16, v176
	v_and_b32_e32 v137, 0xffff0000, v176
	v_lshlrev_b32_e32 v138, 16, v177
	v_and_b32_e32 v139, 0xffff0000, v177
	v_max_f32_e32 v132, 0xda24260, v132
	v_max_f32_e32 v133, 0xda24260, v133
	v_max_f32_e32 v134, 0xda24260, v134
	v_max_f32_e32 v135, 0xda24260, v135
	v_max_f32_e32 v136, 0xda24260, v136
	v_max_f32_e32 v137, 0xda24260, v137
	v_max_f32_e32 v138, 0xda24260, v138
	v_max_f32_e32 v139, 0xda24260, v139
	v_rcp_f32_e32 v132, v132
	v_rcp_f32_e32 v133, v133
	v_rcp_f32_e32 v134, v134
	v_rcp_f32_e32 v135, v135
	v_rcp_f32_e32 v136, v136
	v_rcp_f32_e32 v137, v137
	v_rcp_f32_e32 v138, v138
	v_rcp_f32_e32 v139, v139
	v_lshlrev_b32_e32 v174, 16, v170
	v_and_b32_e32 v170, 0xffff0000, v170
	v_lshlrev_b32_e32 v175, 16, v171
	v_and_b32_e32 v171, 0xffff0000, v171
	v_lshlrev_b32_e32 v176, 16, v172
	v_and_b32_e32 v172, 0xffff0000, v172
	v_lshlrev_b32_e32 v177, 16, v173
	v_and_b32_e32 v173, 0xffff0000, v173
	v_mul_f32_e32 v174, v132, v174
	v_mul_f32_e32 v170, v133, v170
	v_mul_f32_e32 v175, v134, v175
	v_mul_f32_e32 v171, v135, v171
	v_mul_f32_e32 v176, v136, v176
	v_mul_f32_e32 v172, v137, v172
	v_mul_f32_e32 v177, v138, v177
	v_mul_f32_e32 v173, v139, v173
	v_mul_f32_e32 v40, v40, v174
	v_mul_f32_e32 v41, v41, v170
	v_mul_f32_e32 v42, v42, v175
	v_mul_f32_e32 v43, v43, v171
	v_mul_f32_e32 v36, v36, v176
	v_mul_f32_e32 v37, v37, v172
	v_mul_f32_e32 v38, v38, v177
	v_mul_f32_e32 v39, v39, v173
	s_waitcnt vmcnt(0)
	v_lshlrev_b32_e32 v132, 16, v182
	v_and_b32_e32 v133, 0xffff0000, v182
	v_lshlrev_b32_e32 v134, 16, v183
	v_and_b32_e32 v135, 0xffff0000, v183
	v_lshlrev_b32_e32 v136, 16, v184
	v_and_b32_e32 v137, 0xffff0000, v184
	v_lshlrev_b32_e32 v138, 16, v185
	v_and_b32_e32 v139, 0xffff0000, v185
	v_max_f32_e32 v132, 0xda24260, v132
	v_max_f32_e32 v133, 0xda24260, v133
	v_max_f32_e32 v134, 0xda24260, v134
	v_max_f32_e32 v135, 0xda24260, v135
	v_max_f32_e32 v136, 0xda24260, v136
	v_max_f32_e32 v137, 0xda24260, v137
	v_max_f32_e32 v138, 0xda24260, v138
	v_max_f32_e32 v139, 0xda24260, v139
	v_rcp_f32_e32 v132, v132
	v_rcp_f32_e32 v133, v133
	v_rcp_f32_e32 v134, v134
	v_rcp_f32_e32 v135, v135
	v_rcp_f32_e32 v136, v136
	v_rcp_f32_e32 v137, v137
	v_rcp_f32_e32 v138, v138
	v_rcp_f32_e32 v139, v139
	v_lshlrev_b32_e32 v182, 16, v178
	v_and_b32_e32 v178, 0xffff0000, v178
	v_lshlrev_b32_e32 v183, 16, v179
	v_and_b32_e32 v179, 0xffff0000, v179
	v_lshlrev_b32_e32 v184, 16, v180
	v_and_b32_e32 v180, 0xffff0000, v180
	v_lshlrev_b32_e32 v185, 16, v181
	v_and_b32_e32 v181, 0xffff0000, v181
	v_mul_f32_e32 v182, v132, v182
	v_mul_f32_e32 v178, v133, v178
	v_mul_f32_e32 v183, v134, v183
	v_mul_f32_e32 v179, v135, v179
	v_mul_f32_e32 v184, v136, v184
	v_mul_f32_e32 v180, v137, v180
	v_mul_f32_e32 v185, v138, v185
	v_mul_f32_e32 v181, v139, v181
	v_mul_f32_e32 v8, v8, v182
	v_mul_f32_e32 v9, v9, v178
	v_mul_f32_e32 v10, v10, v183
	v_mul_f32_e32 v11, v11, v179
	v_mul_f32_e32 v4, v4, v184
	v_mul_f32_e32 v5, v5, v180
	v_mul_f32_e32 v6, v6, v185
	v_mul_f32_e32 v7, v7, v181
	s_branch .Lm1_done
.Lm1_final:
	global_load_dwordx4 v[170:173], v[160:161], off
	global_load_dwordx4 v[174:177], v[160:161], off offset:256
	v_lshl_add_u64 v[160:161], s[14:15], 0, v[160:161]
	global_load_dwordx4 v[178:181], v[160:161], off
	global_load_dwordx4 v[182:185], v[160:161], off offset:256
	v_lshl_add_u64 v[160:161], s[14:15], 0, v[160:161]
	global_load_dwordx4 v[186:189], v[160:161], off
	global_load_dwordx4 v[190:193], v[160:161], off offset:256
	v_lshl_add_u64 v[160:161], s[14:15], 0, v[160:161]
	global_load_dwordx4 v[194:197], v[160:161], off
	global_load_dwordx4 v[198:201], v[160:161], off offset:256
	v_lshl_add_u64 v[160:161], s[14:15], 0, v[160:161]
	v_lshl_add_u64 v[160:161], s[14:15], 0, v[160:161]
	v_lshl_add_u64 v[160:161], s[14:15], 0, v[160:161]
	v_lshl_add_u64 v[160:161], s[14:15], 0, v[160:161]
	v_lshl_add_u64 v[160:161], s[14:15], 0, v[160:161]
	global_load_dwordx4 v[202:205], v[160:161], off
	global_load_dwordx4 v[206:209], v[160:161], off offset:256
	v_lshl_add_u64 v[160:161], s[14:15], 0, v[160:161]
	global_load_dwordx4 v[210:213], v[160:161], off
	global_load_dwordx4 v[214:217], v[160:161], off offset:256
	v_lshl_add_u64 v[160:161], s[14:15], 0, v[160:161]
	global_load_dwordx4 v[146:149], v[160:161], off
	global_load_dwordx4 v[150:153], v[160:161], off offset:256
	s_mov_b32 s64, 0x8000
	s_mov_b32 s65, 0
	s_waitcnt vmcnt(13)
	v_lshlrev_b32_e32 v132, 16, v170
	v_and_b32_e32 v170, 0xffff0000, v170
	v_lshlrev_b32_e32 v133, 16, v171
	v_and_b32_e32 v171, 0xffff0000, v171
	v_lshlrev_b32_e32 v134, 16, v172
	v_and_b32_e32 v172, 0xffff0000, v172
	v_lshlrev_b32_e32 v135, 16, v173
	v_and_b32_e32 v173, 0xffff0000, v173
	v_mul_f32_e32 v128, v128, v132
	v_mul_f32_e32 v129, v129, v170
	v_mul_f32_e32 v130, v130, v133
	v_mul_f32_e32 v131, v131, v171
	v_mul_f32_e32 v124, v124, v134
	v_mul_f32_e32 v125, v125, v172
	v_mul_f32_e32 v126, v126, v135
	v_mul_f32_e32 v127, v127, v173
	v_cvt_pk_bf16_f32 v136, v128, v129
	v_cvt_pk_bf16_f32 v137, v130, v131
	v_cvt_pk_bf16_f32 v138, v124, v125
	v_cvt_pk_bf16_f32 v139, v126, v127
	global_store_dwordx4 v[162:163], v[136:139], off
	v_lshl_add_u64 v[160:161], s[14:15], 0, v[160:161]
	global_load_dwordx4 v[170:173], v[160:161], off
	s_waitcnt vmcnt(14)
	v_lshlrev_b32_e32 v132, 16, v174
	v_and_b32_e32 v174, 0xffff0000, v174
	v_lshlrev_b32_e32 v133, 16, v175
	v_and_b32_e32 v175, 0xffff0000, v175
	v_lshlrev_b32_e32 v134, 16, v176
	v_and_b32_e32 v176, 0xffff0000, v176
	v_lshlrev_b32_e32 v135, 16, v177
	v_and_b32_e32 v177, 0xffff0000, v177
	v_mul_f32_e32 v96, v96, v132
	v_mul_f32_e32 v97, v97, v174
	v_mul_f32_e32 v98, v98, v133
	v_mul_f32_e32 v99, v99, v175
	v_mul_f32_e32 v92, v92, v134
	v_mul_f32_e32 v93, v93, v176
	v_mul_f32_e32 v94, v94, v135
	v_mul_f32_e32 v95, v95, v177
	v_cvt_pk_bf16_f32 v136, v96, v97
	v_cvt_pk_bf16_f32 v137, v98, v99
	v_cvt_pk_bf16_f32 v138, v92, v93
	v_cvt_pk_bf16_f32 v139, v94, v95
	global_store_dwordx4 v[162:163], v[136:139], off offset:256
	global_load_dwordx4 v[174:177], v[160:161], off offset:256
	s_waitcnt vmcnt(15)
	v_lshlrev_b32_e32 v132, 16, v178
	v_and_b32_e32 v178, 0xffff0000, v178
	v_lshlrev_b32_e32 v133, 16, v179
	v_and_b32_e32 v179, 0xffff0000, v179
	v_lshlrev_b32_e32 v134, 16, v180
	v_and_b32_e32 v180, 0xffff0000, v180
	v_lshlrev_b32_e32 v135, 16, v181
	v_and_b32_e32 v181, 0xffff0000, v181
	v_mul_f32_e32 v120, v120, v132
	v_mul_f32_e32 v121, v121, v178
	v_mul_f32_e32 v122, v122, v133
	v_mul_f32_e32 v123, v123, v179
	v_mul_f32_e32 v116, v116, v134
	v_mul_f32_e32 v117, v117, v180
	v_mul_f32_e32 v118, v118, v135
	v_mul_f32_e32 v119, v119, v181
	v_cvt_pk_bf16_f32 v136, v120, v121
	v_cvt_pk_bf16_f32 v137, v122, v123
	v_cvt_pk_bf16_f32 v138, v116, v117
	v_cvt_pk_bf16_f32 v139, v118, v119
	v_lshl_add_u64 v[162:163], s[64:65], 0, v[162:163]
	global_store_dwordx4 v[162:163], v[136:139], off
	s_waitcnt vmcnt(15)
	v_lshlrev_b32_e32 v132, 16, v182
	v_and_b32_e32 v182, 0xffff0000, v182
	v_lshlrev_b32_e32 v133, 16, v183
	v_and_b32_e32 v183, 0xffff0000, v183
	v_lshlrev_b32_e32 v134, 16, v184
	v_and_b32_e32 v184, 0xffff0000, v184
	v_lshlrev_b32_e32 v135, 16, v185
	v_and_b32_e32 v185, 0xffff0000, v185
	v_mul_f32_e32 v88, v88, v132
	v_mul_f32_e32 v89, v89, v182
	v_mul_f32_e32 v90, v90, v133
	v_mul_f32_e32 v91, v91, v183
	v_mul_f32_e32 v84, v84, v134
	v_mul_f32_e32 v85, v85, v184
	v_mul_f32_e32 v86, v86, v135
	v_mul_f32_e32 v87, v87, v185
	v_cvt_pk_bf16_f32 v136, v88, v89
	v_cvt_pk_bf16_f32 v137, v90, v91
	v_cvt_pk_bf16_f32 v138, v84, v85
	v_cvt_pk_bf16_f32 v139, v86, v87
	global_store_dwordx4 v[162:163], v[136:139], off offset:256
	s_waitcnt vmcnt(15)
	v_lshlrev_b32_e32 v132, 16, v186
	v_and_b32_e32 v186, 0xffff0000, v186
	v_lshlrev_b32_e32 v133, 16, v187
	v_and_b32_e32 v187, 0xffff0000, v187
	v_lshlrev_b32_e32 v134, 16, v188
	v_and_b32_e32 v188, 0xffff0000, v188
	v_lshlrev_b32_e32 v135, 16, v189
	v_and_b32_e32 v189, 0xffff0000, v189
	v_mul_f32_e32 v112, v112, v132
	v_mul_f32_e32 v113, v113, v186
	v_mul_f32_e32 v114, v114, v133
	v_mul_f32_e32 v115, v115, v187
	v_mul_f32_e32 v108, v108, v134
	v_mul_f32_e32 v109, v109, v188
	v_mul_f32_e32 v110, v110, v135
	v_mul_f32_e32 v111, v111, v189
	v_cvt_pk_bf16_f32 v136, v112, v113
	v_cvt_pk_bf16_f32 v137, v114, v115
	v_cvt_pk_bf16_f32 v138, v108, v109
	v_cvt_pk_bf16_f32 v139, v110, v111
	v_lshl_add_u64 v[162:163], s[64:65], 0, v[162:163]
	global_store_dwordx4 v[162:163], v[136:139], off
	s_waitcnt vmcnt(15)
	v_lshlrev_b32_e32 v132, 16, v190
	v_and_b32_e32 v190, 0xffff0000, v190
	v_lshlrev_b32_e32 v133, 16, v191
	v_and_b32_e32 v191, 0xffff0000, v191
	v_lshlrev_b32_e32 v134, 16, v192
	v_and_b32_e32 v192, 0xffff0000, v192
	v_lshlrev_b32_e32 v135, 16, v193
	v_and_b32_e32 v193, 0xffff0000, v193
	v_mul_f32_e32 v80, v80, v132
	v_mul_f32_e32 v81, v81, v190
	v_mul_f32_e32 v82, v82, v133
	v_mul_f32_e32 v83, v83, v191
	v_mul_f32_e32 v76, v76, v134
	v_mul_f32_e32 v77, v77, v192
	v_mul_f32_e32 v78, v78, v135
	v_mul_f32_e32 v79, v79, v193
	v_cvt_pk_bf16_f32 v136, v80, v81
	v_cvt_pk_bf16_f32 v137, v82, v83
	v_cvt_pk_bf16_f32 v138, v76, v77
	v_cvt_pk_bf16_f32 v139, v78, v79
	global_store_dwordx4 v[162:163], v[136:139], off offset:256
	s_waitcnt vmcnt(15)
	v_lshlrev_b32_e32 v132, 16, v194
	v_and_b32_e32 v194, 0xffff0000, v194
	v_lshlrev_b32_e32 v133, 16, v195
	v_and_b32_e32 v195, 0xffff0000, v195
	v_lshlrev_b32_e32 v134, 16, v196
	v_and_b32_e32 v196, 0xffff0000, v196
	v_lshlrev_b32_e32 v135, 16, v197
	v_and_b32_e32 v197, 0xffff0000, v197
	v_mul_f32_e32 v104, v104, v132
	v_mul_f32_e32 v105, v105, v194
	v_mul_f32_e32 v106, v106, v133
	v_mul_f32_e32 v107, v107, v195
	v_mul_f32_e32 v100, v100, v134
	v_mul_f32_e32 v101, v101, v196
	v_mul_f32_e32 v102, v102, v135
	v_mul_f32_e32 v103, v103, v197
	v_cvt_pk_bf16_f32 v136, v104, v105
	v_cvt_pk_bf16_f32 v137, v106, v107
	v_cvt_pk_bf16_f32 v138, v100, v101
	v_cvt_pk_bf16_f32 v139, v102, v103
	v_lshl_add_u64 v[162:163], s[64:65], 0, v[162:163]
	global_store_dwordx4 v[162:163], v[136:139], off
	s_waitcnt vmcnt(15)
	v_lshlrev_b32_e32 v132, 16, v198
	v_and_b32_e32 v198, 0xffff0000, v198
	v_lshlrev_b32_e32 v133, 16, v199
	v_and_b32_e32 v199, 0xffff0000, v199
	v_lshlrev_b32_e32 v134, 16, v200
	v_and_b32_e32 v200, 0xffff0000, v200
	v_lshlrev_b32_e32 v135, 16, v201
	v_and_b32_e32 v201, 0xffff0000, v201
	v_mul_f32_e32 v72, v72, v132
	v_mul_f32_e32 v73, v73, v198
	v_mul_f32_e32 v74, v74, v133
	v_mul_f32_e32 v75, v75, v199
	v_mul_f32_e32 v68, v68, v134
	v_mul_f32_e32 v69, v69, v200
	v_mul_f32_e32 v70, v70, v135
	v_mul_f32_e32 v71, v71, v201
	v_cvt_pk_bf16_f32 v136, v72, v73
	v_cvt_pk_bf16_f32 v137, v74, v75
	v_cvt_pk_bf16_f32 v138, v68, v69
	v_cvt_pk_bf16_f32 v139, v70, v71
	global_store_dwordx4 v[162:163], v[136:139], off offset:256
	s_waitcnt vmcnt(15)
	v_lshlrev_b32_e32 v132, 16, v202
	v_and_b32_e32 v202, 0xffff0000, v202
	v_lshlrev_b32_e32 v133, 16, v203
	v_and_b32_e32 v203, 0xffff0000, v203
	v_lshlrev_b32_e32 v134, 16, v204
	v_and_b32_e32 v204, 0xffff0000, v204
	v_lshlrev_b32_e32 v135, 16, v205
	v_and_b32_e32 v205, 0xffff0000, v205
	v_mul_f32_e32 v64, v64, v132
	v_mul_f32_e32 v65, v65, v202
	v_mul_f32_e32 v66, v66, v133
	v_mul_f32_e32 v67, v67, v203
	v_mul_f32_e32 v60, v60, v134
	v_mul_f32_e32 v61, v61, v204
	v_mul_f32_e32 v62, v62, v135
	v_mul_f32_e32 v63, v63, v205
	v_cvt_pk_bf16_f32 v136, v64, v65
	v_cvt_pk_bf16_f32 v137, v66, v67
	v_cvt_pk_bf16_f32 v138, v60, v61
	v_cvt_pk_bf16_f32 v139, v62, v63
	v_lshl_add_u64 v[162:163], s[64:65], 0, v[162:163]
	v_lshl_add_u64 v[162:163], s[64:65], 0, v[162:163]
	v_lshl_add_u64 v[162:163], s[64:65], 0, v[162:163]
	v_lshl_add_u64 v[162:163], s[64:65], 0, v[162:163]
	v_lshl_add_u64 v[162:163], s[64:65], 0, v[162:163]
	global_store_dwordx4 v[162:163], v[136:139], off
	s_waitcnt vmcnt(15)
	v_lshlrev_b32_e32 v132, 16, v206
	v_and_b32_e32 v206, 0xffff0000, v206
	v_lshlrev_b32_e32 v133, 16, v207
	v_and_b32_e32 v207, 0xffff0000, v207
	v_lshlrev_b32_e32 v134, 16, v208
	v_and_b32_e32 v208, 0xffff0000, v208
	v_lshlrev_b32_e32 v135, 16, v209
	v_and_b32_e32 v209, 0xffff0000, v209
	v_mul_f32_e32 v32, v32, v132
	v_mul_f32_e32 v33, v33, v206
	v_mul_f32_e32 v34, v34, v133
	v_mul_f32_e32 v35, v35, v207
	v_mul_f32_e32 v28, v28, v134
	v_mul_f32_e32 v29, v29, v208
	v_mul_f32_e32 v30, v30, v135
	v_mul_f32_e32 v31, v31, v209
	v_cvt_pk_bf16_f32 v136, v32, v33
	v_cvt_pk_bf16_f32 v137, v34, v35
	v_cvt_pk_bf16_f32 v138, v28, v29
	v_cvt_pk_bf16_f32 v139, v30, v31
	global_store_dwordx4 v[162:163], v[136:139], off offset:256
	s_waitcnt vmcnt(15)
	v_lshlrev_b32_e32 v132, 16, v210
	v_and_b32_e32 v210, 0xffff0000, v210
	v_lshlrev_b32_e32 v133, 16, v211
	v_and_b32_e32 v211, 0xffff0000, v211
	v_lshlrev_b32_e32 v134, 16, v212
	v_and_b32_e32 v212, 0xffff0000, v212
	v_lshlrev_b32_e32 v135, 16, v213
	v_and_b32_e32 v213, 0xffff0000, v213
	v_mul_f32_e32 v56, v56, v132
	v_mul_f32_e32 v57, v57, v210
	v_mul_f32_e32 v58, v58, v133
	v_mul_f32_e32 v59, v59, v211
	v_mul_f32_e32 v52, v52, v134
	v_mul_f32_e32 v53, v53, v212
	v_mul_f32_e32 v54, v54, v135
	v_mul_f32_e32 v55, v55, v213
	v_cvt_pk_bf16_f32 v136, v56, v57
	v_cvt_pk_bf16_f32 v137, v58, v59
	v_cvt_pk_bf16_f32 v138, v52, v53
	v_cvt_pk_bf16_f32 v139, v54, v55
	v_lshl_add_u64 v[162:163], s[64:65], 0, v[162:163]
	global_store_dwordx4 v[162:163], v[136:139], off
	s_waitcnt vmcnt(15)
	v_lshlrev_b32_e32 v132, 16, v214
	v_and_b32_e32 v214, 0xffff0000, v214
	v_lshlrev_b32_e32 v133, 16, v215
	v_and_b32_e32 v215, 0xffff0000, v215
	v_lshlrev_b32_e32 v134, 16, v216
	v_and_b32_e32 v216, 0xffff0000, v216
	v_lshlrev_b32_e32 v135, 16, v217
	v_and_b32_e32 v217, 0xffff0000, v217
	v_mul_f32_e32 v24, v24, v132
	v_mul_f32_e32 v25, v25, v214
	v_mul_f32_e32 v26, v26, v133
	v_mul_f32_e32 v27, v27, v215
	v_mul_f32_e32 v20, v20, v134
	v_mul_f32_e32 v21, v21, v216
	v_mul_f32_e32 v22, v22, v135
	v_mul_f32_e32 v23, v23, v217
	v_cvt_pk_bf16_f32 v136, v24, v25
	v_cvt_pk_bf16_f32 v137, v26, v27
	v_cvt_pk_bf16_f32 v138, v20, v21
	v_cvt_pk_bf16_f32 v139, v22, v23
	global_store_dwordx4 v[162:163], v[136:139], off offset:256
	s_waitcnt vmcnt(15)
	v_lshlrev_b32_e32 v132, 16, v146
	v_and_b32_e32 v146, 0xffff0000, v146
	v_lshlrev_b32_e32 v133, 16, v147
	v_and_b32_e32 v147, 0xffff0000, v147
	v_lshlrev_b32_e32 v134, 16, v148
	v_and_b32_e32 v148, 0xffff0000, v148
	v_lshlrev_b32_e32 v135, 16, v149
	v_and_b32_e32 v149, 0xffff0000, v149
	v_mul_f32_e32 v48, v48, v132
	v_mul_f32_e32 v49, v49, v146
	v_mul_f32_e32 v50, v50, v133
	v_mul_f32_e32 v51, v51, v147
	v_mul_f32_e32 v44, v44, v134
	v_mul_f32_e32 v45, v45, v148
	v_mul_f32_e32 v46, v46, v135
	v_mul_f32_e32 v47, v47, v149
	v_cvt_pk_bf16_f32 v136, v48, v49
	v_cvt_pk_bf16_f32 v137, v50, v51
	v_cvt_pk_bf16_f32 v138, v44, v45
	v_cvt_pk_bf16_f32 v139, v46, v47
	v_lshl_add_u64 v[162:163], s[64:65], 0, v[162:163]
	global_store_dwordx4 v[162:163], v[136:139], off
	s_waitcnt vmcnt(15)
	v_lshlrev_b32_e32 v132, 16, v150
	v_and_b32_e32 v150, 0xffff0000, v150
	v_lshlrev_b32_e32 v133, 16, v151
	v_and_b32_e32 v151, 0xffff0000, v151
	v_lshlrev_b32_e32 v134, 16, v152
	v_and_b32_e32 v152, 0xffff0000, v152
	v_lshlrev_b32_e32 v135, 16, v153
	v_and_b32_e32 v153, 0xffff0000, v153
	v_mul_f32_e32 v16, v16, v132
	v_mul_f32_e32 v17, v17, v150
	v_mul_f32_e32 v18, v18, v133
	v_mul_f32_e32 v19, v19, v151
	v_mul_f32_e32 v12, v12, v134
	v_mul_f32_e32 v13, v13, v152
	v_mul_f32_e32 v14, v14, v135
	v_mul_f32_e32 v15, v15, v153
	v_cvt_pk_bf16_f32 v136, v16, v17
	v_cvt_pk_bf16_f32 v137, v18, v19
	v_cvt_pk_bf16_f32 v138, v12, v13
	v_cvt_pk_bf16_f32 v139, v14, v15
	global_store_dwordx4 v[162:163], v[136:139], off offset:256
	s_waitcnt vmcnt(14)
	v_lshlrev_b32_e32 v132, 16, v170
	v_and_b32_e32 v170, 0xffff0000, v170
	v_lshlrev_b32_e32 v133, 16, v171
	v_and_b32_e32 v171, 0xffff0000, v171
	v_lshlrev_b32_e32 v134, 16, v172
	v_and_b32_e32 v172, 0xffff0000, v172
	v_lshlrev_b32_e32 v135, 16, v173
	v_and_b32_e32 v173, 0xffff0000, v173
	v_mul_f32_e32 v40, v40, v132
	v_mul_f32_e32 v41, v41, v170
	v_mul_f32_e32 v42, v42, v133
	v_mul_f32_e32 v43, v43, v171
	v_mul_f32_e32 v36, v36, v134
	v_mul_f32_e32 v37, v37, v172
	v_mul_f32_e32 v38, v38, v135
	v_mul_f32_e32 v39, v39, v173
	v_cvt_pk_bf16_f32 v136, v40, v41
	v_cvt_pk_bf16_f32 v137, v42, v43
	v_cvt_pk_bf16_f32 v138, v36, v37
	v_cvt_pk_bf16_f32 v139, v38, v39
	v_lshl_add_u64 v[162:163], s[64:65], 0, v[162:163]
	global_store_dwordx4 v[162:163], v[136:139], off
	s_waitcnt vmcnt(13)
	v_lshlrev_b32_e32 v132, 16, v174
	v_and_b32_e32 v174, 0xffff0000, v174
	v_lshlrev_b32_e32 v133, 16, v175
	v_and_b32_e32 v175, 0xffff0000, v175
	v_lshlrev_b32_e32 v134, 16, v176
	v_and_b32_e32 v176, 0xffff0000, v176
	v_lshlrev_b32_e32 v135, 16, v177
	v_and_b32_e32 v177, 0xffff0000, v177
	v_mul_f32_e32 v8, v8, v132
	v_mul_f32_e32 v9, v9, v174
	v_mul_f32_e32 v10, v10, v133
	v_mul_f32_e32 v11, v11, v175
	v_mul_f32_e32 v4, v4, v134
	v_mul_f32_e32 v5, v5, v176
	v_mul_f32_e32 v6, v6, v135
	v_mul_f32_e32 v7, v7, v177
	v_cvt_pk_bf16_f32 v136, v8, v9
	v_cvt_pk_bf16_f32 v137, v10, v11
	v_cvt_pk_bf16_f32 v138, v4, v5
	v_cvt_pk_bf16_f32 v139, v6, v7
	global_store_dwordx4 v[162:163], v[136:139], off offset:256
.Lm1_done:
	s_andn2_b64 vcc, exec, s[42:43]
	s_mov_b64 s[10:11], -1
	s_cbranch_vccnz .LBB0_907
